# epilogue row-sum reductions across lane groups: v_permlane16_swap/v_permlane32_swap instead of ds_bpermute LDS round trips (input-projection and general residual epilogues)
# baseline (speedup 1.0000x reference)
.LBB0_78:
	v_readlane_b32 s54, v254, 46
	v_readlane_b32 s55, v254, 47
	s_waitcnt lgkmcnt(0)
	s_add_u32 s17, s52, s54
	s_addc_u32 s52, s53, s55
	v_readlane_b32 s53, v254, 26
	s_add_u32 s53, s14, s53
	v_readlane_b32 s54, v254, 25
	v_lshl_add_u32 v204, s34, 8, v241
	s_addc_u32 s54, s15, s54
	v_ashrrev_i32_e32 v205, 31, v204
	s_lshl_b64 s[10:11], s[10:11], 2
	v_lshl_add_u64 v[146:147], v[204:205], 4, s[14:15]
	s_mov_b32 s55, 0xa00000
	s_add_u32 s53, s53, s10
	v_add_co_u32_e32 v130, vcc, s55, v146
	s_addc_u32 s54, s54, s11
	s_lshl_b32 s10, s16, 8
	v_addc_co_u32_e32 v131, vcc, 0, v147, vcc
	s_ashr_i32 s11, s10, 31
	global_load_dwordx4 v[150:153], v[130:131], off
	s_lshl_b64 s[10:11], s[10:11], 2
	s_add_u32 s10, s53, s10
	v_readlane_b32 s53, v254, 11
	s_addc_u32 s11, s54, s11
	s_lshl_b32 s53, s53, 2
	s_add_u32 s10, s10, s53
	s_addc_u32 s11, s11, 0
	v_lshlrev_b32_e32 v0, 2, v184
	v_lshl_add_u64 v[130:131], s[10:11], 0, v[0:1]
	s_mov_b32 s10, 0xb05000
	v_add_co_u32_e32 v132, vcc, s10, v130
	s_mov_b64 s[10:11], 0xb05800
	s_nop 0
	v_addc_co_u32_e32 v133, vcc, 0, v131, vcc
	v_lshl_add_u64 v[130:131], v[130:131], 0, s[10:11]
	s_mov_b64 s[10:11], 0xa00000
	global_load_dwordx4 v[142:145], v[132:133], off offset:2048
	global_load_dwordx4 v[138:141], v[130:131], off offset:64
	global_load_dwordx4 v[134:137], v[130:131], off offset:512
	s_nop 0
	global_load_dwordx4 v[130:133], v[130:131], off offset:576
	v_lshl_add_u64 v[208:209], v[146:147], 0, s[10:11]
	v_mov_b32_e32 v210, v204
	global_load_dwordx4 v[146:149], v[208:209], off offset:256
	s_cmp_lg_u32 s16, 0
	s_cselect_b64 s[88:89], -1, 0
	s_cmp_gt_i32 s16, 4
	s_cselect_b64 s[80:81], -1, 0
	s_cmp_gt_u32 s16, 6
	s_cselect_b64 s[10:11], -1, 0
	v_writelane_b32 v254, s10, 60
	s_cmp_lg_u32 s16, 7
	v_lshlrev_b32_e32 v0, 2, v182
	v_writelane_b32 v254, s11, 61
	s_cselect_b64 s[10:11], -1, 0
	v_writelane_b32 v254, s10, 62
	v_lshlrev_b32_e32 v154, 1, v182
	v_mov_b32_e32 v155, v1
	v_writelane_b32 v254, s11, 63
	s_add_u32 s10, s14, 0x9000000
	s_addc_u32 s11, s15, 0
	v_writelane_b32 v255, s10, 0
	v_readlane_b32 s53, v254, 18
	v_mov_b32_e32 v199, v1
	v_writelane_b32 v255, s11, 1
	s_lshl_b32 s10, s53, 2
	s_add_u32 s10, s17, s10
	s_addc_u32 s11, s52, 0
	v_lshl_add_u64 v[202:203], s[10:11], 0, v[0:1]
	s_lshl_b32 s10, s53, 1
	s_add_u32 s10, s14, s10
	s_addc_u32 s11, s15, 0
	v_lshl_add_u64 v[206:207], s[10:11], 0, v[154:155]
	s_mov_b64 s[10:11], 0x8800000
	v_lshl_add_u64 v[200:201], v[206:207], 0, s[10:11]
	s_lshl_b32 s10, s16, 2
	v_readlane_b32 s11, v254, 12
	s_add_i32 s70, s11, s10
	s_lshl_b64 s[10:11], s[70:71], 21
	s_add_u32 s10, s14, s10
	s_addc_u32 s11, s15, s11
	s_add_u32 s54, s10, 0xb800000
	s_addc_u32 s55, s11, 0
	s_add_u32 s10, s12, 0x6000000
	s_addc_u32 s11, s13, 0
	v_writelane_b32 v255, s10, 2
	s_cmp_lt_i32 s16, 3
	s_waitcnt vmcnt(0)
	v_mov_b32_e32 v156, v151
	v_writelane_b32 v255, s11, 3
	s_cselect_b64 s[10:11], -1, 0
	v_writelane_b32 v255, s10, 4
	s_cmp_gt_i32 s16, 2
	v_mov_b32_e32 v157, v152
	v_writelane_b32 v255, s11, 5
	s_cselect_b64 s[10:11], -1, 0
	s_and_b64 s[52:53], s[10:11], exec
	s_cselect_b32 s17, -3, -1
	s_cselect_b32 s52, s66, s64
	s_cselect_b32 s53, s67, s65
	s_add_i32 s17, s17, s16
	s_lshl_b32 s17, s17, 2
	v_readlane_b32 s64, v254, 43
	s_or_b32 s66, s17, s64
	v_readlane_b32 s64, v254, 48
	v_mov_b32_e32 v151, v153
	v_readlane_b32 s65, v254, 49
	s_add_u32 s64, s52, s64
	v_pk_add_f32 v[150:151], v[156:157], v[150:151]
	s_addc_u32 s65, s53, s65
	s_ashr_i32 s67, s66, 31
	v_add_f32_e32 v150, v150, v151
	s_lshl_b64 s[52:53], s[66:67], 21
	v_fmamk_f32 v150, v150, 0x3a800000, v231
	s_add_u32 s14, s14, s52
	v_rsq_f32_e32 v162, v150
	s_addc_u32 s15, s15, s53
	v_lshl_add_u64 v[154:155], s[14:15], 0, v[154:155]
	s_mov_b64 s[52:53], 0x9800000
	v_lshl_add_u64 v[176:177], v[154:155], 0, s[52:53]
	v_lshl_add_u64 v[154:155], s[14:15], 0, v[198:199]
	s_mov_b64 s[14:15], 0xa800000
	s_add_u32 s52, s12, 0x4000000
	v_lshl_add_u64 v[174:175], v[154:155], 0, s[14:15]
	s_addc_u32 s53, s13, 0
	v_pk_fma_f32 v[152:153], v[32:33], v[162:163], v[144:145] op_sel_hi:[1,0,1]
	v_pk_fma_f32 v[150:151], v[30:31], v[162:163], v[142:143] op_sel_hi:[1,0,1]
	v_pk_fma_f32 v[156:157], v[28:29], v[162:163], v[140:141] op_sel_hi:[1,0,1]
	v_pk_fma_f32 v[154:155], v[26:27], v[162:163], v[138:139] op_sel_hi:[1,0,1]
	v_pk_fma_f32 v[160:161], v[24:25], v[162:163], v[136:137] op_sel_hi:[1,0,1]
	v_pk_fma_f32 v[158:159], v[22:23], v[162:163], v[134:135] op_sel_hi:[1,0,1]
	v_pk_fma_f32 v[164:165], v[16:17], v[162:163], v[132:133] op_sel_hi:[1,0,1]
	v_pk_fma_f32 v[162:163], v[14:15], v[162:163], v[130:131] op_sel_hi:[1,0,1]
	s_mov_b64 s[12:13], -1
	s_and_b64 vcc, exec, s[88:89]
	s_cbranch_vccz .LBB0_108
	s_and_b64 vcc, exec, s[80:81]
	s_cbranch_vccz .LBB0_97
	v_readlane_b32 s14, v254, 60
	v_readlane_b32 s15, v254, 61
	s_and_b64 vcc, exec, s[14:15]
	s_cbranch_vccz .LBB0_86
	v_readlane_b32 s14, v254, 62
	v_readlane_b32 s15, v254, 63
	s_andn2_b64 vcc, exec, s[14:15]
	v_mul_f32_e32 v222, 0x3d372713, v150
	v_mul_f32_e32 v220, 0x3d372713, v151
	v_mul_f32_e32 v218, 0x3d372713, v152
	v_mul_f32_e32 v216, 0x3d372713, v153
	v_mul_f32_e32 v221, 0x3d372713, v154
	v_mul_f32_e32 v219, 0x3d372713, v155
	v_mul_f32_e32 v217, 0x3d372713, v156
	v_mul_f32_e32 v215, 0x3d372713, v157
	v_mul_f32_e32 v214, 0x3d372713, v158
	v_mul_f32_e32 v212, 0x3d372713, v159
	v_mul_f32_e32 v199, 0x3d372713, v160
	v_mul_f32_e32 v173, 0x3d372713, v161
	v_mul_f32_e32 v213, 0x3d372713, v162
	v_mul_f32_e32 v205, 0x3d372713, v163
	v_mul_f32_e32 v191, 0x3d372713, v164
	v_mul_f32_e32 v172, 0x3d372713, v165
	s_cbranch_vccnz .LBB0_83
	v_mul_f32_e32 v167, v152, v218
	v_fma_f32 v167, v152, v167, v152
	v_mul_f32_e32 v167, 0x3f4c422a, v167
	v_add_f32_e32 v167, v167, v167
	v_mul_f32_e32 v167, 0xbfb8aa3b, v167
	v_exp_f32_e32 v167, v167
	v_mul_f32_e32 v166, v150, v222
	v_fma_f32 v166, v150, v166, v150
	v_mul_f32_e32 v166, 0x3f4c422a, v166
	v_add_f32_e32 v167, 1.0, v167
	v_rcp_f32_e32 v167, v167
	v_add_f32_e32 v166, v166, v166
	v_mul_f32_e32 v166, 0xbfb8aa3b, v166
	v_exp_f32_e32 v166, v166
	v_mul_f32_e32 v224, v152, v167
	v_mul_f32_e32 v167, v153, v216
	v_fma_f32 v167, v153, v167, v153
	v_mul_f32_e32 v167, 0x3f4c422a, v167
	v_add_f32_e32 v167, v167, v167
	v_mul_f32_e32 v167, 0xbfb8aa3b, v167
	v_exp_f32_e32 v167, v167
	v_add_f32_e32 v166, 1.0, v166
	v_rcp_f32_e32 v166, v166
	v_readlane_b32 s12, v255, 0
	v_add_f32_e32 v167, 1.0, v167
	v_rcp_f32_e32 v167, v167
	v_mul_f32_e32 v211, v150, v166
	v_mul_f32_e32 v166, v151, v220
	v_fma_f32 v166, v151, v166, v151
	v_mul_f32_e32 v225, v153, v167
	v_mul_f32_e32 v167, v154, v221
	v_fma_f32 v167, v154, v167, v154
	v_mul_f32_e32 v167, 0x3f4c422a, v167
	v_add_f32_e32 v167, v167, v167
	v_mul_f32_e32 v167, 0xbfb8aa3b, v167
	v_exp_f32_e32 v167, v167
	v_mul_f32_e32 v166, 0x3f4c422a, v166
	v_add_f32_e32 v166, v166, v166
	v_mul_f32_e32 v166, 0xbfb8aa3b, v166
	v_add_f32_e32 v167, 1.0, v167
	v_rcp_f32_e32 v167, v167
	v_exp_f32_e32 v166, v166
	v_readlane_b32 s13, v255, 1
	v_lshlrev_b32_e32 v168, 6, v210
	v_mul_f32_e32 v226, v154, v167
	v_mul_f32_e32 v167, v155, v219
	v_fma_f32 v167, v155, v167, v155
	v_mul_f32_e32 v167, 0x3f4c422a, v167
	v_add_f32_e32 v167, v167, v167
	v_mul_f32_e32 v167, 0xbfb8aa3b, v167
	v_exp_f32_e32 v167, v167
	v_add_f32_e32 v166, 1.0, v166
	v_rcp_f32_e32 v166, v166
	v_and_b32_e32 v168, 0x1c00, v168
	v_add_f32_e32 v167, 1.0, v167
	v_rcp_f32_e32 v167, v167
	v_mul_f32_e32 v223, v151, v166
	v_mul_f32_e32 v166, v223, v223
	v_fmac_f32_e32 v166, v211, v211
	v_mul_f32_e32 v227, v155, v167
	v_mul_f32_e32 v167, v156, v217
	v_fma_f32 v167, v156, v167, v156
	v_mul_f32_e32 v167, 0x3f4c422a, v167
	v_add_f32_e32 v167, v167, v167
	v_mul_f32_e32 v167, 0xbfb8aa3b, v167
	v_exp_f32_e32 v167, v167
	v_fmac_f32_e32 v166, v224, v224
	v_fmac_f32_e32 v166, v225, v225
	v_fmac_f32_e32 v166, v226, v226
	v_add_f32_e32 v167, 1.0, v167
	v_rcp_f32_e32 v167, v167
	v_fmac_f32_e32 v166, v227, v227
	v_mov_b32_e32 v169, v1
	v_mul_f32_e32 v228, v156, v167
	v_mul_f32_e32 v167, v157, v215
	v_fma_f32 v167, v157, v167, v157
	v_mul_f32_e32 v167, 0x3f4c422a, v167
	v_add_f32_e32 v167, v167, v167
	v_mul_f32_e32 v167, 0xbfb8aa3b, v167
	v_exp_f32_e32 v167, v167
	v_fmac_f32_e32 v166, v228, v228
	v_add_f32_e32 v167, 1.0, v167
	v_rcp_f32_e32 v167, v167
	s_nop 0
	v_mul_f32_e32 v229, v157, v167
	v_mul_f32_e32 v167, v158, v214
	v_fma_f32 v167, v158, v167, v158
	v_mul_f32_e32 v167, 0x3f4c422a, v167
	v_add_f32_e32 v167, v167, v167
	v_mul_f32_e32 v167, 0xbfb8aa3b, v167
	v_exp_f32_e32 v167, v167
	v_fmac_f32_e32 v166, v229, v229
	v_add_f32_e32 v167, 1.0, v167
	v_rcp_f32_e32 v167, v167
	s_nop 0
	v_mul_f32_e32 v248, v158, v167
	v_mul_f32_e32 v167, v159, v212
	v_fma_f32 v167, v159, v167, v159
	v_mul_f32_e32 v167, 0x3f4c422a, v167
	v_add_f32_e32 v167, v167, v167
	v_mul_f32_e32 v167, 0xbfb8aa3b, v167
	v_exp_f32_e32 v167, v167
	v_fmac_f32_e32 v166, v248, v248
	v_add_f32_e32 v167, 1.0, v167
	v_rcp_f32_e32 v167, v167
	s_nop 0
	v_mul_f32_e32 v230, v159, v167
	v_mul_f32_e32 v167, v160, v199
	v_fma_f32 v167, v160, v167, v160
	v_mul_f32_e32 v167, 0x3f4c422a, v167
	v_add_f32_e32 v167, v167, v167
	v_mul_f32_e32 v167, 0xbfb8aa3b, v167
	v_exp_f32_e32 v167, v167
	v_fmac_f32_e32 v166, v230, v230
	v_add_f32_e32 v167, 1.0, v167
	v_rcp_f32_e32 v167, v167
	s_nop 0
	v_mul_f32_e32 v187, v160, v167
	v_mul_f32_e32 v167, v161, v173
	v_fma_f32 v167, v161, v167, v161
	v_mul_f32_e32 v167, 0x3f4c422a, v167
	v_add_f32_e32 v167, v167, v167
	v_mul_f32_e32 v167, 0xbfb8aa3b, v167
	v_exp_f32_e32 v167, v167
	v_fmac_f32_e32 v166, v187, v187
	v_add_f32_e32 v167, 1.0, v167
	v_rcp_f32_e32 v167, v167
	s_nop 0
	v_mul_f32_e32 v235, v161, v167
	v_mul_f32_e32 v167, v162, v213
	v_fma_f32 v167, v162, v167, v162
	v_mul_f32_e32 v167, 0x3f4c422a, v167
	v_add_f32_e32 v167, v167, v167
	v_mul_f32_e32 v167, 0xbfb8aa3b, v167
	v_exp_f32_e32 v167, v167
	v_fmac_f32_e32 v166, v235, v235
	v_add_f32_e32 v167, 1.0, v167
	v_rcp_f32_e32 v167, v167
	s_nop 0
	v_mul_f32_e32 v233, v162, v167
	v_mul_f32_e32 v167, v163, v205
	v_fma_f32 v167, v163, v167, v163
	v_mul_f32_e32 v167, 0x3f4c422a, v167
	v_add_f32_e32 v167, v167, v167
	v_mul_f32_e32 v167, 0xbfb8aa3b, v167
	v_exp_f32_e32 v167, v167
	v_fmac_f32_e32 v166, v233, v233
	v_add_f32_e32 v167, 1.0, v167
	v_rcp_f32_e32 v167, v167
	s_nop 0
	v_mul_f32_e32 v232, v163, v167
	v_mul_f32_e32 v167, v164, v191
	v_fma_f32 v167, v164, v167, v164
	v_mul_f32_e32 v167, 0x3f4c422a, v167
	v_add_f32_e32 v167, v167, v167
	v_mul_f32_e32 v167, 0xbfb8aa3b, v167
	v_exp_f32_e32 v167, v167
	v_fmac_f32_e32 v166, v232, v232
	v_add_f32_e32 v167, 1.0, v167
	v_rcp_f32_e32 v167, v167
	s_nop 0
	v_mul_f32_e32 v250, v164, v167
	v_mul_f32_e32 v167, v165, v172
	v_fma_f32 v167, v165, v167, v165
	v_mul_f32_e32 v167, 0x3f4c422a, v167
	v_add_f32_e32 v167, v167, v167
	v_mul_f32_e32 v167, 0xbfb8aa3b, v167
	v_exp_f32_e32 v167, v167
	v_fmac_f32_e32 v166, v250, v250
	v_add_f32_e32 v167, 1.0, v167
	v_rcp_f32_e32 v167, v167
	s_nop 0
	v_mul_f32_e32 v249, v165, v167
	v_fmac_f32_e32 v166, v249, v249
	v_mov_b32_e32 v167, v166
	s_nop 1
	v_permlane16_swap_b32_e32 v167, v166
	s_waitcnt lgkmcnt(0)
	v_add_f32_e32 v166, v166, v167
	v_mov_b32_e32 v167, v166
	s_nop 1
	v_permlane32_swap_b32_e32 v167, v166
	s_waitcnt lgkmcnt(0)
	v_add_f32_e32 v166, v166, v167
	v_fmamk_f32 v166, v166, 0x3c800000, v231
	v_rsq_f32_e32 v251, v166
	v_ashrrev_i32_e32 v166, 7, v210
	v_ashrrev_i32_e32 v167, 31, v166
	v_lshlrev_b64 v[166:167], 16, v[166:167]
	v_lshl_add_u64 v[166:167], s[12:13], 0, v[166:167]
	v_lshl_add_u64 v[166:167], v[166:167], 0, v[168:169]
	v_and_b32_e32 v168, 8, v210
	v_lshlrev_b32_e32 v168, 1, v168
	v_lshl_add_u64 v[166:167], v[166:167], 0, v[168:169]
	v_and_b32_e32 v168, 7, v210
	v_lshlrev_b32_e32 v168, 1, v168
	v_readlane_b32 s12, v254, 15
	v_lshl_add_u64 v[166:167], v[166:167], 0, v[168:169]
	s_lshl_b32 s12, s12, 1
	s_mov_b32 s13, s71
	v_lshl_add_u64 v[166:167], v[166:167], 0, s[12:13]
	v_lshlrev_b32_e32 v168, 1, v186
	v_lshl_add_u64 v[170:171], v[166:167], 0, v[168:169]
	global_load_dwordx4 v[166:169], v[202:203], off
	v_mul_f32_e32 v211, v211, v251
	s_movk_i32 s12, 0x2000
	s_waitcnt vmcnt(0)
	v_mul_f32_e32 v166, v166, v211
	v_cvt_pk_bf16_f32 v166, v166, s0
	global_store_short v[170:171], v166, off
	v_mul_f32_e32 v166, v223, v251
	v_mul_f32_e32 v166, v167, v166
	v_cvt_pk_bf16_f32 v166, v166, s0
	global_store_short v[170:171], v166, off offset:32
	v_mul_f32_e32 v166, v224, v251
	v_mul_f32_e32 v166, v168, v166
	v_cvt_pk_bf16_f32 v166, v166, s0
	global_store_short v[170:171], v166, off offset:64
	v_mul_f32_e32 v166, v225, v251
	v_mul_f32_e32 v166, v169, v166
	v_cvt_pk_bf16_f32 v166, v166, s0
	global_store_short v[170:171], v166, off offset:96
	global_load_dwordx4 v[166:169], v[202:203], off offset:16
	v_mul_f32_e32 v211, v226, v251
	s_waitcnt vmcnt(0)
	v_mul_f32_e32 v166, v211, v166
	v_cvt_pk_bf16_f32 v166, v166, s0
	global_store_short v[170:171], v166, off offset:128
	v_mul_f32_e32 v166, v227, v251
	v_mul_f32_e32 v166, v166, v167
	v_cvt_pk_bf16_f32 v166, v166, s0
	global_store_short v[170:171], v166, off offset:160
	v_mul_f32_e32 v166, v228, v251
	v_mul_f32_e32 v166, v166, v168
	v_cvt_pk_bf16_f32 v166, v166, s0
	global_store_short v[170:171], v166, off offset:192
	v_mul_f32_e32 v166, v229, v251
	v_mul_f32_e32 v166, v166, v169
	v_cvt_pk_bf16_f32 v166, v166, s0
	global_store_short v[170:171], v166, off offset:224
	global_load_dwordx4 v[166:169], v[202:203], off offset:128
	v_mul_f32_e32 v211, v248, v251
	v_add_co_u32_e32 v170, vcc, s12, v170
	s_mov_b64 s[12:13], 0
	s_nop 0
	v_addc_co_u32_e32 v171, vcc, 0, v171, vcc
	s_waitcnt vmcnt(0)
	v_mul_f32_e32 v166, v211, v166
	v_cvt_pk_bf16_f32 v166, v166, s0
	global_store_short v[170:171], v166, off
	v_mul_f32_e32 v166, v230, v251
	v_mul_f32_e32 v166, v166, v167
	v_cvt_pk_bf16_f32 v166, v166, s0
	global_store_short v[170:171], v166, off offset:32
	v_mul_f32_e32 v166, v187, v251
	v_mul_f32_e32 v166, v166, v168
	v_cvt_pk_bf16_f32 v166, v166, s0
	global_store_short v[170:171], v166, off offset:64
	v_mul_f32_e32 v166, v235, v251
	v_mul_f32_e32 v166, v166, v169
	v_cvt_pk_bf16_f32 v166, v166, s0
	global_store_short v[170:171], v166, off offset:96
	global_load_dwordx4 v[166:169], v[202:203], off offset:144
	v_mul_f32_e32 v187, v233, v251
	s_waitcnt vmcnt(0)
	v_mul_f32_e32 v166, v187, v166
	v_cvt_pk_bf16_f32 v166, v166, s0
	global_store_short v[170:171], v166, off offset:128
	v_mul_f32_e32 v166, v232, v251
	v_mul_f32_e32 v166, v166, v167
	v_cvt_pk_bf16_f32 v166, v166, s0
	global_store_short v[170:171], v166, off offset:160
	v_mul_f32_e32 v166, v250, v251
	v_mul_f32_e32 v166, v166, v168
	v_cvt_pk_bf16_f32 v166, v166, s0
	global_store_short v[170:171], v166, off offset:192
	v_mul_f32_e32 v166, v249, v251
	v_mul_f32_e32 v166, v166, v169
	v_cvt_pk_bf16_f32 v166, v166, s0
	global_store_short v[170:171], v166, off offset:224

.LBB0_97:
	s_andn2_b64 vcc, exec, s[12:13]
	s_cbranch_vccnz .LBB0_107
	v_mul_f32_e32 v166, v151, v151
	v_mul_f32_e32 v167, v153, v153
	v_fmac_f32_e32 v166, v150, v150
	v_fmac_f32_e32 v167, v152, v152
	v_add_f32_e32 v166, v166, v167
	v_mul_f32_e32 v167, v155, v155
	v_mul_f32_e32 v168, v157, v157
	v_fmac_f32_e32 v167, v154, v154
	v_fmac_f32_e32 v168, v156, v156
	v_add_f32_e32 v167, v167, v168
	v_add_f32_e32 v166, v166, v167
	v_mul_f32_e32 v167, v159, v159
	v_mul_f32_e32 v168, v161, v161
	v_fmac_f32_e32 v167, v158, v158
	v_fmac_f32_e32 v168, v160, v160
	v_add_f32_e32 v167, v167, v168
	v_add_f32_e32 v166, v167, v166
	v_mul_f32_e32 v167, v163, v163
	v_mul_f32_e32 v168, v165, v165
	v_fmac_f32_e32 v167, v162, v162
	v_fmac_f32_e32 v168, v164, v164
	v_add_f32_e32 v167, v167, v168
	v_add_f32_e32 v166, v167, v166
	v_mov_b32_e32 v167, v166
	s_nop 1
	v_permlane16_swap_b32_e32 v167, v166
	v_readlane_b32 s14, v255, 4
	v_readlane_b32 s15, v255, 5
	s_mov_b64 s[12:13], -1
	s_and_b64 vcc, exec, s[14:15]
	s_waitcnt lgkmcnt(0)
	v_add_f32_e32 v166, v166, v167
	v_mov_b32_e32 v167, v166
	s_nop 1
	v_permlane32_swap_b32_e32 v167, v166
	s_cbranch_vccz .LBB0_100
	v_ashrrev_i32_e32 v211, 31, v210
	v_lshlrev_b64 v[168:169], 7, v[210:211]
	v_lshl_add_u64 v[212:213], v[176:177], 0, v[168:169]
	s_mov_b64 s[12:13], 0

.LBB0_110:
	v_or_b32_e32 v210, 16, v204
	global_load_dwordx4 v[150:153], v[208:209], off offset:512
	v_mov_b32_e32 v154, v147
	v_mov_b32_e32 v155, v148
	v_mov_b32_e32 v147, v149
	v_pk_add_f32 v[146:147], v[154:155], v[146:147]
	v_cndmask_b32_e64 v166, 0, 1, s[88:89]
	v_add_f32_e32 v146, v146, v147
	v_fmamk_f32 v146, v146, 0x3a800000, v231
	v_rsq_f32_e32 v162, v146
	v_cmp_ne_u32_e64 s[14:15], 1, v166
	v_cndmask_b32_e64 v166, 0, 1, s[80:81]
	s_andn2_b64 vcc, exec, s[88:89]
	v_pk_fma_f32 v[148:149], v[20:21], v[162:163], v[144:145] op_sel_hi:[1,0,1]
	v_pk_fma_f32 v[146:147], v[18:19], v[162:163], v[142:143] op_sel_hi:[1,0,1]
	v_pk_fma_f32 v[156:157], v[12:13], v[162:163], v[140:141] op_sel_hi:[1,0,1]
	v_pk_fma_f32 v[154:155], v[10:11], v[162:163], v[138:139] op_sel_hi:[1,0,1]
	v_pk_fma_f32 v[160:161], v[8:9], v[162:163], v[136:137] op_sel_hi:[1,0,1]
	v_pk_fma_f32 v[158:159], v[6:7], v[162:163], v[134:135] op_sel_hi:[1,0,1]
	v_pk_fma_f32 v[164:165], v[4:5], v[162:163], v[132:133] op_sel_hi:[1,0,1]
	v_pk_fma_f32 v[162:163], v[2:3], v[162:163], v[130:131] op_sel_hi:[1,0,1]
	v_cmp_ne_u32_e64 s[12:13], 1, v166
	s_cbranch_vccnz .LBB0_326
	s_and_b64 vcc, exec, s[12:13]
	s_mov_b64 s[80:81], -1
	s_cbranch_vccnz .LBB0_129
	v_readlane_b32 s80, v254, 60
	v_readlane_b32 s81, v254, 61
	s_andn2_b64 vcc, exec, s[80:81]
	s_mov_b64 s[80:81], -1
	s_cbranch_vccnz .LBB0_118
	v_readlane_b32 s88, v254, 62
	v_readlane_b32 s89, v254, 63
	s_andn2_b64 vcc, exec, s[88:89]
	v_mul_f32_e32 v222, 0x3d372713, v146
	v_mul_f32_e32 v220, 0x3d372713, v147
	v_mul_f32_e32 v218, 0x3d372713, v148
	v_mul_f32_e32 v216, 0x3d372713, v149
	v_mul_f32_e32 v221, 0x3d372713, v154
	v_mul_f32_e32 v219, 0x3d372713, v155
	v_mul_f32_e32 v217, 0x3d372713, v156
	v_mul_f32_e32 v215, 0x3d372713, v157
	v_mul_f32_e32 v214, 0x3d372713, v158
	v_mul_f32_e32 v212, 0x3d372713, v159
	v_mul_f32_e32 v199, 0x3d372713, v160
	v_mul_f32_e32 v173, 0x3d372713, v161
	v_mul_f32_e32 v213, 0x3d372713, v162
	v_mul_f32_e32 v205, 0x3d372713, v163
	v_mul_f32_e32 v191, 0x3d372713, v164
	v_mul_f32_e32 v172, 0x3d372713, v165
	s_cbranch_vccnz .LBB0_115
	v_mul_f32_e32 v167, v148, v218
	v_fma_f32 v167, v148, v167, v148
	v_mul_f32_e32 v167, 0x3f4c422a, v167
	v_add_f32_e32 v167, v167, v167
	v_mul_f32_e32 v167, 0xbfb8aa3b, v167
	v_exp_f32_e32 v167, v167
	v_mul_f32_e32 v166, v146, v222
	v_fma_f32 v166, v146, v166, v146
	v_mul_f32_e32 v166, 0x3f4c422a, v166
	v_add_f32_e32 v167, 1.0, v167
	v_rcp_f32_e32 v167, v167
	v_add_f32_e32 v166, v166, v166
	v_mul_f32_e32 v166, 0xbfb8aa3b, v166
	v_exp_f32_e32 v166, v166
	v_mul_f32_e32 v224, v148, v167
	v_mul_f32_e32 v167, v149, v216
	v_fma_f32 v167, v149, v167, v149
	v_mul_f32_e32 v167, 0x3f4c422a, v167
	v_add_f32_e32 v167, v167, v167
	v_mul_f32_e32 v167, 0xbfb8aa3b, v167
	v_exp_f32_e32 v167, v167
	v_add_f32_e32 v166, 1.0, v166
	v_rcp_f32_e32 v166, v166
	v_readlane_b32 s80, v255, 0
	v_add_f32_e32 v167, 1.0, v167
	v_rcp_f32_e32 v167, v167
	v_mul_f32_e32 v211, v146, v166
	v_mul_f32_e32 v166, v147, v220
	v_fma_f32 v166, v147, v166, v147
	v_mul_f32_e32 v225, v149, v167
	v_mul_f32_e32 v167, v154, v221
	v_fma_f32 v167, v154, v167, v154
	v_mul_f32_e32 v167, 0x3f4c422a, v167
	v_add_f32_e32 v167, v167, v167
	v_mul_f32_e32 v167, 0xbfb8aa3b, v167
	v_exp_f32_e32 v167, v167
	v_mul_f32_e32 v166, 0x3f4c422a, v166
	v_add_f32_e32 v166, v166, v166
	v_mul_f32_e32 v166, 0xbfb8aa3b, v166
	v_add_f32_e32 v167, 1.0, v167
	v_rcp_f32_e32 v167, v167
	v_exp_f32_e32 v166, v166
	v_readlane_b32 s81, v255, 1
	v_lshlrev_b32_e32 v168, 6, v210
	v_mul_f32_e32 v226, v154, v167
	v_mul_f32_e32 v167, v155, v219
	v_fma_f32 v167, v155, v167, v155
	v_mul_f32_e32 v167, 0x3f4c422a, v167
	v_add_f32_e32 v167, v167, v167
	v_mul_f32_e32 v167, 0xbfb8aa3b, v167
	v_exp_f32_e32 v167, v167
	v_add_f32_e32 v166, 1.0, v166
	v_rcp_f32_e32 v166, v166
	v_and_b32_e32 v168, 0x1c00, v168
	v_add_f32_e32 v167, 1.0, v167
	v_rcp_f32_e32 v167, v167
	v_mul_f32_e32 v223, v147, v166
	v_mul_f32_e32 v166, v223, v223
	v_fmac_f32_e32 v166, v211, v211
	v_mul_f32_e32 v227, v155, v167
	v_mul_f32_e32 v167, v156, v217
	v_fma_f32 v167, v156, v167, v156
	v_mul_f32_e32 v167, 0x3f4c422a, v167
	v_add_f32_e32 v167, v167, v167
	v_mul_f32_e32 v167, 0xbfb8aa3b, v167
	v_exp_f32_e32 v167, v167
	v_fmac_f32_e32 v166, v224, v224
	v_fmac_f32_e32 v166, v225, v225
	v_fmac_f32_e32 v166, v226, v226
	v_add_f32_e32 v167, 1.0, v167
	v_rcp_f32_e32 v167, v167
	v_fmac_f32_e32 v166, v227, v227
	v_mov_b32_e32 v169, v1
	v_readlane_b32 s17, v254, 15
	v_mul_f32_e32 v228, v156, v167
	v_mul_f32_e32 v167, v157, v215
	v_fma_f32 v167, v157, v167, v157
	v_mul_f32_e32 v167, 0x3f4c422a, v167
	v_add_f32_e32 v167, v167, v167
	v_mul_f32_e32 v167, 0xbfb8aa3b, v167
	v_exp_f32_e32 v167, v167
	v_fmac_f32_e32 v166, v228, v228
	v_add_f32_e32 v167, 1.0, v167
	v_rcp_f32_e32 v167, v167
	s_nop 0
	v_mul_f32_e32 v229, v157, v167
	v_mul_f32_e32 v167, v158, v214
	v_fma_f32 v167, v158, v167, v158
	v_mul_f32_e32 v167, 0x3f4c422a, v167
	v_add_f32_e32 v167, v167, v167
	v_mul_f32_e32 v167, 0xbfb8aa3b, v167
	v_exp_f32_e32 v167, v167
	v_fmac_f32_e32 v166, v229, v229
	v_add_f32_e32 v167, 1.0, v167
	v_rcp_f32_e32 v167, v167
	s_nop 0
	v_mul_f32_e32 v248, v158, v167
	v_mul_f32_e32 v167, v159, v212
	v_fma_f32 v167, v159, v167, v159
	v_mul_f32_e32 v167, 0x3f4c422a, v167
	v_add_f32_e32 v167, v167, v167
	v_mul_f32_e32 v167, 0xbfb8aa3b, v167
	v_exp_f32_e32 v167, v167
	v_fmac_f32_e32 v166, v248, v248
	v_add_f32_e32 v167, 1.0, v167
	v_rcp_f32_e32 v167, v167
	s_nop 0
	v_mul_f32_e32 v230, v159, v167
	v_mul_f32_e32 v167, v160, v199
	v_fma_f32 v167, v160, v167, v160
	v_mul_f32_e32 v167, 0x3f4c422a, v167
	v_add_f32_e32 v167, v167, v167
	v_mul_f32_e32 v167, 0xbfb8aa3b, v167
	v_exp_f32_e32 v167, v167
	v_fmac_f32_e32 v166, v230, v230
	v_add_f32_e32 v167, 1.0, v167
	v_rcp_f32_e32 v167, v167
	s_nop 0
	v_mul_f32_e32 v187, v160, v167
	v_mul_f32_e32 v167, v161, v173
	v_fma_f32 v167, v161, v167, v161
	v_mul_f32_e32 v167, 0x3f4c422a, v167
	v_add_f32_e32 v167, v167, v167
	v_mul_f32_e32 v167, 0xbfb8aa3b, v167
	v_exp_f32_e32 v167, v167
	v_fmac_f32_e32 v166, v187, v187
	v_add_f32_e32 v167, 1.0, v167
	v_rcp_f32_e32 v167, v167
	s_nop 0
	v_mul_f32_e32 v235, v161, v167
	v_mul_f32_e32 v167, v162, v213
	v_fma_f32 v167, v162, v167, v162
	v_mul_f32_e32 v167, 0x3f4c422a, v167
	v_add_f32_e32 v167, v167, v167
	v_mul_f32_e32 v167, 0xbfb8aa3b, v167
	v_exp_f32_e32 v167, v167
	v_fmac_f32_e32 v166, v235, v235
	v_add_f32_e32 v167, 1.0, v167
	v_rcp_f32_e32 v167, v167
	s_nop 0
	v_mul_f32_e32 v233, v162, v167
	v_mul_f32_e32 v167, v163, v205
	v_fma_f32 v167, v163, v167, v163
	v_mul_f32_e32 v167, 0x3f4c422a, v167
	v_add_f32_e32 v167, v167, v167
	v_mul_f32_e32 v167, 0xbfb8aa3b, v167
	v_exp_f32_e32 v167, v167
	v_fmac_f32_e32 v166, v233, v233
	v_add_f32_e32 v167, 1.0, v167
	v_rcp_f32_e32 v167, v167
	s_nop 0
	v_mul_f32_e32 v232, v163, v167
	v_mul_f32_e32 v167, v164, v191
	v_fma_f32 v167, v164, v167, v164
	v_mul_f32_e32 v167, 0x3f4c422a, v167
	v_add_f32_e32 v167, v167, v167
	v_mul_f32_e32 v167, 0xbfb8aa3b, v167
	v_exp_f32_e32 v167, v167
	v_fmac_f32_e32 v166, v232, v232
	v_add_f32_e32 v167, 1.0, v167
	v_rcp_f32_e32 v167, v167
	s_nop 0
	v_mul_f32_e32 v250, v164, v167
	v_mul_f32_e32 v167, v165, v172
	v_fma_f32 v167, v165, v167, v165
	v_mul_f32_e32 v167, 0x3f4c422a, v167
	v_add_f32_e32 v167, v167, v167
	v_mul_f32_e32 v167, 0xbfb8aa3b, v167
	v_exp_f32_e32 v167, v167
	v_fmac_f32_e32 v166, v250, v250
	v_add_f32_e32 v167, 1.0, v167
	v_rcp_f32_e32 v167, v167
	s_nop 0
	v_mul_f32_e32 v249, v165, v167
	v_fmac_f32_e32 v166, v249, v249
	v_mov_b32_e32 v167, v166
	s_nop 1
	v_permlane16_swap_b32_e32 v167, v166
	s_waitcnt lgkmcnt(0)
	v_add_f32_e32 v166, v166, v167
	v_mov_b32_e32 v167, v166
	s_nop 1
	v_permlane32_swap_b32_e32 v167, v166
	s_waitcnt lgkmcnt(0)
	v_add_f32_e32 v166, v166, v167
	v_fmamk_f32 v166, v166, 0x3c800000, v231
	v_rsq_f32_e32 v251, v166
	v_ashrrev_i32_e32 v166, 7, v210
	v_ashrrev_i32_e32 v167, 31, v166
	v_lshlrev_b64 v[166:167], 16, v[166:167]
	v_lshl_add_u64 v[166:167], s[80:81], 0, v[166:167]
	v_lshl_add_u64 v[166:167], v[166:167], 0, v[168:169]
	v_and_b32_e32 v168, 8, v210
	v_lshlrev_b32_e32 v168, 1, v168
	v_lshl_add_u64 v[166:167], v[166:167], 0, v[168:169]
	v_and_b32_e32 v168, 7, v210
	v_lshlrev_b32_e32 v168, 1, v168
	v_lshl_add_u64 v[166:167], v[166:167], 0, v[168:169]
	s_lshl_b32 s80, s17, 1
	s_mov_b32 s81, s71
	v_lshl_add_u64 v[166:167], v[166:167], 0, s[80:81]
	v_lshlrev_b32_e32 v168, 1, v186
	v_lshl_add_u64 v[170:171], v[166:167], 0, v[168:169]
	global_load_dwordx4 v[166:169], v[202:203], off
	v_mul_f32_e32 v211, v211, v251
	s_movk_i32 s17, 0x2000
	s_mov_b64 s[80:81], 0
	s_waitcnt vmcnt(0)
	v_mul_f32_e32 v166, v166, v211
	v_cvt_pk_bf16_f32 v166, v166, s0
	global_store_short v[170:171], v166, off
	v_mul_f32_e32 v166, v223, v251
	v_mul_f32_e32 v166, v167, v166
	v_cvt_pk_bf16_f32 v166, v166, s0
	global_store_short v[170:171], v166, off offset:32
	v_mul_f32_e32 v166, v224, v251
	v_mul_f32_e32 v166, v168, v166
	v_cvt_pk_bf16_f32 v166, v166, s0
	global_store_short v[170:171], v166, off offset:64
	v_mul_f32_e32 v166, v225, v251
	v_mul_f32_e32 v166, v169, v166
	v_cvt_pk_bf16_f32 v166, v166, s0
	global_store_short v[170:171], v166, off offset:96
	global_load_dwordx4 v[166:169], v[202:203], off offset:16
	v_mul_f32_e32 v211, v226, v251
	s_waitcnt vmcnt(0)
	v_mul_f32_e32 v166, v211, v166
	v_cvt_pk_bf16_f32 v166, v166, s0
	global_store_short v[170:171], v166, off offset:128
	v_mul_f32_e32 v166, v227, v251
	v_mul_f32_e32 v166, v166, v167
	v_cvt_pk_bf16_f32 v166, v166, s0
	global_store_short v[170:171], v166, off offset:160
	v_mul_f32_e32 v166, v228, v251
	v_mul_f32_e32 v166, v166, v168
	v_cvt_pk_bf16_f32 v166, v166, s0
	global_store_short v[170:171], v166, off offset:192
	v_mul_f32_e32 v166, v229, v251
	v_mul_f32_e32 v166, v166, v169
	v_cvt_pk_bf16_f32 v166, v166, s0
	global_store_short v[170:171], v166, off offset:224
	global_load_dwordx4 v[166:169], v[202:203], off offset:128
	v_mul_f32_e32 v211, v248, v251
	v_add_co_u32_e32 v170, vcc, s17, v170
	s_waitcnt vmcnt(0)
	v_mul_f32_e32 v166, v211, v166
	v_cvt_pk_bf16_f32 v166, v166, s0
	v_addc_co_u32_e32 v171, vcc, 0, v171, vcc
	global_store_short v[170:171], v166, off
	v_mul_f32_e32 v166, v230, v251
	v_mul_f32_e32 v166, v166, v167
	v_cvt_pk_bf16_f32 v166, v166, s0
	global_store_short v[170:171], v166, off offset:32
	v_mul_f32_e32 v166, v187, v251
	v_mul_f32_e32 v166, v166, v168
	v_cvt_pk_bf16_f32 v166, v166, s0
	global_store_short v[170:171], v166, off offset:64
	v_mul_f32_e32 v166, v235, v251
	v_mul_f32_e32 v166, v166, v169
	v_cvt_pk_bf16_f32 v166, v166, s0
	global_store_short v[170:171], v166, off offset:96
	global_load_dwordx4 v[166:169], v[202:203], off offset:144
	v_mul_f32_e32 v187, v233, v251
	s_waitcnt vmcnt(0)
	v_mul_f32_e32 v166, v187, v166
	v_cvt_pk_bf16_f32 v166, v166, s0
	global_store_short v[170:171], v166, off offset:128
	v_mul_f32_e32 v166, v232, v251
	v_mul_f32_e32 v166, v166, v167
	v_cvt_pk_bf16_f32 v166, v166, s0
	global_store_short v[170:171], v166, off offset:160
	v_mul_f32_e32 v166, v250, v251
	v_mul_f32_e32 v166, v166, v168
	v_cvt_pk_bf16_f32 v166, v166, s0
	global_store_short v[170:171], v166, off offset:192
	v_mul_f32_e32 v166, v249, v251
	v_mul_f32_e32 v166, v166, v169
	v_cvt_pk_bf16_f32 v166, v166, s0
	global_store_short v[170:171], v166, off offset:224

.LBB0_129:
	s_andn2_b64 vcc, exec, s[80:81]
	s_cbranch_vccnz .LBB0_139
	v_mul_f32_e32 v166, v147, v147
	v_mul_f32_e32 v167, v149, v149
	v_fmac_f32_e32 v166, v146, v146
	v_fmac_f32_e32 v167, v148, v148
	v_add_f32_e32 v166, v166, v167
	v_mul_f32_e32 v167, v155, v155
	v_mul_f32_e32 v168, v157, v157
	v_fmac_f32_e32 v167, v154, v154
	v_fmac_f32_e32 v168, v156, v156
	v_add_f32_e32 v167, v167, v168
	v_add_f32_e32 v166, v166, v167
	v_mul_f32_e32 v167, v159, v159
	v_mul_f32_e32 v168, v161, v161
	v_fmac_f32_e32 v167, v158, v158
	v_fmac_f32_e32 v168, v160, v160
	v_add_f32_e32 v167, v167, v168
	v_add_f32_e32 v166, v167, v166
	v_mul_f32_e32 v167, v163, v163
	v_mul_f32_e32 v168, v165, v165
	v_fmac_f32_e32 v167, v162, v162
	v_fmac_f32_e32 v168, v164, v164
	v_add_f32_e32 v167, v167, v168
	v_add_f32_e32 v166, v167, v166
	v_mov_b32_e32 v167, v166
	s_nop 1
	v_permlane16_swap_b32_e32 v167, v166
	v_readlane_b32 s80, v255, 4
	v_readlane_b32 s81, v255, 5
	s_andn2_b64 vcc, exec, s[80:81]
	s_mov_b64 s[80:81], -1
	s_waitcnt lgkmcnt(0)
	v_add_f32_e32 v166, v166, v167
	v_mov_b32_e32 v167, v166
	s_nop 1
	v_permlane32_swap_b32_e32 v167, v166
	s_cbranch_vccnz .LBB0_132
	v_ashrrev_i32_e32 v211, 31, v210
	v_lshlrev_b64 v[168:169], 7, v[210:211]
	v_lshl_add_u64 v[212:213], v[176:177], 0, v[168:169]
	s_mov_b64 s[80:81], 0

.LBB0_141:
	v_or_b32_e32 v210, 32, v204
	global_load_dwordx4 v[146:149], v[208:209], off offset:768
	s_waitcnt vmcnt(1)
	v_mov_b32_e32 v154, v151
	v_mov_b32_e32 v155, v152
	v_mov_b32_e32 v151, v153
	v_pk_add_f32 v[150:151], v[154:155], v[150:151]
	s_and_b64 vcc, exec, s[14:15]
	v_add_f32_e32 v150, v150, v151
	v_fmamk_f32 v150, v150, 0x3a800000, v231
	v_rsq_f32_e32 v162, v150
	s_nop 0
	v_pk_fma_f32 v[152:153], v[128:129], v[162:163], v[144:145] op_sel_hi:[1,0,1]
	v_pk_fma_f32 v[150:151], v[126:127], v[162:163], v[142:143] op_sel_hi:[1,0,1]
	v_pk_fma_f32 v[156:157], v[124:125], v[162:163], v[140:141] op_sel_hi:[1,0,1]
	v_pk_fma_f32 v[154:155], v[122:123], v[162:163], v[138:139] op_sel_hi:[1,0,1]
	v_pk_fma_f32 v[160:161], v[120:121], v[162:163], v[136:137] op_sel_hi:[1,0,1]
	v_pk_fma_f32 v[158:159], v[118:119], v[162:163], v[134:135] op_sel_hi:[1,0,1]
	v_pk_fma_f32 v[164:165], v[116:117], v[162:163], v[132:133] op_sel_hi:[1,0,1]
	v_pk_fma_f32 v[162:163], v[114:115], v[162:163], v[130:131] op_sel_hi:[1,0,1]
	s_cbranch_vccnz .LBB0_327
	s_and_b64 vcc, exec, s[12:13]
	s_mov_b64 s[80:81], -1
	s_cbranch_vccnz .LBB0_160
	v_readlane_b32 s80, v254, 60
	v_readlane_b32 s81, v254, 61
	s_andn2_b64 vcc, exec, s[80:81]
	s_mov_b64 s[80:81], -1
	s_cbranch_vccnz .LBB0_149
	v_readlane_b32 s88, v254, 62
	v_readlane_b32 s89, v254, 63
	s_andn2_b64 vcc, exec, s[88:89]
	v_mul_f32_e32 v222, 0x3d372713, v150
	v_mul_f32_e32 v220, 0x3d372713, v151
	v_mul_f32_e32 v218, 0x3d372713, v152
	v_mul_f32_e32 v216, 0x3d372713, v153
	v_mul_f32_e32 v221, 0x3d372713, v154
	v_mul_f32_e32 v219, 0x3d372713, v155
	v_mul_f32_e32 v217, 0x3d372713, v156
	v_mul_f32_e32 v215, 0x3d372713, v157
	v_mul_f32_e32 v214, 0x3d372713, v158
	v_mul_f32_e32 v212, 0x3d372713, v159
	v_mul_f32_e32 v199, 0x3d372713, v160
	v_mul_f32_e32 v173, 0x3d372713, v161
	v_mul_f32_e32 v213, 0x3d372713, v162
	v_mul_f32_e32 v205, 0x3d372713, v163
	v_mul_f32_e32 v191, 0x3d372713, v164
	v_mul_f32_e32 v172, 0x3d372713, v165
	s_cbranch_vccnz .LBB0_146
	v_mul_f32_e32 v167, v152, v218
	v_fma_f32 v167, v152, v167, v152
	v_mul_f32_e32 v167, 0x3f4c422a, v167
	v_add_f32_e32 v167, v167, v167
	v_mul_f32_e32 v167, 0xbfb8aa3b, v167
	v_exp_f32_e32 v167, v167
	v_mul_f32_e32 v166, v150, v222
	v_fma_f32 v166, v150, v166, v150
	v_mul_f32_e32 v166, 0x3f4c422a, v166
	v_add_f32_e32 v167, 1.0, v167
	v_rcp_f32_e32 v167, v167
	v_add_f32_e32 v166, v166, v166
	v_mul_f32_e32 v166, 0xbfb8aa3b, v166
	v_exp_f32_e32 v166, v166
	v_mul_f32_e32 v224, v152, v167
	v_mul_f32_e32 v167, v153, v216
	v_fma_f32 v167, v153, v167, v153
	v_mul_f32_e32 v167, 0x3f4c422a, v167
	v_add_f32_e32 v167, v167, v167
	v_mul_f32_e32 v167, 0xbfb8aa3b, v167
	v_exp_f32_e32 v167, v167
	v_add_f32_e32 v166, 1.0, v166
	v_rcp_f32_e32 v166, v166
	v_readlane_b32 s80, v255, 0
	v_add_f32_e32 v167, 1.0, v167
	v_rcp_f32_e32 v167, v167
	v_mul_f32_e32 v211, v150, v166
	v_mul_f32_e32 v166, v151, v220
	v_fma_f32 v166, v151, v166, v151
	v_mul_f32_e32 v225, v153, v167
	v_mul_f32_e32 v167, v154, v221
	v_fma_f32 v167, v154, v167, v154
	v_mul_f32_e32 v167, 0x3f4c422a, v167
	v_add_f32_e32 v167, v167, v167
	v_mul_f32_e32 v167, 0xbfb8aa3b, v167
	v_exp_f32_e32 v167, v167
	v_mul_f32_e32 v166, 0x3f4c422a, v166
	v_add_f32_e32 v166, v166, v166
	v_mul_f32_e32 v166, 0xbfb8aa3b, v166
	v_add_f32_e32 v167, 1.0, v167
	v_rcp_f32_e32 v167, v167
	v_exp_f32_e32 v166, v166
	v_readlane_b32 s81, v255, 1
	v_lshlrev_b32_e32 v168, 6, v210
	v_mul_f32_e32 v226, v154, v167
	v_mul_f32_e32 v167, v155, v219
	v_fma_f32 v167, v155, v167, v155
	v_mul_f32_e32 v167, 0x3f4c422a, v167
	v_add_f32_e32 v167, v167, v167
	v_mul_f32_e32 v167, 0xbfb8aa3b, v167
	v_exp_f32_e32 v167, v167
	v_add_f32_e32 v166, 1.0, v166
	v_rcp_f32_e32 v166, v166
	v_and_b32_e32 v168, 0x1c00, v168
	v_add_f32_e32 v167, 1.0, v167
	v_rcp_f32_e32 v167, v167
	v_mul_f32_e32 v223, v151, v166
	v_mul_f32_e32 v166, v223, v223
	v_fmac_f32_e32 v166, v211, v211
	v_mul_f32_e32 v227, v155, v167
	v_mul_f32_e32 v167, v156, v217
	v_fma_f32 v167, v156, v167, v156
	v_mul_f32_e32 v167, 0x3f4c422a, v167
	v_add_f32_e32 v167, v167, v167
	v_mul_f32_e32 v167, 0xbfb8aa3b, v167
	v_exp_f32_e32 v167, v167
	v_fmac_f32_e32 v166, v224, v224
	v_fmac_f32_e32 v166, v225, v225
	v_fmac_f32_e32 v166, v226, v226
	v_add_f32_e32 v167, 1.0, v167
	v_rcp_f32_e32 v167, v167
	v_fmac_f32_e32 v166, v227, v227
	v_mov_b32_e32 v169, v1
	v_readlane_b32 s17, v254, 15
	v_mul_f32_e32 v228, v156, v167
	v_mul_f32_e32 v167, v157, v215
	v_fma_f32 v167, v157, v167, v157
	v_mul_f32_e32 v167, 0x3f4c422a, v167
	v_add_f32_e32 v167, v167, v167
	v_mul_f32_e32 v167, 0xbfb8aa3b, v167
	v_exp_f32_e32 v167, v167
	v_fmac_f32_e32 v166, v228, v228
	v_add_f32_e32 v167, 1.0, v167
	v_rcp_f32_e32 v167, v167
	s_nop 0
	v_mul_f32_e32 v229, v157, v167
	v_mul_f32_e32 v167, v158, v214
	v_fma_f32 v167, v158, v167, v158
	v_mul_f32_e32 v167, 0x3f4c422a, v167
	v_add_f32_e32 v167, v167, v167
	v_mul_f32_e32 v167, 0xbfb8aa3b, v167
	v_exp_f32_e32 v167, v167
	v_fmac_f32_e32 v166, v229, v229
	v_add_f32_e32 v167, 1.0, v167
	v_rcp_f32_e32 v167, v167
	s_nop 0
	v_mul_f32_e32 v248, v158, v167
	v_mul_f32_e32 v167, v159, v212
	v_fma_f32 v167, v159, v167, v159
	v_mul_f32_e32 v167, 0x3f4c422a, v167
	v_add_f32_e32 v167, v167, v167
	v_mul_f32_e32 v167, 0xbfb8aa3b, v167
	v_exp_f32_e32 v167, v167
	v_fmac_f32_e32 v166, v248, v248
	v_add_f32_e32 v167, 1.0, v167
	v_rcp_f32_e32 v167, v167
	s_nop 0
	v_mul_f32_e32 v230, v159, v167
	v_mul_f32_e32 v167, v160, v199
	v_fma_f32 v167, v160, v167, v160
	v_mul_f32_e32 v167, 0x3f4c422a, v167
	v_add_f32_e32 v167, v167, v167
	v_mul_f32_e32 v167, 0xbfb8aa3b, v167
	v_exp_f32_e32 v167, v167
	v_fmac_f32_e32 v166, v230, v230
	v_add_f32_e32 v167, 1.0, v167
	v_rcp_f32_e32 v167, v167
	s_nop 0
	v_mul_f32_e32 v187, v160, v167
	v_mul_f32_e32 v167, v161, v173
	v_fma_f32 v167, v161, v167, v161
	v_mul_f32_e32 v167, 0x3f4c422a, v167
	v_add_f32_e32 v167, v167, v167
	v_mul_f32_e32 v167, 0xbfb8aa3b, v167
	v_exp_f32_e32 v167, v167
	v_fmac_f32_e32 v166, v187, v187
	v_add_f32_e32 v167, 1.0, v167
	v_rcp_f32_e32 v167, v167
	s_nop 0
	v_mul_f32_e32 v235, v161, v167
	v_mul_f32_e32 v167, v162, v213
	v_fma_f32 v167, v162, v167, v162
	v_mul_f32_e32 v167, 0x3f4c422a, v167
	v_add_f32_e32 v167, v167, v167
	v_mul_f32_e32 v167, 0xbfb8aa3b, v167
	v_exp_f32_e32 v167, v167
	v_fmac_f32_e32 v166, v235, v235
	v_add_f32_e32 v167, 1.0, v167
	v_rcp_f32_e32 v167, v167
	s_nop 0
	v_mul_f32_e32 v233, v162, v167
	v_mul_f32_e32 v167, v163, v205
	v_fma_f32 v167, v163, v167, v163
	v_mul_f32_e32 v167, 0x3f4c422a, v167
	v_add_f32_e32 v167, v167, v167
	v_mul_f32_e32 v167, 0xbfb8aa3b, v167
	v_exp_f32_e32 v167, v167
	v_fmac_f32_e32 v166, v233, v233
	v_add_f32_e32 v167, 1.0, v167
	v_rcp_f32_e32 v167, v167
	s_nop 0
	v_mul_f32_e32 v232, v163, v167
	v_mul_f32_e32 v167, v164, v191
	v_fma_f32 v167, v164, v167, v164
	v_mul_f32_e32 v167, 0x3f4c422a, v167
	v_add_f32_e32 v167, v167, v167
	v_mul_f32_e32 v167, 0xbfb8aa3b, v167
	v_exp_f32_e32 v167, v167
	v_fmac_f32_e32 v166, v232, v232
	v_add_f32_e32 v167, 1.0, v167
	v_rcp_f32_e32 v167, v167
	s_nop 0
	v_mul_f32_e32 v250, v164, v167
	v_mul_f32_e32 v167, v165, v172
	v_fma_f32 v167, v165, v167, v165
	v_mul_f32_e32 v167, 0x3f4c422a, v167
	v_add_f32_e32 v167, v167, v167
	v_mul_f32_e32 v167, 0xbfb8aa3b, v167
	v_exp_f32_e32 v167, v167
	v_fmac_f32_e32 v166, v250, v250
	v_add_f32_e32 v167, 1.0, v167
	v_rcp_f32_e32 v167, v167
	s_nop 0
	v_mul_f32_e32 v249, v165, v167
	v_fmac_f32_e32 v166, v249, v249
	v_mov_b32_e32 v167, v166
	s_nop 1
	v_permlane16_swap_b32_e32 v167, v166
	s_waitcnt lgkmcnt(0)
	v_add_f32_e32 v166, v166, v167
	v_mov_b32_e32 v167, v166
	s_nop 1
	v_permlane32_swap_b32_e32 v167, v166
	s_waitcnt lgkmcnt(0)
	v_add_f32_e32 v166, v166, v167
	v_fmamk_f32 v166, v166, 0x3c800000, v231
	v_rsq_f32_e32 v251, v166
	v_ashrrev_i32_e32 v166, 7, v210
	v_ashrrev_i32_e32 v167, 31, v166
	v_lshlrev_b64 v[166:167], 16, v[166:167]
	v_lshl_add_u64 v[166:167], s[80:81], 0, v[166:167]
	v_lshl_add_u64 v[166:167], v[166:167], 0, v[168:169]
	v_and_b32_e32 v168, 8, v210
	v_lshlrev_b32_e32 v168, 1, v168
	v_lshl_add_u64 v[166:167], v[166:167], 0, v[168:169]
	v_and_b32_e32 v168, 7, v210
	v_lshlrev_b32_e32 v168, 1, v168
	v_lshl_add_u64 v[166:167], v[166:167], 0, v[168:169]
	s_lshl_b32 s80, s17, 1
	s_mov_b32 s81, s71
	v_lshl_add_u64 v[166:167], v[166:167], 0, s[80:81]
	v_lshlrev_b32_e32 v168, 1, v186
	v_lshl_add_u64 v[170:171], v[166:167], 0, v[168:169]
	global_load_dwordx4 v[166:169], v[202:203], off
	v_mul_f32_e32 v211, v211, v251
	s_movk_i32 s17, 0x2000
	s_mov_b64 s[80:81], 0
	s_waitcnt vmcnt(0)
	v_mul_f32_e32 v166, v166, v211
	v_cvt_pk_bf16_f32 v166, v166, s0
	global_store_short v[170:171], v166, off
	v_mul_f32_e32 v166, v223, v251
	v_mul_f32_e32 v166, v167, v166
	v_cvt_pk_bf16_f32 v166, v166, s0
	global_store_short v[170:171], v166, off offset:32
	v_mul_f32_e32 v166, v224, v251
	v_mul_f32_e32 v166, v168, v166
	v_cvt_pk_bf16_f32 v166, v166, s0
	global_store_short v[170:171], v166, off offset:64
	v_mul_f32_e32 v166, v225, v251
	v_mul_f32_e32 v166, v169, v166
	v_cvt_pk_bf16_f32 v166, v166, s0
	global_store_short v[170:171], v166, off offset:96
	global_load_dwordx4 v[166:169], v[202:203], off offset:16
	v_mul_f32_e32 v211, v226, v251
	s_waitcnt vmcnt(0)
	v_mul_f32_e32 v166, v211, v166
	v_cvt_pk_bf16_f32 v166, v166, s0
	global_store_short v[170:171], v166, off offset:128
	v_mul_f32_e32 v166, v227, v251
	v_mul_f32_e32 v166, v166, v167
	v_cvt_pk_bf16_f32 v166, v166, s0
	global_store_short v[170:171], v166, off offset:160
	v_mul_f32_e32 v166, v228, v251
	v_mul_f32_e32 v166, v166, v168
	v_cvt_pk_bf16_f32 v166, v166, s0
	global_store_short v[170:171], v166, off offset:192
	v_mul_f32_e32 v166, v229, v251
	v_mul_f32_e32 v166, v166, v169
	v_cvt_pk_bf16_f32 v166, v166, s0
	global_store_short v[170:171], v166, off offset:224
	global_load_dwordx4 v[166:169], v[202:203], off offset:128
	v_mul_f32_e32 v211, v248, v251
	v_add_co_u32_e32 v170, vcc, s17, v170
	s_waitcnt vmcnt(0)
	v_mul_f32_e32 v166, v211, v166
	v_cvt_pk_bf16_f32 v166, v166, s0
	v_addc_co_u32_e32 v171, vcc, 0, v171, vcc
	global_store_short v[170:171], v166, off
	v_mul_f32_e32 v166, v230, v251
	v_mul_f32_e32 v166, v166, v167
	v_cvt_pk_bf16_f32 v166, v166, s0
	global_store_short v[170:171], v166, off offset:32
	v_mul_f32_e32 v166, v187, v251
	v_mul_f32_e32 v166, v166, v168
	v_cvt_pk_bf16_f32 v166, v166, s0
	global_store_short v[170:171], v166, off offset:64
	v_mul_f32_e32 v166, v235, v251
	v_mul_f32_e32 v166, v166, v169
	v_cvt_pk_bf16_f32 v166, v166, s0
	global_store_short v[170:171], v166, off offset:96
	global_load_dwordx4 v[166:169], v[202:203], off offset:144
	v_mul_f32_e32 v187, v233, v251
	s_waitcnt vmcnt(0)
	v_mul_f32_e32 v166, v187, v166
	v_cvt_pk_bf16_f32 v166, v166, s0
	global_store_short v[170:171], v166, off offset:128
	v_mul_f32_e32 v166, v232, v251
	v_mul_f32_e32 v166, v166, v167
	v_cvt_pk_bf16_f32 v166, v166, s0
	global_store_short v[170:171], v166, off offset:160
	v_mul_f32_e32 v166, v250, v251
	v_mul_f32_e32 v166, v166, v168
	v_cvt_pk_bf16_f32 v166, v166, s0
	global_store_short v[170:171], v166, off offset:192
	v_mul_f32_e32 v166, v249, v251
	v_mul_f32_e32 v166, v166, v169
	v_cvt_pk_bf16_f32 v166, v166, s0
	global_store_short v[170:171], v166, off offset:224

.LBB0_160:
	s_andn2_b64 vcc, exec, s[80:81]
	s_cbranch_vccnz .LBB0_170
	v_mul_f32_e32 v166, v151, v151
	v_mul_f32_e32 v167, v153, v153
	v_fmac_f32_e32 v166, v150, v150
	v_fmac_f32_e32 v167, v152, v152
	v_add_f32_e32 v166, v166, v167
	v_mul_f32_e32 v167, v155, v155
	v_mul_f32_e32 v168, v157, v157
	v_fmac_f32_e32 v167, v154, v154
	v_fmac_f32_e32 v168, v156, v156
	v_add_f32_e32 v167, v167, v168
	v_add_f32_e32 v166, v166, v167
	v_mul_f32_e32 v167, v159, v159
	v_mul_f32_e32 v168, v161, v161
	v_fmac_f32_e32 v167, v158, v158
	v_fmac_f32_e32 v168, v160, v160
	v_add_f32_e32 v167, v167, v168
	v_add_f32_e32 v166, v167, v166
	v_mul_f32_e32 v167, v163, v163
	v_mul_f32_e32 v168, v165, v165
	v_fmac_f32_e32 v167, v162, v162
	v_fmac_f32_e32 v168, v164, v164
	v_add_f32_e32 v167, v167, v168
	v_add_f32_e32 v166, v167, v166
	v_mov_b32_e32 v167, v166
	s_nop 1
	v_permlane16_swap_b32_e32 v167, v166
	v_readlane_b32 s80, v255, 4
	v_readlane_b32 s81, v255, 5
	s_andn2_b64 vcc, exec, s[80:81]
	s_mov_b64 s[80:81], -1
	s_waitcnt lgkmcnt(0)
	v_add_f32_e32 v166, v166, v167
	v_mov_b32_e32 v167, v166
	s_nop 1
	v_permlane32_swap_b32_e32 v167, v166
	s_cbranch_vccnz .LBB0_163
	v_ashrrev_i32_e32 v211, 31, v210
	v_lshlrev_b64 v[168:169], 7, v[210:211]
	v_lshl_add_u64 v[212:213], v[176:177], 0, v[168:169]
	s_mov_b64 s[80:81], 0

.LBB0_172:
	v_or_b32_e32 v210, 48, v204
	global_load_dwordx4 v[150:153], v[208:209], off offset:2048
	s_waitcnt vmcnt(1)
	v_mov_b32_e32 v154, v147
	v_mov_b32_e32 v155, v148
	v_mov_b32_e32 v147, v149
	v_pk_add_f32 v[146:147], v[154:155], v[146:147]
	s_and_b64 vcc, exec, s[14:15]
	v_add_f32_e32 v146, v146, v147
	v_fmamk_f32 v146, v146, 0x3a800000, v231
	v_rsq_f32_e32 v162, v146
	s_nop 0
	v_pk_fma_f32 v[148:149], v[112:113], v[162:163], v[144:145] op_sel_hi:[1,0,1]
	v_pk_fma_f32 v[146:147], v[110:111], v[162:163], v[142:143] op_sel_hi:[1,0,1]
	v_pk_fma_f32 v[156:157], v[108:109], v[162:163], v[140:141] op_sel_hi:[1,0,1]
	v_pk_fma_f32 v[154:155], v[106:107], v[162:163], v[138:139] op_sel_hi:[1,0,1]
	v_pk_fma_f32 v[160:161], v[104:105], v[162:163], v[136:137] op_sel_hi:[1,0,1]
	v_pk_fma_f32 v[158:159], v[102:103], v[162:163], v[134:135] op_sel_hi:[1,0,1]
	v_pk_fma_f32 v[164:165], v[100:101], v[162:163], v[132:133] op_sel_hi:[1,0,1]
	v_pk_fma_f32 v[162:163], v[98:99], v[162:163], v[130:131] op_sel_hi:[1,0,1]
	s_cbranch_vccnz .LBB0_328
	s_and_b64 vcc, exec, s[12:13]
	s_mov_b64 s[80:81], -1
	s_cbranch_vccnz .LBB0_191
	v_readlane_b32 s80, v254, 60
	v_readlane_b32 s81, v254, 61
	s_andn2_b64 vcc, exec, s[80:81]
	s_mov_b64 s[80:81], -1
	s_cbranch_vccnz .LBB0_180
	v_readlane_b32 s88, v254, 62
	v_readlane_b32 s89, v254, 63
	s_andn2_b64 vcc, exec, s[88:89]
	v_mul_f32_e32 v222, 0x3d372713, v146
	v_mul_f32_e32 v220, 0x3d372713, v147
	v_mul_f32_e32 v218, 0x3d372713, v148
	v_mul_f32_e32 v216, 0x3d372713, v149
	v_mul_f32_e32 v221, 0x3d372713, v154
	v_mul_f32_e32 v219, 0x3d372713, v155
	v_mul_f32_e32 v217, 0x3d372713, v156
	v_mul_f32_e32 v215, 0x3d372713, v157
	v_mul_f32_e32 v214, 0x3d372713, v158
	v_mul_f32_e32 v212, 0x3d372713, v159
	v_mul_f32_e32 v199, 0x3d372713, v160
	v_mul_f32_e32 v173, 0x3d372713, v161
	v_mul_f32_e32 v213, 0x3d372713, v162
	v_mul_f32_e32 v205, 0x3d372713, v163
	v_mul_f32_e32 v191, 0x3d372713, v164
	v_mul_f32_e32 v172, 0x3d372713, v165
	s_cbranch_vccnz .LBB0_177
	v_mul_f32_e32 v167, v148, v218
	v_fma_f32 v167, v148, v167, v148
	v_mul_f32_e32 v167, 0x3f4c422a, v167
	v_add_f32_e32 v167, v167, v167
	v_mul_f32_e32 v167, 0xbfb8aa3b, v167
	v_exp_f32_e32 v167, v167
	v_mul_f32_e32 v166, v146, v222
	v_fma_f32 v166, v146, v166, v146
	v_mul_f32_e32 v166, 0x3f4c422a, v166
	v_add_f32_e32 v167, 1.0, v167
	v_rcp_f32_e32 v167, v167
	v_add_f32_e32 v166, v166, v166
	v_mul_f32_e32 v166, 0xbfb8aa3b, v166
	v_exp_f32_e32 v166, v166
	v_mul_f32_e32 v224, v148, v167
	v_mul_f32_e32 v167, v149, v216
	v_fma_f32 v167, v149, v167, v149
	v_mul_f32_e32 v167, 0x3f4c422a, v167
	v_add_f32_e32 v167, v167, v167
	v_mul_f32_e32 v167, 0xbfb8aa3b, v167
	v_exp_f32_e32 v167, v167
	v_add_f32_e32 v166, 1.0, v166
	v_rcp_f32_e32 v166, v166
	v_readlane_b32 s80, v255, 0
	v_add_f32_e32 v167, 1.0, v167
	v_rcp_f32_e32 v167, v167
	v_mul_f32_e32 v211, v146, v166
	v_mul_f32_e32 v166, v147, v220
	v_fma_f32 v166, v147, v166, v147
	v_mul_f32_e32 v225, v149, v167
	v_mul_f32_e32 v167, v154, v221
	v_fma_f32 v167, v154, v167, v154
	v_mul_f32_e32 v167, 0x3f4c422a, v167
	v_add_f32_e32 v167, v167, v167
	v_mul_f32_e32 v167, 0xbfb8aa3b, v167
	v_exp_f32_e32 v167, v167
	v_mul_f32_e32 v166, 0x3f4c422a, v166
	v_add_f32_e32 v166, v166, v166
	v_mul_f32_e32 v166, 0xbfb8aa3b, v166
	v_add_f32_e32 v167, 1.0, v167
	v_rcp_f32_e32 v167, v167
	v_exp_f32_e32 v166, v166
	v_readlane_b32 s81, v255, 1
	v_lshlrev_b32_e32 v168, 6, v210
	v_mul_f32_e32 v226, v154, v167
	v_mul_f32_e32 v167, v155, v219
	v_fma_f32 v167, v155, v167, v155
	v_mul_f32_e32 v167, 0x3f4c422a, v167
	v_add_f32_e32 v167, v167, v167
	v_mul_f32_e32 v167, 0xbfb8aa3b, v167
	v_exp_f32_e32 v167, v167
	v_add_f32_e32 v166, 1.0, v166
	v_rcp_f32_e32 v166, v166
	v_and_b32_e32 v168, 0x1c00, v168
	v_add_f32_e32 v167, 1.0, v167
	v_rcp_f32_e32 v167, v167
	v_mul_f32_e32 v223, v147, v166
	v_mul_f32_e32 v166, v223, v223
	v_fmac_f32_e32 v166, v211, v211
	v_mul_f32_e32 v227, v155, v167
	v_mul_f32_e32 v167, v156, v217
	v_fma_f32 v167, v156, v167, v156
	v_mul_f32_e32 v167, 0x3f4c422a, v167
	v_add_f32_e32 v167, v167, v167
	v_mul_f32_e32 v167, 0xbfb8aa3b, v167
	v_exp_f32_e32 v167, v167
	v_fmac_f32_e32 v166, v224, v224
	v_fmac_f32_e32 v166, v225, v225
	v_fmac_f32_e32 v166, v226, v226
	v_add_f32_e32 v167, 1.0, v167
	v_rcp_f32_e32 v167, v167
	v_fmac_f32_e32 v166, v227, v227
	v_mov_b32_e32 v169, v1
	v_readlane_b32 s17, v254, 15
	v_mul_f32_e32 v228, v156, v167
	v_mul_f32_e32 v167, v157, v215
	v_fma_f32 v167, v157, v167, v157
	v_mul_f32_e32 v167, 0x3f4c422a, v167
	v_add_f32_e32 v167, v167, v167
	v_mul_f32_e32 v167, 0xbfb8aa3b, v167
	v_exp_f32_e32 v167, v167
	v_fmac_f32_e32 v166, v228, v228
	v_add_f32_e32 v167, 1.0, v167
	v_rcp_f32_e32 v167, v167
	s_nop 0
	v_mul_f32_e32 v229, v157, v167
	v_mul_f32_e32 v167, v158, v214
	v_fma_f32 v167, v158, v167, v158
	v_mul_f32_e32 v167, 0x3f4c422a, v167
	v_add_f32_e32 v167, v167, v167
	v_mul_f32_e32 v167, 0xbfb8aa3b, v167
	v_exp_f32_e32 v167, v167
	v_fmac_f32_e32 v166, v229, v229
	v_add_f32_e32 v167, 1.0, v167
	v_rcp_f32_e32 v167, v167
	s_nop 0
	v_mul_f32_e32 v248, v158, v167
	v_mul_f32_e32 v167, v159, v212
	v_fma_f32 v167, v159, v167, v159
	v_mul_f32_e32 v167, 0x3f4c422a, v167
	v_add_f32_e32 v167, v167, v167
	v_mul_f32_e32 v167, 0xbfb8aa3b, v167
	v_exp_f32_e32 v167, v167
	v_fmac_f32_e32 v166, v248, v248
	v_add_f32_e32 v167, 1.0, v167
	v_rcp_f32_e32 v167, v167
	s_nop 0
	v_mul_f32_e32 v230, v159, v167
	v_mul_f32_e32 v167, v160, v199
	v_fma_f32 v167, v160, v167, v160
	v_mul_f32_e32 v167, 0x3f4c422a, v167
	v_add_f32_e32 v167, v167, v167
	v_mul_f32_e32 v167, 0xbfb8aa3b, v167
	v_exp_f32_e32 v167, v167
	v_fmac_f32_e32 v166, v230, v230
	v_add_f32_e32 v167, 1.0, v167
	v_rcp_f32_e32 v167, v167
	s_nop 0
	v_mul_f32_e32 v187, v160, v167
	v_mul_f32_e32 v167, v161, v173
	v_fma_f32 v167, v161, v167, v161
	v_mul_f32_e32 v167, 0x3f4c422a, v167
	v_add_f32_e32 v167, v167, v167
	v_mul_f32_e32 v167, 0xbfb8aa3b, v167
	v_exp_f32_e32 v167, v167
	v_fmac_f32_e32 v166, v187, v187
	v_add_f32_e32 v167, 1.0, v167
	v_rcp_f32_e32 v167, v167
	s_nop 0
	v_mul_f32_e32 v235, v161, v167
	v_mul_f32_e32 v167, v162, v213
	v_fma_f32 v167, v162, v167, v162
	v_mul_f32_e32 v167, 0x3f4c422a, v167
	v_add_f32_e32 v167, v167, v167
	v_mul_f32_e32 v167, 0xbfb8aa3b, v167
	v_exp_f32_e32 v167, v167
	v_fmac_f32_e32 v166, v235, v235
	v_add_f32_e32 v167, 1.0, v167
	v_rcp_f32_e32 v167, v167
	s_nop 0
	v_mul_f32_e32 v233, v162, v167
	v_mul_f32_e32 v167, v163, v205
	v_fma_f32 v167, v163, v167, v163
	v_mul_f32_e32 v167, 0x3f4c422a, v167
	v_add_f32_e32 v167, v167, v167
	v_mul_f32_e32 v167, 0xbfb8aa3b, v167
	v_exp_f32_e32 v167, v167
	v_fmac_f32_e32 v166, v233, v233
	v_add_f32_e32 v167, 1.0, v167
	v_rcp_f32_e32 v167, v167
	s_nop 0
	v_mul_f32_e32 v232, v163, v167
	v_mul_f32_e32 v167, v164, v191
	v_fma_f32 v167, v164, v167, v164
	v_mul_f32_e32 v167, 0x3f4c422a, v167
	v_add_f32_e32 v167, v167, v167
	v_mul_f32_e32 v167, 0xbfb8aa3b, v167
	v_exp_f32_e32 v167, v167
	v_fmac_f32_e32 v166, v232, v232
	v_add_f32_e32 v167, 1.0, v167
	v_rcp_f32_e32 v167, v167
	s_nop 0
	v_mul_f32_e32 v250, v164, v167
	v_mul_f32_e32 v167, v165, v172
	v_fma_f32 v167, v165, v167, v165
	v_mul_f32_e32 v167, 0x3f4c422a, v167
	v_add_f32_e32 v167, v167, v167
	v_mul_f32_e32 v167, 0xbfb8aa3b, v167
	v_exp_f32_e32 v167, v167
	v_fmac_f32_e32 v166, v250, v250
	v_add_f32_e32 v167, 1.0, v167
	v_rcp_f32_e32 v167, v167
	s_nop 0
	v_mul_f32_e32 v249, v165, v167
	v_fmac_f32_e32 v166, v249, v249
	v_mov_b32_e32 v167, v166
	s_nop 1
	v_permlane16_swap_b32_e32 v167, v166
	s_waitcnt lgkmcnt(0)
	v_add_f32_e32 v166, v166, v167
	v_mov_b32_e32 v167, v166
	s_nop 1
	v_permlane32_swap_b32_e32 v167, v166
	s_waitcnt lgkmcnt(0)
	v_add_f32_e32 v166, v166, v167
	v_fmamk_f32 v166, v166, 0x3c800000, v231
	v_rsq_f32_e32 v251, v166
	v_ashrrev_i32_e32 v166, 7, v210
	v_ashrrev_i32_e32 v167, 31, v166
	v_lshlrev_b64 v[166:167], 16, v[166:167]
	v_lshl_add_u64 v[166:167], s[80:81], 0, v[166:167]
	v_lshl_add_u64 v[166:167], v[166:167], 0, v[168:169]
	v_and_b32_e32 v168, 8, v210
	v_lshlrev_b32_e32 v168, 1, v168
	v_lshl_add_u64 v[166:167], v[166:167], 0, v[168:169]
	v_and_b32_e32 v168, 7, v210
	v_lshlrev_b32_e32 v168, 1, v168
	v_lshl_add_u64 v[166:167], v[166:167], 0, v[168:169]
	s_lshl_b32 s80, s17, 1
	s_mov_b32 s81, s71
	v_lshl_add_u64 v[166:167], v[166:167], 0, s[80:81]
	v_lshlrev_b32_e32 v168, 1, v186
	v_lshl_add_u64 v[170:171], v[166:167], 0, v[168:169]
	global_load_dwordx4 v[166:169], v[202:203], off
	v_mul_f32_e32 v211, v211, v251
	s_movk_i32 s17, 0x2000
	s_mov_b64 s[80:81], 0
	s_waitcnt vmcnt(0)
	v_mul_f32_e32 v166, v166, v211
	v_cvt_pk_bf16_f32 v166, v166, s0
	global_store_short v[170:171], v166, off
	v_mul_f32_e32 v166, v223, v251
	v_mul_f32_e32 v166, v167, v166
	v_cvt_pk_bf16_f32 v166, v166, s0
	global_store_short v[170:171], v166, off offset:32
	v_mul_f32_e32 v166, v224, v251
	v_mul_f32_e32 v166, v168, v166
	v_cvt_pk_bf16_f32 v166, v166, s0
	global_store_short v[170:171], v166, off offset:64
	v_mul_f32_e32 v166, v225, v251
	v_mul_f32_e32 v166, v169, v166
	v_cvt_pk_bf16_f32 v166, v166, s0
	global_store_short v[170:171], v166, off offset:96
	global_load_dwordx4 v[166:169], v[202:203], off offset:16
	v_mul_f32_e32 v211, v226, v251
	s_waitcnt vmcnt(0)
	v_mul_f32_e32 v166, v211, v166
	v_cvt_pk_bf16_f32 v166, v166, s0
	global_store_short v[170:171], v166, off offset:128
	v_mul_f32_e32 v166, v227, v251
	v_mul_f32_e32 v166, v166, v167
	v_cvt_pk_bf16_f32 v166, v166, s0
	global_store_short v[170:171], v166, off offset:160
	v_mul_f32_e32 v166, v228, v251
	v_mul_f32_e32 v166, v166, v168
	v_cvt_pk_bf16_f32 v166, v166, s0
	global_store_short v[170:171], v166, off offset:192
	v_mul_f32_e32 v166, v229, v251
	v_mul_f32_e32 v166, v166, v169
	v_cvt_pk_bf16_f32 v166, v166, s0
	global_store_short v[170:171], v166, off offset:224
	global_load_dwordx4 v[166:169], v[202:203], off offset:128
	v_mul_f32_e32 v211, v248, v251
	v_add_co_u32_e32 v170, vcc, s17, v170
	s_waitcnt vmcnt(0)
	v_mul_f32_e32 v166, v211, v166
	v_cvt_pk_bf16_f32 v166, v166, s0
	v_addc_co_u32_e32 v171, vcc, 0, v171, vcc
	global_store_short v[170:171], v166, off
	v_mul_f32_e32 v166, v230, v251
	v_mul_f32_e32 v166, v166, v167
	v_cvt_pk_bf16_f32 v166, v166, s0
	global_store_short v[170:171], v166, off offset:32
	v_mul_f32_e32 v166, v187, v251
	v_mul_f32_e32 v166, v166, v168
	v_cvt_pk_bf16_f32 v166, v166, s0
	global_store_short v[170:171], v166, off offset:64
	v_mul_f32_e32 v166, v235, v251
	v_mul_f32_e32 v166, v166, v169
	v_cvt_pk_bf16_f32 v166, v166, s0
	global_store_short v[170:171], v166, off offset:96
	global_load_dwordx4 v[166:169], v[202:203], off offset:144
	v_mul_f32_e32 v187, v233, v251
	s_waitcnt vmcnt(0)
	v_mul_f32_e32 v166, v187, v166
	v_cvt_pk_bf16_f32 v166, v166, s0
	global_store_short v[170:171], v166, off offset:128
	v_mul_f32_e32 v166, v232, v251
	v_mul_f32_e32 v166, v166, v167
	v_cvt_pk_bf16_f32 v166, v166, s0
	global_store_short v[170:171], v166, off offset:160
	v_mul_f32_e32 v166, v250, v251
	v_mul_f32_e32 v166, v166, v168
	v_cvt_pk_bf16_f32 v166, v166, s0
	global_store_short v[170:171], v166, off offset:192
	v_mul_f32_e32 v166, v249, v251
	v_mul_f32_e32 v166, v166, v169
	v_cvt_pk_bf16_f32 v166, v166, s0
	global_store_short v[170:171], v166, off offset:224

.LBB0_203:
	v_add_u32_e32 v210, 0x80, v204
	global_load_dwordx4 v[146:149], v[208:209], off offset:2304
	s_waitcnt vmcnt(1)
	v_mov_b32_e32 v154, v151
	v_mov_b32_e32 v155, v152
	v_mov_b32_e32 v151, v153
	v_pk_add_f32 v[150:151], v[154:155], v[150:151]
	s_and_b64 vcc, exec, s[14:15]
	v_add_f32_e32 v150, v150, v151
	v_fmamk_f32 v150, v150, 0x3a800000, v231
	v_rsq_f32_e32 v162, v150
	s_nop 0
	v_pk_fma_f32 v[152:153], v[96:97], v[162:163], v[144:145] op_sel_hi:[1,0,1]
	v_pk_fma_f32 v[150:151], v[94:95], v[162:163], v[142:143] op_sel_hi:[1,0,1]
	v_pk_fma_f32 v[156:157], v[92:93], v[162:163], v[140:141] op_sel_hi:[1,0,1]
	v_pk_fma_f32 v[154:155], v[90:91], v[162:163], v[138:139] op_sel_hi:[1,0,1]
	v_pk_fma_f32 v[160:161], v[88:89], v[162:163], v[136:137] op_sel_hi:[1,0,1]
	v_pk_fma_f32 v[158:159], v[86:87], v[162:163], v[134:135] op_sel_hi:[1,0,1]
	v_pk_fma_f32 v[164:165], v[84:85], v[162:163], v[132:133] op_sel_hi:[1,0,1]
	v_pk_fma_f32 v[162:163], v[82:83], v[162:163], v[130:131] op_sel_hi:[1,0,1]
	s_cbranch_vccnz .LBB0_329
	s_and_b64 vcc, exec, s[12:13]
	s_mov_b64 s[80:81], -1
	s_cbranch_vccnz .LBB0_222
	v_readlane_b32 s80, v254, 60
	v_readlane_b32 s81, v254, 61
	s_andn2_b64 vcc, exec, s[80:81]
	s_mov_b64 s[80:81], -1
	s_cbranch_vccnz .LBB0_211
	v_readlane_b32 s88, v254, 62
	v_readlane_b32 s89, v254, 63
	s_andn2_b64 vcc, exec, s[88:89]
	v_mul_f32_e32 v222, 0x3d372713, v150
	v_mul_f32_e32 v220, 0x3d372713, v151
	v_mul_f32_e32 v218, 0x3d372713, v152
	v_mul_f32_e32 v216, 0x3d372713, v153
	v_mul_f32_e32 v221, 0x3d372713, v154
	v_mul_f32_e32 v219, 0x3d372713, v155
	v_mul_f32_e32 v217, 0x3d372713, v156
	v_mul_f32_e32 v215, 0x3d372713, v157
	v_mul_f32_e32 v214, 0x3d372713, v158
	v_mul_f32_e32 v212, 0x3d372713, v159
	v_mul_f32_e32 v199, 0x3d372713, v160
	v_mul_f32_e32 v173, 0x3d372713, v161
	v_mul_f32_e32 v213, 0x3d372713, v162
	v_mul_f32_e32 v205, 0x3d372713, v163
	v_mul_f32_e32 v191, 0x3d372713, v164
	v_mul_f32_e32 v172, 0x3d372713, v165
	s_cbranch_vccnz .LBB0_208
	v_mul_f32_e32 v167, v152, v218
	v_fma_f32 v167, v152, v167, v152
	v_mul_f32_e32 v167, 0x3f4c422a, v167
	v_add_f32_e32 v167, v167, v167
	v_mul_f32_e32 v167, 0xbfb8aa3b, v167
	v_exp_f32_e32 v167, v167
	v_mul_f32_e32 v166, v150, v222
	v_fma_f32 v166, v150, v166, v150
	v_mul_f32_e32 v166, 0x3f4c422a, v166
	v_add_f32_e32 v167, 1.0, v167
	v_rcp_f32_e32 v167, v167
	v_add_f32_e32 v166, v166, v166
	v_mul_f32_e32 v166, 0xbfb8aa3b, v166
	v_exp_f32_e32 v166, v166
	v_mul_f32_e32 v224, v152, v167
	v_mul_f32_e32 v167, v153, v216
	v_fma_f32 v167, v153, v167, v153
	v_mul_f32_e32 v167, 0x3f4c422a, v167
	v_add_f32_e32 v167, v167, v167
	v_mul_f32_e32 v167, 0xbfb8aa3b, v167
	v_exp_f32_e32 v167, v167
	v_add_f32_e32 v166, 1.0, v166
	v_rcp_f32_e32 v166, v166
	v_readlane_b32 s80, v255, 0
	v_add_f32_e32 v167, 1.0, v167
	v_rcp_f32_e32 v167, v167
	v_mul_f32_e32 v211, v150, v166
	v_mul_f32_e32 v166, v151, v220
	v_fma_f32 v166, v151, v166, v151
	v_mul_f32_e32 v225, v153, v167
	v_mul_f32_e32 v167, v154, v221
	v_fma_f32 v167, v154, v167, v154
	v_mul_f32_e32 v167, 0x3f4c422a, v167
	v_add_f32_e32 v167, v167, v167
	v_mul_f32_e32 v167, 0xbfb8aa3b, v167
	v_exp_f32_e32 v167, v167
	v_mul_f32_e32 v166, 0x3f4c422a, v166
	v_add_f32_e32 v166, v166, v166
	v_mul_f32_e32 v166, 0xbfb8aa3b, v166
	v_add_f32_e32 v167, 1.0, v167
	v_rcp_f32_e32 v167, v167
	v_exp_f32_e32 v166, v166
	v_readlane_b32 s81, v255, 1
	v_lshlrev_b32_e32 v168, 6, v210
	v_mul_f32_e32 v226, v154, v167
	v_mul_f32_e32 v167, v155, v219
	v_fma_f32 v167, v155, v167, v155
	v_mul_f32_e32 v167, 0x3f4c422a, v167
	v_add_f32_e32 v167, v167, v167
	v_mul_f32_e32 v167, 0xbfb8aa3b, v167
	v_exp_f32_e32 v167, v167
	v_add_f32_e32 v166, 1.0, v166
	v_rcp_f32_e32 v166, v166
	v_and_b32_e32 v168, 0x1c00, v168
	v_add_f32_e32 v167, 1.0, v167
	v_rcp_f32_e32 v167, v167
	v_mul_f32_e32 v223, v151, v166
	v_mul_f32_e32 v166, v223, v223
	v_fmac_f32_e32 v166, v211, v211
	v_mul_f32_e32 v227, v155, v167
	v_mul_f32_e32 v167, v156, v217
	v_fma_f32 v167, v156, v167, v156
	v_mul_f32_e32 v167, 0x3f4c422a, v167
	v_add_f32_e32 v167, v167, v167
	v_mul_f32_e32 v167, 0xbfb8aa3b, v167
	v_exp_f32_e32 v167, v167
	v_fmac_f32_e32 v166, v224, v224
	v_fmac_f32_e32 v166, v225, v225
	v_fmac_f32_e32 v166, v226, v226
	v_add_f32_e32 v167, 1.0, v167
	v_rcp_f32_e32 v167, v167
	v_fmac_f32_e32 v166, v227, v227
	v_mov_b32_e32 v169, v1
	v_readlane_b32 s17, v254, 15
	v_mul_f32_e32 v228, v156, v167
	v_mul_f32_e32 v167, v157, v215
	v_fma_f32 v167, v157, v167, v157
	v_mul_f32_e32 v167, 0x3f4c422a, v167
	v_add_f32_e32 v167, v167, v167
	v_mul_f32_e32 v167, 0xbfb8aa3b, v167
	v_exp_f32_e32 v167, v167
	v_fmac_f32_e32 v166, v228, v228
	v_add_f32_e32 v167, 1.0, v167
	v_rcp_f32_e32 v167, v167
	s_nop 0
	v_mul_f32_e32 v229, v157, v167
	v_mul_f32_e32 v167, v158, v214
	v_fma_f32 v167, v158, v167, v158
	v_mul_f32_e32 v167, 0x3f4c422a, v167
	v_add_f32_e32 v167, v167, v167
	v_mul_f32_e32 v167, 0xbfb8aa3b, v167
	v_exp_f32_e32 v167, v167
	v_fmac_f32_e32 v166, v229, v229
	v_add_f32_e32 v167, 1.0, v167
	v_rcp_f32_e32 v167, v167
	s_nop 0
	v_mul_f32_e32 v248, v158, v167
	v_mul_f32_e32 v167, v159, v212
	v_fma_f32 v167, v159, v167, v159
	v_mul_f32_e32 v167, 0x3f4c422a, v167
	v_add_f32_e32 v167, v167, v167
	v_mul_f32_e32 v167, 0xbfb8aa3b, v167
	v_exp_f32_e32 v167, v167
	v_fmac_f32_e32 v166, v248, v248
	v_add_f32_e32 v167, 1.0, v167
	v_rcp_f32_e32 v167, v167
	s_nop 0
	v_mul_f32_e32 v230, v159, v167
	v_mul_f32_e32 v167, v160, v199
	v_fma_f32 v167, v160, v167, v160
	v_mul_f32_e32 v167, 0x3f4c422a, v167
	v_add_f32_e32 v167, v167, v167
	v_mul_f32_e32 v167, 0xbfb8aa3b, v167
	v_exp_f32_e32 v167, v167
	v_fmac_f32_e32 v166, v230, v230
	v_add_f32_e32 v167, 1.0, v167
	v_rcp_f32_e32 v167, v167
	s_nop 0
	v_mul_f32_e32 v187, v160, v167
	v_mul_f32_e32 v167, v161, v173
	v_fma_f32 v167, v161, v167, v161
	v_mul_f32_e32 v167, 0x3f4c422a, v167
	v_add_f32_e32 v167, v167, v167
	v_mul_f32_e32 v167, 0xbfb8aa3b, v167
	v_exp_f32_e32 v167, v167
	v_fmac_f32_e32 v166, v187, v187
	v_add_f32_e32 v167, 1.0, v167
	v_rcp_f32_e32 v167, v167
	s_nop 0
	v_mul_f32_e32 v235, v161, v167
	v_mul_f32_e32 v167, v162, v213
	v_fma_f32 v167, v162, v167, v162
	v_mul_f32_e32 v167, 0x3f4c422a, v167
	v_add_f32_e32 v167, v167, v167
	v_mul_f32_e32 v167, 0xbfb8aa3b, v167
	v_exp_f32_e32 v167, v167
	v_fmac_f32_e32 v166, v235, v235
	v_add_f32_e32 v167, 1.0, v167
	v_rcp_f32_e32 v167, v167
	s_nop 0
	v_mul_f32_e32 v233, v162, v167
	v_mul_f32_e32 v167, v163, v205
	v_fma_f32 v167, v163, v167, v163
	v_mul_f32_e32 v167, 0x3f4c422a, v167
	v_add_f32_e32 v167, v167, v167
	v_mul_f32_e32 v167, 0xbfb8aa3b, v167
	v_exp_f32_e32 v167, v167
	v_fmac_f32_e32 v166, v233, v233
	v_add_f32_e32 v167, 1.0, v167
	v_rcp_f32_e32 v167, v167
	s_nop 0
	v_mul_f32_e32 v232, v163, v167
	v_mul_f32_e32 v167, v164, v191
	v_fma_f32 v167, v164, v167, v164
	v_mul_f32_e32 v167, 0x3f4c422a, v167
	v_add_f32_e32 v167, v167, v167
	v_mul_f32_e32 v167, 0xbfb8aa3b, v167
	v_exp_f32_e32 v167, v167
	v_fmac_f32_e32 v166, v232, v232
	v_add_f32_e32 v167, 1.0, v167
	v_rcp_f32_e32 v167, v167
	s_nop 0
	v_mul_f32_e32 v250, v164, v167
	v_mul_f32_e32 v167, v165, v172
	v_fma_f32 v167, v165, v167, v165
	v_mul_f32_e32 v167, 0x3f4c422a, v167
	v_add_f32_e32 v167, v167, v167
	v_mul_f32_e32 v167, 0xbfb8aa3b, v167
	v_exp_f32_e32 v167, v167
	v_fmac_f32_e32 v166, v250, v250
	v_add_f32_e32 v167, 1.0, v167
	v_rcp_f32_e32 v167, v167
	s_nop 0
	v_mul_f32_e32 v249, v165, v167
	v_fmac_f32_e32 v166, v249, v249
	v_mov_b32_e32 v167, v166
	s_nop 1
	v_permlane16_swap_b32_e32 v167, v166
	s_waitcnt lgkmcnt(0)
	v_add_f32_e32 v166, v166, v167
	v_mov_b32_e32 v167, v166
	s_nop 1
	v_permlane32_swap_b32_e32 v167, v166
	s_waitcnt lgkmcnt(0)
	v_add_f32_e32 v166, v166, v167
	v_fmamk_f32 v166, v166, 0x3c800000, v231
	v_rsq_f32_e32 v251, v166
	v_ashrrev_i32_e32 v166, 7, v210
	v_ashrrev_i32_e32 v167, 31, v166
	v_lshlrev_b64 v[166:167], 16, v[166:167]
	v_lshl_add_u64 v[166:167], s[80:81], 0, v[166:167]
	v_lshl_add_u64 v[166:167], v[166:167], 0, v[168:169]
	v_and_b32_e32 v168, 8, v210
	v_lshlrev_b32_e32 v168, 1, v168
	v_lshl_add_u64 v[166:167], v[166:167], 0, v[168:169]
	v_and_b32_e32 v168, 7, v210
	v_lshlrev_b32_e32 v168, 1, v168
	v_lshl_add_u64 v[166:167], v[166:167], 0, v[168:169]
	s_lshl_b32 s80, s17, 1
	s_mov_b32 s81, s71
	v_lshl_add_u64 v[166:167], v[166:167], 0, s[80:81]
	v_lshlrev_b32_e32 v168, 1, v186
	v_lshl_add_u64 v[170:171], v[166:167], 0, v[168:169]
	global_load_dwordx4 v[166:169], v[202:203], off
	v_mul_f32_e32 v211, v211, v251
	s_movk_i32 s17, 0x2000
	s_mov_b64 s[80:81], 0
	s_waitcnt vmcnt(0)
	v_mul_f32_e32 v166, v166, v211
	v_cvt_pk_bf16_f32 v166, v166, s0
	global_store_short v[170:171], v166, off
	v_mul_f32_e32 v166, v223, v251
	v_mul_f32_e32 v166, v167, v166
	v_cvt_pk_bf16_f32 v166, v166, s0
	global_store_short v[170:171], v166, off offset:32
	v_mul_f32_e32 v166, v224, v251
	v_mul_f32_e32 v166, v168, v166
	v_cvt_pk_bf16_f32 v166, v166, s0
	global_store_short v[170:171], v166, off offset:64
	v_mul_f32_e32 v166, v225, v251
	v_mul_f32_e32 v166, v169, v166
	v_cvt_pk_bf16_f32 v166, v166, s0
	global_store_short v[170:171], v166, off offset:96
	global_load_dwordx4 v[166:169], v[202:203], off offset:16
	v_mul_f32_e32 v211, v226, v251
	s_waitcnt vmcnt(0)
	v_mul_f32_e32 v166, v211, v166
	v_cvt_pk_bf16_f32 v166, v166, s0
	global_store_short v[170:171], v166, off offset:128
	v_mul_f32_e32 v166, v227, v251
	v_mul_f32_e32 v166, v166, v167
	v_cvt_pk_bf16_f32 v166, v166, s0
	global_store_short v[170:171], v166, off offset:160
	v_mul_f32_e32 v166, v228, v251
	v_mul_f32_e32 v166, v166, v168
	v_cvt_pk_bf16_f32 v166, v166, s0
	global_store_short v[170:171], v166, off offset:192
	v_mul_f32_e32 v166, v229, v251
	v_mul_f32_e32 v166, v166, v169
	v_cvt_pk_bf16_f32 v166, v166, s0
	global_store_short v[170:171], v166, off offset:224
	global_load_dwordx4 v[166:169], v[202:203], off offset:128
	v_mul_f32_e32 v211, v248, v251
	v_add_co_u32_e32 v170, vcc, s17, v170
	s_waitcnt vmcnt(0)
	v_mul_f32_e32 v166, v211, v166
	v_cvt_pk_bf16_f32 v166, v166, s0
	v_addc_co_u32_e32 v171, vcc, 0, v171, vcc
	global_store_short v[170:171], v166, off
	v_mul_f32_e32 v166, v230, v251
	v_mul_f32_e32 v166, v166, v167
	v_cvt_pk_bf16_f32 v166, v166, s0
	global_store_short v[170:171], v166, off offset:32
	v_mul_f32_e32 v166, v187, v251
	v_mul_f32_e32 v166, v166, v168
	v_cvt_pk_bf16_f32 v166, v166, s0
	global_store_short v[170:171], v166, off offset:64
	v_mul_f32_e32 v166, v235, v251
	v_mul_f32_e32 v166, v166, v169
	v_cvt_pk_bf16_f32 v166, v166, s0
	global_store_short v[170:171], v166, off offset:96
	global_load_dwordx4 v[166:169], v[202:203], off offset:144
	v_mul_f32_e32 v187, v233, v251
	s_waitcnt vmcnt(0)
	v_mul_f32_e32 v166, v187, v166
	v_cvt_pk_bf16_f32 v166, v166, s0
	global_store_short v[170:171], v166, off offset:128
	v_mul_f32_e32 v166, v232, v251
	v_mul_f32_e32 v166, v166, v167
	v_cvt_pk_bf16_f32 v166, v166, s0
	global_store_short v[170:171], v166, off offset:160
	v_mul_f32_e32 v166, v250, v251
	v_mul_f32_e32 v166, v166, v168
	v_cvt_pk_bf16_f32 v166, v166, s0
	global_store_short v[170:171], v166, off offset:192
	v_mul_f32_e32 v166, v249, v251
	v_mul_f32_e32 v166, v166, v169
	v_cvt_pk_bf16_f32 v166, v166, s0
	global_store_short v[170:171], v166, off offset:224

.LBB0_234:
	v_add_u32_e32 v210, 0x90, v204
	global_load_dwordx4 v[150:153], v[208:209], off offset:2560
	s_waitcnt vmcnt(1)
	v_mov_b32_e32 v154, v147
	v_mov_b32_e32 v155, v148
	v_mov_b32_e32 v147, v149
	v_pk_add_f32 v[146:147], v[154:155], v[146:147]
	s_and_b64 vcc, exec, s[14:15]
	v_add_f32_e32 v146, v146, v147
	v_fmamk_f32 v146, v146, 0x3a800000, v231
	v_rsq_f32_e32 v162, v146
	s_nop 0
	v_pk_fma_f32 v[148:149], v[80:81], v[162:163], v[144:145] op_sel_hi:[1,0,1]
	v_pk_fma_f32 v[146:147], v[78:79], v[162:163], v[142:143] op_sel_hi:[1,0,1]
	v_pk_fma_f32 v[156:157], v[76:77], v[162:163], v[140:141] op_sel_hi:[1,0,1]
	v_pk_fma_f32 v[154:155], v[74:75], v[162:163], v[138:139] op_sel_hi:[1,0,1]
	v_pk_fma_f32 v[160:161], v[72:73], v[162:163], v[136:137] op_sel_hi:[1,0,1]
	v_pk_fma_f32 v[158:159], v[70:71], v[162:163], v[134:135] op_sel_hi:[1,0,1]
	v_pk_fma_f32 v[164:165], v[68:69], v[162:163], v[132:133] op_sel_hi:[1,0,1]
	v_pk_fma_f32 v[162:163], v[66:67], v[162:163], v[130:131] op_sel_hi:[1,0,1]
	s_cbranch_vccnz .LBB0_330
	s_and_b64 vcc, exec, s[12:13]
	s_mov_b64 s[80:81], -1
	s_cbranch_vccnz .LBB0_253
	v_readlane_b32 s80, v254, 60
	v_readlane_b32 s81, v254, 61
	s_andn2_b64 vcc, exec, s[80:81]
	s_mov_b64 s[80:81], -1
	s_cbranch_vccnz .LBB0_242
	v_readlane_b32 s88, v254, 62
	v_readlane_b32 s89, v254, 63
	s_andn2_b64 vcc, exec, s[88:89]
	v_mul_f32_e32 v222, 0x3d372713, v146
	v_mul_f32_e32 v220, 0x3d372713, v147
	v_mul_f32_e32 v218, 0x3d372713, v148
	v_mul_f32_e32 v216, 0x3d372713, v149
	v_mul_f32_e32 v221, 0x3d372713, v154
	v_mul_f32_e32 v219, 0x3d372713, v155
	v_mul_f32_e32 v217, 0x3d372713, v156
	v_mul_f32_e32 v215, 0x3d372713, v157
	v_mul_f32_e32 v214, 0x3d372713, v158
	v_mul_f32_e32 v212, 0x3d372713, v159
	v_mul_f32_e32 v199, 0x3d372713, v160
	v_mul_f32_e32 v173, 0x3d372713, v161
	v_mul_f32_e32 v213, 0x3d372713, v162
	v_mul_f32_e32 v205, 0x3d372713, v163
	v_mul_f32_e32 v191, 0x3d372713, v164
	v_mul_f32_e32 v172, 0x3d372713, v165
	s_cbranch_vccnz .LBB0_239
	v_mul_f32_e32 v167, v148, v218
	v_fma_f32 v167, v148, v167, v148
	v_mul_f32_e32 v167, 0x3f4c422a, v167
	v_add_f32_e32 v167, v167, v167
	v_mul_f32_e32 v167, 0xbfb8aa3b, v167
	v_exp_f32_e32 v167, v167
	v_mul_f32_e32 v166, v146, v222
	v_fma_f32 v166, v146, v166, v146
	v_mul_f32_e32 v166, 0x3f4c422a, v166
	v_add_f32_e32 v167, 1.0, v167
	v_rcp_f32_e32 v167, v167
	v_add_f32_e32 v166, v166, v166
	v_mul_f32_e32 v166, 0xbfb8aa3b, v166
	v_exp_f32_e32 v166, v166
	v_mul_f32_e32 v224, v148, v167
	v_mul_f32_e32 v167, v149, v216
	v_fma_f32 v167, v149, v167, v149
	v_mul_f32_e32 v167, 0x3f4c422a, v167
	v_add_f32_e32 v167, v167, v167
	v_mul_f32_e32 v167, 0xbfb8aa3b, v167
	v_exp_f32_e32 v167, v167
	v_add_f32_e32 v166, 1.0, v166
	v_rcp_f32_e32 v166, v166
	v_readlane_b32 s80, v255, 0
	v_add_f32_e32 v167, 1.0, v167
	v_rcp_f32_e32 v167, v167
	v_mul_f32_e32 v211, v146, v166
	v_mul_f32_e32 v166, v147, v220
	v_fma_f32 v166, v147, v166, v147
	v_mul_f32_e32 v225, v149, v167
	v_mul_f32_e32 v167, v154, v221
	v_fma_f32 v167, v154, v167, v154
	v_mul_f32_e32 v167, 0x3f4c422a, v167
	v_add_f32_e32 v167, v167, v167
	v_mul_f32_e32 v167, 0xbfb8aa3b, v167
	v_exp_f32_e32 v167, v167
	v_mul_f32_e32 v166, 0x3f4c422a, v166
	v_add_f32_e32 v166, v166, v166
	v_mul_f32_e32 v166, 0xbfb8aa3b, v166
	v_add_f32_e32 v167, 1.0, v167
	v_rcp_f32_e32 v167, v167
	v_exp_f32_e32 v166, v166
	v_readlane_b32 s81, v255, 1
	v_lshlrev_b32_e32 v168, 6, v210
	v_mul_f32_e32 v226, v154, v167
	v_mul_f32_e32 v167, v155, v219
	v_fma_f32 v167, v155, v167, v155
	v_mul_f32_e32 v167, 0x3f4c422a, v167
	v_add_f32_e32 v167, v167, v167
	v_mul_f32_e32 v167, 0xbfb8aa3b, v167
	v_exp_f32_e32 v167, v167
	v_add_f32_e32 v166, 1.0, v166
	v_rcp_f32_e32 v166, v166
	v_and_b32_e32 v168, 0x1c00, v168
	v_add_f32_e32 v167, 1.0, v167
	v_rcp_f32_e32 v167, v167
	v_mul_f32_e32 v223, v147, v166
	v_mul_f32_e32 v166, v223, v223
	v_fmac_f32_e32 v166, v211, v211
	v_mul_f32_e32 v227, v155, v167
	v_mul_f32_e32 v167, v156, v217
	v_fma_f32 v167, v156, v167, v156
	v_mul_f32_e32 v167, 0x3f4c422a, v167
	v_add_f32_e32 v167, v167, v167
	v_mul_f32_e32 v167, 0xbfb8aa3b, v167
	v_exp_f32_e32 v167, v167
	v_fmac_f32_e32 v166, v224, v224
	v_fmac_f32_e32 v166, v225, v225
	v_fmac_f32_e32 v166, v226, v226
	v_add_f32_e32 v167, 1.0, v167
	v_rcp_f32_e32 v167, v167
	v_fmac_f32_e32 v166, v227, v227
	v_mov_b32_e32 v169, v1
	v_readlane_b32 s17, v254, 15
	v_mul_f32_e32 v228, v156, v167
	v_mul_f32_e32 v167, v157, v215
	v_fma_f32 v167, v157, v167, v157
	v_mul_f32_e32 v167, 0x3f4c422a, v167
	v_add_f32_e32 v167, v167, v167
	v_mul_f32_e32 v167, 0xbfb8aa3b, v167
	v_exp_f32_e32 v167, v167
	v_fmac_f32_e32 v166, v228, v228
	v_add_f32_e32 v167, 1.0, v167
	v_rcp_f32_e32 v167, v167
	s_nop 0
	v_mul_f32_e32 v229, v157, v167
	v_mul_f32_e32 v167, v158, v214
	v_fma_f32 v167, v158, v167, v158
	v_mul_f32_e32 v167, 0x3f4c422a, v167
	v_add_f32_e32 v167, v167, v167
	v_mul_f32_e32 v167, 0xbfb8aa3b, v167
	v_exp_f32_e32 v167, v167
	v_fmac_f32_e32 v166, v229, v229
	v_add_f32_e32 v167, 1.0, v167
	v_rcp_f32_e32 v167, v167
	s_nop 0
	v_mul_f32_e32 v248, v158, v167
	v_mul_f32_e32 v167, v159, v212
	v_fma_f32 v167, v159, v167, v159
	v_mul_f32_e32 v167, 0x3f4c422a, v167
	v_add_f32_e32 v167, v167, v167
	v_mul_f32_e32 v167, 0xbfb8aa3b, v167
	v_exp_f32_e32 v167, v167
	v_fmac_f32_e32 v166, v248, v248
	v_add_f32_e32 v167, 1.0, v167
	v_rcp_f32_e32 v167, v167
	s_nop 0
	v_mul_f32_e32 v230, v159, v167
	v_mul_f32_e32 v167, v160, v199
	v_fma_f32 v167, v160, v167, v160
	v_mul_f32_e32 v167, 0x3f4c422a, v167
	v_add_f32_e32 v167, v167, v167
	v_mul_f32_e32 v167, 0xbfb8aa3b, v167
	v_exp_f32_e32 v167, v167
	v_fmac_f32_e32 v166, v230, v230
	v_add_f32_e32 v167, 1.0, v167
	v_rcp_f32_e32 v167, v167
	s_nop 0
	v_mul_f32_e32 v187, v160, v167
	v_mul_f32_e32 v167, v161, v173
	v_fma_f32 v167, v161, v167, v161
	v_mul_f32_e32 v167, 0x3f4c422a, v167
	v_add_f32_e32 v167, v167, v167
	v_mul_f32_e32 v167, 0xbfb8aa3b, v167
	v_exp_f32_e32 v167, v167
	v_fmac_f32_e32 v166, v187, v187
	v_add_f32_e32 v167, 1.0, v167
	v_rcp_f32_e32 v167, v167
	s_nop 0
	v_mul_f32_e32 v235, v161, v167
	v_mul_f32_e32 v167, v162, v213
	v_fma_f32 v167, v162, v167, v162
	v_mul_f32_e32 v167, 0x3f4c422a, v167
	v_add_f32_e32 v167, v167, v167
	v_mul_f32_e32 v167, 0xbfb8aa3b, v167
	v_exp_f32_e32 v167, v167
	v_fmac_f32_e32 v166, v235, v235
	v_add_f32_e32 v167, 1.0, v167
	v_rcp_f32_e32 v167, v167
	s_nop 0
	v_mul_f32_e32 v233, v162, v167
	v_mul_f32_e32 v167, v163, v205
	v_fma_f32 v167, v163, v167, v163
	v_mul_f32_e32 v167, 0x3f4c422a, v167
	v_add_f32_e32 v167, v167, v167
	v_mul_f32_e32 v167, 0xbfb8aa3b, v167
	v_exp_f32_e32 v167, v167
	v_fmac_f32_e32 v166, v233, v233
	v_add_f32_e32 v167, 1.0, v167
	v_rcp_f32_e32 v167, v167
	s_nop 0
	v_mul_f32_e32 v232, v163, v167
	v_mul_f32_e32 v167, v164, v191
	v_fma_f32 v167, v164, v167, v164
	v_mul_f32_e32 v167, 0x3f4c422a, v167
	v_add_f32_e32 v167, v167, v167
	v_mul_f32_e32 v167, 0xbfb8aa3b, v167
	v_exp_f32_e32 v167, v167
	v_fmac_f32_e32 v166, v232, v232
	v_add_f32_e32 v167, 1.0, v167
	v_rcp_f32_e32 v167, v167
	s_nop 0
	v_mul_f32_e32 v250, v164, v167
	v_mul_f32_e32 v167, v165, v172
	v_fma_f32 v167, v165, v167, v165
	v_mul_f32_e32 v167, 0x3f4c422a, v167
	v_add_f32_e32 v167, v167, v167
	v_mul_f32_e32 v167, 0xbfb8aa3b, v167
	v_exp_f32_e32 v167, v167
	v_fmac_f32_e32 v166, v250, v250
	v_add_f32_e32 v167, 1.0, v167
	v_rcp_f32_e32 v167, v167
	s_nop 0
	v_mul_f32_e32 v249, v165, v167
	v_fmac_f32_e32 v166, v249, v249
	v_mov_b32_e32 v167, v166
	s_nop 1
	v_permlane16_swap_b32_e32 v167, v166
	s_waitcnt lgkmcnt(0)
	v_add_f32_e32 v166, v166, v167
	v_mov_b32_e32 v167, v166
	s_nop 1
	v_permlane32_swap_b32_e32 v167, v166
	s_waitcnt lgkmcnt(0)
	v_add_f32_e32 v166, v166, v167
	v_fmamk_f32 v166, v166, 0x3c800000, v231
	v_rsq_f32_e32 v251, v166
	v_ashrrev_i32_e32 v166, 7, v210
	v_ashrrev_i32_e32 v167, 31, v166
	v_lshlrev_b64 v[166:167], 16, v[166:167]
	v_lshl_add_u64 v[166:167], s[80:81], 0, v[166:167]
	v_lshl_add_u64 v[166:167], v[166:167], 0, v[168:169]
	v_and_b32_e32 v168, 8, v210
	v_lshlrev_b32_e32 v168, 1, v168
	v_lshl_add_u64 v[166:167], v[166:167], 0, v[168:169]
	v_and_b32_e32 v168, 7, v210
	v_lshlrev_b32_e32 v168, 1, v168
	v_lshl_add_u64 v[166:167], v[166:167], 0, v[168:169]
	s_lshl_b32 s80, s17, 1
	s_mov_b32 s81, s71
	v_lshl_add_u64 v[166:167], v[166:167], 0, s[80:81]
	v_lshlrev_b32_e32 v168, 1, v186
	v_lshl_add_u64 v[170:171], v[166:167], 0, v[168:169]
	global_load_dwordx4 v[166:169], v[202:203], off
	v_mul_f32_e32 v211, v211, v251
	s_movk_i32 s17, 0x2000
	s_mov_b64 s[80:81], 0
	s_waitcnt vmcnt(0)
	v_mul_f32_e32 v166, v166, v211
	v_cvt_pk_bf16_f32 v166, v166, s0
	global_store_short v[170:171], v166, off
	v_mul_f32_e32 v166, v223, v251
	v_mul_f32_e32 v166, v167, v166
	v_cvt_pk_bf16_f32 v166, v166, s0
	global_store_short v[170:171], v166, off offset:32
	v_mul_f32_e32 v166, v224, v251
	v_mul_f32_e32 v166, v168, v166
	v_cvt_pk_bf16_f32 v166, v166, s0
	global_store_short v[170:171], v166, off offset:64
	v_mul_f32_e32 v166, v225, v251
	v_mul_f32_e32 v166, v169, v166
	v_cvt_pk_bf16_f32 v166, v166, s0
	global_store_short v[170:171], v166, off offset:96
	global_load_dwordx4 v[166:169], v[202:203], off offset:16
	v_mul_f32_e32 v211, v226, v251
	s_waitcnt vmcnt(0)
	v_mul_f32_e32 v166, v211, v166
	v_cvt_pk_bf16_f32 v166, v166, s0
	global_store_short v[170:171], v166, off offset:128
	v_mul_f32_e32 v166, v227, v251
	v_mul_f32_e32 v166, v166, v167
	v_cvt_pk_bf16_f32 v166, v166, s0
	global_store_short v[170:171], v166, off offset:160
	v_mul_f32_e32 v166, v228, v251
	v_mul_f32_e32 v166, v166, v168
	v_cvt_pk_bf16_f32 v166, v166, s0
	global_store_short v[170:171], v166, off offset:192
	v_mul_f32_e32 v166, v229, v251
	v_mul_f32_e32 v166, v166, v169
	v_cvt_pk_bf16_f32 v166, v166, s0
	global_store_short v[170:171], v166, off offset:224
	global_load_dwordx4 v[166:169], v[202:203], off offset:128
	v_mul_f32_e32 v211, v248, v251
	v_add_co_u32_e32 v170, vcc, s17, v170
	s_waitcnt vmcnt(0)
	v_mul_f32_e32 v166, v211, v166
	v_cvt_pk_bf16_f32 v166, v166, s0
	v_addc_co_u32_e32 v171, vcc, 0, v171, vcc
	global_store_short v[170:171], v166, off
	v_mul_f32_e32 v166, v230, v251
	v_mul_f32_e32 v166, v166, v167
	v_cvt_pk_bf16_f32 v166, v166, s0
	global_store_short v[170:171], v166, off offset:32
	v_mul_f32_e32 v166, v187, v251
	v_mul_f32_e32 v166, v166, v168
	v_cvt_pk_bf16_f32 v166, v166, s0
	global_store_short v[170:171], v166, off offset:64
	v_mul_f32_e32 v166, v235, v251
	v_mul_f32_e32 v166, v166, v169
	v_cvt_pk_bf16_f32 v166, v166, s0
	global_store_short v[170:171], v166, off offset:96
	global_load_dwordx4 v[166:169], v[202:203], off offset:144
	v_mul_f32_e32 v187, v233, v251
	s_waitcnt vmcnt(0)
	v_mul_f32_e32 v166, v187, v166
	v_cvt_pk_bf16_f32 v166, v166, s0
	global_store_short v[170:171], v166, off offset:128
	v_mul_f32_e32 v166, v232, v251
	v_mul_f32_e32 v166, v166, v167
	v_cvt_pk_bf16_f32 v166, v166, s0
	global_store_short v[170:171], v166, off offset:160
	v_mul_f32_e32 v166, v250, v251
	v_mul_f32_e32 v166, v166, v168
	v_cvt_pk_bf16_f32 v166, v166, s0
	global_store_short v[170:171], v166, off offset:192
	v_mul_f32_e32 v166, v249, v251
	v_mul_f32_e32 v166, v166, v169
	v_cvt_pk_bf16_f32 v166, v166, s0
	global_store_short v[170:171], v166, off offset:224

.LBB0_265:
	v_add_u32_e32 v210, 0xa0, v204
	global_load_dwordx4 v[146:149], v[208:209], off offset:2816
	s_waitcnt vmcnt(1)
	v_mov_b32_e32 v154, v151
	v_mov_b32_e32 v155, v152
	v_mov_b32_e32 v151, v153
	v_pk_add_f32 v[150:151], v[154:155], v[150:151]
	s_and_b64 vcc, exec, s[14:15]
	v_add_f32_e32 v150, v150, v151
	v_fmamk_f32 v150, v150, 0x3a800000, v231
	v_rsq_f32_e32 v162, v150
	s_nop 0
	v_pk_fma_f32 v[152:153], v[64:65], v[162:163], v[144:145] op_sel_hi:[1,0,1]
	v_pk_fma_f32 v[150:151], v[62:63], v[162:163], v[142:143] op_sel_hi:[1,0,1]
	v_pk_fma_f32 v[156:157], v[60:61], v[162:163], v[140:141] op_sel_hi:[1,0,1]
	v_pk_fma_f32 v[154:155], v[58:59], v[162:163], v[138:139] op_sel_hi:[1,0,1]
	v_pk_fma_f32 v[160:161], v[56:57], v[162:163], v[136:137] op_sel_hi:[1,0,1]
	v_pk_fma_f32 v[158:159], v[54:55], v[162:163], v[134:135] op_sel_hi:[1,0,1]
	v_pk_fma_f32 v[164:165], v[52:53], v[162:163], v[132:133] op_sel_hi:[1,0,1]
	v_pk_fma_f32 v[162:163], v[50:51], v[162:163], v[130:131] op_sel_hi:[1,0,1]
	s_cbranch_vccnz .LBB0_331
	s_and_b64 vcc, exec, s[12:13]
	s_mov_b64 s[80:81], -1
	s_cbranch_vccnz .LBB0_284
	v_readlane_b32 s80, v254, 60
	v_readlane_b32 s81, v254, 61
	s_andn2_b64 vcc, exec, s[80:81]
	s_mov_b64 s[80:81], -1
	s_cbranch_vccnz .LBB0_273
	v_readlane_b32 s88, v254, 62
	v_readlane_b32 s89, v254, 63
	s_andn2_b64 vcc, exec, s[88:89]
	v_mul_f32_e32 v220, 0x3d372713, v150
	v_mul_f32_e32 v218, 0x3d372713, v151
	v_mul_f32_e32 v216, 0x3d372713, v152
	v_mul_f32_e32 v214, 0x3d372713, v153
	v_mul_f32_e32 v219, 0x3d372713, v154
	v_mul_f32_e32 v217, 0x3d372713, v155
	v_mul_f32_e32 v215, 0x3d372713, v156
	v_mul_f32_e32 v213, 0x3d372713, v157
	v_mul_f32_e32 v212, 0x3d372713, v158
	v_mul_f32_e32 v208, 0x3d372713, v159
	v_mul_f32_e32 v199, 0x3d372713, v160
	v_mul_f32_e32 v173, 0x3d372713, v161
	v_mul_f32_e32 v209, 0x3d372713, v162
	v_mul_f32_e32 v205, 0x3d372713, v163
	v_mul_f32_e32 v191, 0x3d372713, v164
	v_mul_f32_e32 v172, 0x3d372713, v165
	s_cbranch_vccnz .LBB0_270
	v_mul_f32_e32 v167, v152, v216
	v_fma_f32 v167, v152, v167, v152
	v_mul_f32_e32 v167, 0x3f4c422a, v167
	v_add_f32_e32 v167, v167, v167
	v_mul_f32_e32 v167, 0xbfb8aa3b, v167
	v_exp_f32_e32 v167, v167
	v_mul_f32_e32 v166, v150, v220
	v_fma_f32 v166, v150, v166, v150
	v_mul_f32_e32 v166, 0x3f4c422a, v166
	v_add_f32_e32 v167, 1.0, v167
	v_rcp_f32_e32 v167, v167
	v_add_f32_e32 v166, v166, v166
	v_mul_f32_e32 v166, 0xbfb8aa3b, v166
	v_exp_f32_e32 v166, v166
	v_mul_f32_e32 v222, v152, v167
	v_mul_f32_e32 v167, v153, v214
	v_fma_f32 v167, v153, v167, v153
	v_mul_f32_e32 v167, 0x3f4c422a, v167
	v_add_f32_e32 v167, v167, v167
	v_mul_f32_e32 v167, 0xbfb8aa3b, v167
	v_exp_f32_e32 v167, v167
	v_add_f32_e32 v166, 1.0, v166
	v_rcp_f32_e32 v166, v166
	v_readlane_b32 s80, v255, 0
	v_add_f32_e32 v167, 1.0, v167
	v_rcp_f32_e32 v167, v167
	v_mul_f32_e32 v211, v150, v166
	v_mul_f32_e32 v166, v151, v218
	v_fma_f32 v166, v151, v166, v151
	v_mul_f32_e32 v223, v153, v167
	v_mul_f32_e32 v167, v154, v219
	v_fma_f32 v167, v154, v167, v154
	v_mul_f32_e32 v167, 0x3f4c422a, v167
	v_add_f32_e32 v167, v167, v167
	v_mul_f32_e32 v167, 0xbfb8aa3b, v167
	v_exp_f32_e32 v167, v167
	v_mul_f32_e32 v166, 0x3f4c422a, v166
	v_add_f32_e32 v166, v166, v166
	v_mul_f32_e32 v166, 0xbfb8aa3b, v166
	v_add_f32_e32 v167, 1.0, v167
	v_rcp_f32_e32 v167, v167
	v_exp_f32_e32 v166, v166
	v_readlane_b32 s81, v255, 1
	v_lshlrev_b32_e32 v168, 6, v210
	v_mul_f32_e32 v224, v154, v167
	v_mul_f32_e32 v167, v155, v217
	v_fma_f32 v167, v155, v167, v155
	v_mul_f32_e32 v167, 0x3f4c422a, v167
	v_add_f32_e32 v167, v167, v167
	v_mul_f32_e32 v167, 0xbfb8aa3b, v167
	v_exp_f32_e32 v167, v167
	v_add_f32_e32 v166, 1.0, v166
	v_rcp_f32_e32 v166, v166
	v_and_b32_e32 v168, 0x1c00, v168
	v_add_f32_e32 v167, 1.0, v167
	v_rcp_f32_e32 v167, v167
	v_mul_f32_e32 v221, v151, v166
	v_mul_f32_e32 v166, v221, v221
	v_fmac_f32_e32 v166, v211, v211
	v_mul_f32_e32 v225, v155, v167
	v_mul_f32_e32 v167, v156, v215
	v_fma_f32 v167, v156, v167, v156
	v_mul_f32_e32 v167, 0x3f4c422a, v167
	v_add_f32_e32 v167, v167, v167
	v_mul_f32_e32 v167, 0xbfb8aa3b, v167
	v_exp_f32_e32 v167, v167
	v_fmac_f32_e32 v166, v222, v222
	v_fmac_f32_e32 v166, v223, v223
	v_fmac_f32_e32 v166, v224, v224
	v_add_f32_e32 v167, 1.0, v167
	v_rcp_f32_e32 v167, v167
	v_fmac_f32_e32 v166, v225, v225
	v_mov_b32_e32 v169, v1
	v_readlane_b32 s17, v254, 15
	v_mul_f32_e32 v226, v156, v167
	v_mul_f32_e32 v167, v157, v213
	v_fma_f32 v167, v157, v167, v157
	v_mul_f32_e32 v167, 0x3f4c422a, v167
	v_add_f32_e32 v167, v167, v167
	v_mul_f32_e32 v167, 0xbfb8aa3b, v167
	v_exp_f32_e32 v167, v167
	v_fmac_f32_e32 v166, v226, v226
	v_add_f32_e32 v167, 1.0, v167
	v_rcp_f32_e32 v167, v167
	s_nop 0
	v_mul_f32_e32 v227, v157, v167
	v_mul_f32_e32 v167, v158, v212
	v_fma_f32 v167, v158, v167, v158
	v_mul_f32_e32 v167, 0x3f4c422a, v167
	v_add_f32_e32 v167, v167, v167
	v_mul_f32_e32 v167, 0xbfb8aa3b, v167
	v_exp_f32_e32 v167, v167
	v_fmac_f32_e32 v166, v227, v227
	v_add_f32_e32 v167, 1.0, v167
	v_rcp_f32_e32 v167, v167
	s_nop 0
	v_mul_f32_e32 v228, v158, v167
	v_mul_f32_e32 v167, v159, v208
	v_fma_f32 v167, v159, v167, v159
	v_mul_f32_e32 v167, 0x3f4c422a, v167
	v_add_f32_e32 v167, v167, v167
	v_mul_f32_e32 v167, 0xbfb8aa3b, v167
	v_exp_f32_e32 v167, v167
	v_fmac_f32_e32 v166, v228, v228
	v_add_f32_e32 v167, 1.0, v167
	v_rcp_f32_e32 v167, v167
	s_nop 0
	v_mul_f32_e32 v230, v159, v167
	v_mul_f32_e32 v167, v160, v199
	v_fma_f32 v167, v160, v167, v160
	v_mul_f32_e32 v167, 0x3f4c422a, v167
	v_add_f32_e32 v167, v167, v167
	v_mul_f32_e32 v167, 0xbfb8aa3b, v167
	v_exp_f32_e32 v167, v167
	v_fmac_f32_e32 v166, v230, v230
	v_add_f32_e32 v167, 1.0, v167
	v_rcp_f32_e32 v167, v167
	s_nop 0
	v_mul_f32_e32 v187, v160, v167
	v_mul_f32_e32 v167, v161, v173
	v_fma_f32 v167, v161, v167, v161
	v_mul_f32_e32 v167, 0x3f4c422a, v167
	v_add_f32_e32 v167, v167, v167
	v_mul_f32_e32 v167, 0xbfb8aa3b, v167
	v_exp_f32_e32 v167, v167
	v_fmac_f32_e32 v166, v187, v187
	v_add_f32_e32 v167, 1.0, v167
	v_rcp_f32_e32 v167, v167
	s_nop 0
	v_mul_f32_e32 v235, v161, v167
	v_mul_f32_e32 v167, v162, v209
	v_fma_f32 v167, v162, v167, v162
	v_mul_f32_e32 v167, 0x3f4c422a, v167
	v_add_f32_e32 v167, v167, v167
	v_mul_f32_e32 v167, 0xbfb8aa3b, v167
	v_exp_f32_e32 v167, v167
	v_fmac_f32_e32 v166, v235, v235
	v_add_f32_e32 v167, 1.0, v167
	v_rcp_f32_e32 v167, v167
	s_nop 0
	v_mul_f32_e32 v233, v162, v167
	v_mul_f32_e32 v167, v163, v205
	v_fma_f32 v167, v163, v167, v163
	v_mul_f32_e32 v167, 0x3f4c422a, v167
	v_add_f32_e32 v167, v167, v167
	v_mul_f32_e32 v167, 0xbfb8aa3b, v167
	v_exp_f32_e32 v167, v167
	v_fmac_f32_e32 v166, v233, v233
	v_add_f32_e32 v167, 1.0, v167
	v_rcp_f32_e32 v167, v167
	s_nop 0
	v_mul_f32_e32 v232, v163, v167
	v_mul_f32_e32 v167, v164, v191
	v_fma_f32 v167, v164, v167, v164
	v_mul_f32_e32 v167, 0x3f4c422a, v167
	v_add_f32_e32 v167, v167, v167
	v_mul_f32_e32 v167, 0xbfb8aa3b, v167
	v_exp_f32_e32 v167, v167
	v_fmac_f32_e32 v166, v232, v232
	v_add_f32_e32 v167, 1.0, v167
	v_rcp_f32_e32 v167, v167
	s_nop 0
	v_mul_f32_e32 v248, v164, v167
	v_mul_f32_e32 v167, v165, v172
	v_fma_f32 v167, v165, v167, v165
	v_mul_f32_e32 v167, 0x3f4c422a, v167
	v_add_f32_e32 v167, v167, v167
	v_mul_f32_e32 v167, 0xbfb8aa3b, v167
	v_exp_f32_e32 v167, v167
	v_fmac_f32_e32 v166, v248, v248
	v_add_f32_e32 v167, 1.0, v167
	v_rcp_f32_e32 v167, v167
	s_nop 0
	v_mul_f32_e32 v229, v165, v167
	v_fmac_f32_e32 v166, v229, v229
	v_mov_b32_e32 v167, v166
	s_nop 1
	v_permlane16_swap_b32_e32 v167, v166
	s_waitcnt lgkmcnt(0)
	v_add_f32_e32 v166, v166, v167
	v_mov_b32_e32 v167, v166
	s_nop 1
	v_permlane32_swap_b32_e32 v167, v166
	s_waitcnt lgkmcnt(0)
	v_add_f32_e32 v166, v166, v167
	v_fmamk_f32 v166, v166, 0x3c800000, v231
	v_rsq_f32_e32 v249, v166
	v_ashrrev_i32_e32 v166, 7, v210
	v_ashrrev_i32_e32 v167, 31, v166
	v_lshlrev_b64 v[166:167], 16, v[166:167]
	v_lshl_add_u64 v[166:167], s[80:81], 0, v[166:167]
	v_lshl_add_u64 v[166:167], v[166:167], 0, v[168:169]
	v_and_b32_e32 v168, 8, v210
	v_lshlrev_b32_e32 v168, 1, v168
	v_lshl_add_u64 v[166:167], v[166:167], 0, v[168:169]
	v_and_b32_e32 v168, 7, v210
	v_lshlrev_b32_e32 v168, 1, v168
	v_lshl_add_u64 v[166:167], v[166:167], 0, v[168:169]
	s_lshl_b32 s80, s17, 1
	s_mov_b32 s81, s71
	v_lshl_add_u64 v[166:167], v[166:167], 0, s[80:81]
	v_lshlrev_b32_e32 v168, 1, v186
	v_lshl_add_u64 v[170:171], v[166:167], 0, v[168:169]
	global_load_dwordx4 v[166:169], v[202:203], off
	v_mul_f32_e32 v211, v211, v249
	s_movk_i32 s17, 0x2000
	s_mov_b64 s[80:81], 0
	s_waitcnt vmcnt(0)
	v_mul_f32_e32 v166, v166, v211
	v_cvt_pk_bf16_f32 v166, v166, s0
	global_store_short v[170:171], v166, off
	v_mul_f32_e32 v166, v221, v249
	v_mul_f32_e32 v166, v167, v166
	v_cvt_pk_bf16_f32 v166, v166, s0
	global_store_short v[170:171], v166, off offset:32
	v_mul_f32_e32 v166, v222, v249
	v_mul_f32_e32 v166, v168, v166
	v_cvt_pk_bf16_f32 v166, v166, s0
	global_store_short v[170:171], v166, off offset:64
	v_mul_f32_e32 v166, v223, v249
	v_mul_f32_e32 v166, v169, v166
	v_cvt_pk_bf16_f32 v166, v166, s0
	global_store_short v[170:171], v166, off offset:96
	global_load_dwordx4 v[166:169], v[202:203], off offset:16
	v_mul_f32_e32 v211, v224, v249
	s_waitcnt vmcnt(0)
	v_mul_f32_e32 v166, v211, v166
	v_cvt_pk_bf16_f32 v166, v166, s0
	global_store_short v[170:171], v166, off offset:128
	v_mul_f32_e32 v166, v225, v249
	v_mul_f32_e32 v166, v166, v167
	v_cvt_pk_bf16_f32 v166, v166, s0
	global_store_short v[170:171], v166, off offset:160
	v_mul_f32_e32 v166, v226, v249
	v_mul_f32_e32 v166, v166, v168
	v_cvt_pk_bf16_f32 v166, v166, s0
	global_store_short v[170:171], v166, off offset:192
	v_mul_f32_e32 v166, v227, v249
	v_mul_f32_e32 v166, v166, v169
	v_cvt_pk_bf16_f32 v166, v166, s0
	global_store_short v[170:171], v166, off offset:224
	global_load_dwordx4 v[166:169], v[202:203], off offset:128
	v_mul_f32_e32 v211, v228, v249
	v_add_co_u32_e32 v170, vcc, s17, v170
	s_waitcnt vmcnt(0)
	v_mul_f32_e32 v166, v211, v166
	v_cvt_pk_bf16_f32 v166, v166, s0
	v_addc_co_u32_e32 v171, vcc, 0, v171, vcc
	global_store_short v[170:171], v166, off
	v_mul_f32_e32 v166, v230, v249
	v_mul_f32_e32 v166, v166, v167
	v_cvt_pk_bf16_f32 v166, v166, s0
	global_store_short v[170:171], v166, off offset:32
	v_mul_f32_e32 v166, v187, v249
	v_mul_f32_e32 v166, v166, v168
	v_cvt_pk_bf16_f32 v166, v166, s0
	global_store_short v[170:171], v166, off offset:64
	v_mul_f32_e32 v166, v235, v249
	v_mul_f32_e32 v166, v166, v169
	v_cvt_pk_bf16_f32 v166, v166, s0
	global_store_short v[170:171], v166, off offset:96
	global_load_dwordx4 v[166:169], v[202:203], off offset:144
	v_mul_f32_e32 v187, v233, v249
	s_waitcnt vmcnt(0)
	v_mul_f32_e32 v166, v187, v166
	v_cvt_pk_bf16_f32 v166, v166, s0
	global_store_short v[170:171], v166, off offset:128
	v_mul_f32_e32 v166, v232, v249
	v_mul_f32_e32 v166, v166, v167
	v_cvt_pk_bf16_f32 v166, v166, s0
	global_store_short v[170:171], v166, off offset:160
	v_mul_f32_e32 v166, v248, v249
	v_mul_f32_e32 v166, v166, v168
	v_cvt_pk_bf16_f32 v166, v166, s0
	global_store_short v[170:171], v166, off offset:192
	v_mul_f32_e32 v166, v229, v249
	v_mul_f32_e32 v166, v166, v169
	v_cvt_pk_bf16_f32 v166, v166, s0
	global_store_short v[170:171], v166, off offset:224

.LBB0_284:
	s_andn2_b64 vcc, exec, s[80:81]
	s_cbranch_vccnz .LBB0_294
	v_mul_f32_e32 v166, v151, v151
	v_mul_f32_e32 v167, v153, v153
	v_fmac_f32_e32 v166, v150, v150
	v_fmac_f32_e32 v167, v152, v152
	v_add_f32_e32 v166, v166, v167
	v_mul_f32_e32 v167, v155, v155
	v_mul_f32_e32 v168, v157, v157
	v_fmac_f32_e32 v167, v154, v154
	v_fmac_f32_e32 v168, v156, v156
	v_add_f32_e32 v167, v167, v168
	v_add_f32_e32 v166, v166, v167
	v_mul_f32_e32 v167, v159, v159
	v_mul_f32_e32 v168, v161, v161
	v_fmac_f32_e32 v167, v158, v158
	v_fmac_f32_e32 v168, v160, v160
	v_add_f32_e32 v167, v167, v168
	v_add_f32_e32 v166, v167, v166
	v_mul_f32_e32 v167, v163, v163
	v_mul_f32_e32 v168, v165, v165
	v_fmac_f32_e32 v167, v162, v162
	v_fmac_f32_e32 v168, v164, v164
	v_add_f32_e32 v167, v167, v168
	v_add_f32_e32 v166, v167, v166
	v_mov_b32_e32 v167, v166
	s_nop 1
	v_permlane16_swap_b32_e32 v167, v166
	v_readlane_b32 s80, v255, 4
	v_readlane_b32 s81, v255, 5
	s_andn2_b64 vcc, exec, s[80:81]
	s_mov_b64 s[80:81], -1
	s_waitcnt lgkmcnt(0)
	v_add_f32_e32 v166, v166, v167
	v_mov_b32_e32 v167, v166
	s_nop 1
	v_permlane32_swap_b32_e32 v167, v166
	s_cbranch_vccnz .LBB0_287
	v_ashrrev_i32_e32 v211, 31, v210
	v_lshlrev_b64 v[168:169], 7, v[210:211]
	v_lshl_add_u64 v[208:209], v[176:177], 0, v[168:169]
	s_mov_b64 s[80:81], 0

.LBB0_296:
	s_waitcnt vmcnt(0)
	s_nop 0
	v_mov_b32_e32 v150, v147
	v_mov_b32_e32 v151, v148
	v_mov_b32_e32 v147, v149
	v_pk_add_f32 v[146:147], v[150:151], v[146:147]
	v_add_u32_e32 v154, 0xb0, v204
	v_add_f32_e32 v146, v146, v147
	v_fmamk_f32 v146, v146, 0x3a800000, v231
	v_rsq_f32_e32 v146, v146
	s_and_b64 vcc, exec, s[14:15]
	v_readlane_b32 s80, v254, 51
	v_readlane_b32 s81, v254, 52
	v_pk_fma_f32 v[144:145], v[48:49], v[146:147], v[144:145] op_sel_hi:[1,0,1]
	v_pk_fma_f32 v[142:143], v[46:47], v[146:147], v[142:143] op_sel_hi:[1,0,1]
	v_pk_fma_f32 v[140:141], v[44:45], v[146:147], v[140:141] op_sel_hi:[1,0,1]
	v_pk_fma_f32 v[138:139], v[42:43], v[146:147], v[138:139] op_sel_hi:[1,0,1]
	v_pk_fma_f32 v[136:137], v[40:41], v[146:147], v[136:137] op_sel_hi:[1,0,1]
	v_pk_fma_f32 v[134:135], v[38:39], v[146:147], v[134:135] op_sel_hi:[1,0,1]
	v_pk_fma_f32 v[132:133], v[36:37], v[146:147], v[132:133] op_sel_hi:[1,0,1]
	v_pk_fma_f32 v[130:131], v[34:35], v[146:147], v[130:131] op_sel_hi:[1,0,1]
	s_cbranch_vccnz .LBB0_332
	s_and_b64 vcc, exec, s[12:13]
	s_mov_b64 s[12:13], -1
	s_cbranch_vccnz .LBB0_315
	v_readlane_b32 s12, v254, 60
	v_readlane_b32 s13, v254, 61
	s_andn2_b64 vcc, exec, s[12:13]
	s_mov_b64 s[12:13], -1
	s_cbranch_vccnz .LBB0_304
	v_readlane_b32 s14, v254, 62
	v_readlane_b32 s15, v254, 63
	s_andn2_b64 vcc, exec, s[14:15]
	v_mul_f32_e32 v169, 0x3d372713, v142
	v_mul_f32_e32 v167, 0x3d372713, v143
	v_mul_f32_e32 v165, 0x3d372713, v144
	v_mul_f32_e32 v163, 0x3d372713, v145
	v_mul_f32_e32 v168, 0x3d372713, v138
	v_mul_f32_e32 v166, 0x3d372713, v139
	v_mul_f32_e32 v164, 0x3d372713, v140
	v_mul_f32_e32 v162, 0x3d372713, v141
	v_mul_f32_e32 v161, 0x3d372713, v134
	v_mul_f32_e32 v159, 0x3d372713, v135
	v_mul_f32_e32 v157, 0x3d372713, v136
	v_mul_f32_e32 v153, 0x3d372713, v137
	v_mul_f32_e32 v160, 0x3d372713, v130
	v_mul_f32_e32 v158, 0x3d372713, v131
	v_mul_f32_e32 v156, 0x3d372713, v132
	v_mul_f32_e32 v152, 0x3d372713, v133
	s_cbranch_vccnz .LBB0_301
	v_mul_f32_e32 v147, v144, v165
	v_fma_f32 v147, v144, v147, v144
	v_mul_f32_e32 v147, 0x3f4c422a, v147
	v_add_f32_e32 v147, v147, v147
	v_mul_f32_e32 v147, 0xbfb8aa3b, v147
	v_exp_f32_e32 v147, v147
	v_mul_f32_e32 v146, v142, v169
	v_fma_f32 v146, v142, v146, v142
	v_mul_f32_e32 v146, 0x3f4c422a, v146
	v_add_f32_e32 v147, 1.0, v147
	v_rcp_f32_e32 v147, v147
	v_add_f32_e32 v146, v146, v146
	v_mul_f32_e32 v146, 0xbfb8aa3b, v146
	v_exp_f32_e32 v146, v146
	v_mul_f32_e32 v171, v144, v147
	v_mul_f32_e32 v147, v145, v163
	v_fma_f32 v147, v145, v147, v145
	v_mul_f32_e32 v147, 0x3f4c422a, v147
	v_add_f32_e32 v147, v147, v147
	v_mul_f32_e32 v147, 0xbfb8aa3b, v147
	v_exp_f32_e32 v147, v147
	v_add_f32_e32 v146, 1.0, v146
	v_rcp_f32_e32 v146, v146
	v_readlane_b32 s12, v255, 0
	v_add_f32_e32 v147, 1.0, v147
	v_rcp_f32_e32 v147, v147
	v_mul_f32_e32 v155, v142, v146
	v_mul_f32_e32 v146, v143, v167
	v_fma_f32 v146, v143, v146, v143
	v_mul_f32_e32 v172, v145, v147
	v_mul_f32_e32 v147, v138, v168
	v_fma_f32 v147, v138, v147, v138
	v_mul_f32_e32 v147, 0x3f4c422a, v147
	v_add_f32_e32 v147, v147, v147
	v_mul_f32_e32 v147, 0xbfb8aa3b, v147
	v_exp_f32_e32 v147, v147
	v_mul_f32_e32 v146, 0x3f4c422a, v146
	v_add_f32_e32 v146, v146, v146
	v_mul_f32_e32 v146, 0xbfb8aa3b, v146
	v_add_f32_e32 v147, 1.0, v147
	v_rcp_f32_e32 v147, v147
	v_exp_f32_e32 v146, v146
	v_readlane_b32 s13, v255, 1
	v_lshlrev_b32_e32 v148, 6, v154
	v_mul_f32_e32 v173, v138, v147
	v_mul_f32_e32 v147, v139, v166
	v_fma_f32 v147, v139, v147, v139
	v_mul_f32_e32 v147, 0x3f4c422a, v147
	v_add_f32_e32 v147, v147, v147
	v_mul_f32_e32 v147, 0xbfb8aa3b, v147
	v_exp_f32_e32 v147, v147
	v_add_f32_e32 v146, 1.0, v146
	v_rcp_f32_e32 v146, v146
	v_and_b32_e32 v148, 0x1c00, v148
	v_add_f32_e32 v147, 1.0, v147
	v_rcp_f32_e32 v147, v147
	v_mul_f32_e32 v170, v143, v146
	v_mul_f32_e32 v146, v170, v170
	v_fmac_f32_e32 v146, v155, v155
	v_mul_f32_e32 v191, v139, v147
	v_mul_f32_e32 v147, v140, v164
	v_fma_f32 v147, v140, v147, v140
	v_mul_f32_e32 v147, 0x3f4c422a, v147
	v_add_f32_e32 v147, v147, v147
	v_mul_f32_e32 v147, 0xbfb8aa3b, v147
	v_exp_f32_e32 v147, v147
	v_fmac_f32_e32 v146, v171, v171
	v_fmac_f32_e32 v146, v172, v172
	v_fmac_f32_e32 v146, v173, v173
	v_add_f32_e32 v147, 1.0, v147
	v_rcp_f32_e32 v147, v147
	v_fmac_f32_e32 v146, v191, v191
	v_mov_b32_e32 v149, v1
	v_mul_f32_e32 v199, v140, v147
	v_mul_f32_e32 v147, v141, v162
	v_fma_f32 v147, v141, v147, v141
	v_mul_f32_e32 v147, 0x3f4c422a, v147
	v_add_f32_e32 v147, v147, v147
	v_mul_f32_e32 v147, 0xbfb8aa3b, v147
	v_exp_f32_e32 v147, v147
	v_fmac_f32_e32 v146, v199, v199
	v_add_f32_e32 v147, 1.0, v147
	v_rcp_f32_e32 v147, v147
	s_nop 0
	v_mul_f32_e32 v204, v141, v147
	v_mul_f32_e32 v147, v134, v161
	v_fma_f32 v147, v134, v147, v134
	v_mul_f32_e32 v147, 0x3f4c422a, v147
	v_add_f32_e32 v147, v147, v147
	v_mul_f32_e32 v147, 0xbfb8aa3b, v147
	v_exp_f32_e32 v147, v147
	v_fmac_f32_e32 v146, v204, v204
	v_add_f32_e32 v147, 1.0, v147
	v_rcp_f32_e32 v147, v147
	s_nop 0
	v_mul_f32_e32 v205, v134, v147
	v_mul_f32_e32 v147, v135, v159
	v_fma_f32 v147, v135, v147, v135
	v_mul_f32_e32 v147, 0x3f4c422a, v147
	v_add_f32_e32 v147, v147, v147
	v_mul_f32_e32 v147, 0xbfb8aa3b, v147
	v_exp_f32_e32 v147, v147
	v_fmac_f32_e32 v146, v205, v205
	v_add_f32_e32 v147, 1.0, v147
	v_rcp_f32_e32 v147, v147
	s_nop 0
	v_mul_f32_e32 v212, v135, v147
	v_mul_f32_e32 v147, v136, v157
	v_fma_f32 v147, v136, v147, v136
	v_mul_f32_e32 v147, 0x3f4c422a, v147
	v_add_f32_e32 v147, v147, v147
	v_mul_f32_e32 v147, 0xbfb8aa3b, v147
	v_exp_f32_e32 v147, v147
	v_fmac_f32_e32 v146, v212, v212
	v_add_f32_e32 v147, 1.0, v147
	v_rcp_f32_e32 v147, v147
	s_nop 0
	v_mul_f32_e32 v187, v136, v147
	v_mul_f32_e32 v147, v137, v153
	v_fma_f32 v147, v137, v147, v137
	v_mul_f32_e32 v147, 0x3f4c422a, v147
	v_add_f32_e32 v147, v147, v147
	v_mul_f32_e32 v147, 0xbfb8aa3b, v147
	v_exp_f32_e32 v147, v147
	v_fmac_f32_e32 v146, v187, v187
	v_add_f32_e32 v147, 1.0, v147
	v_rcp_f32_e32 v147, v147
	s_nop 0
	v_mul_f32_e32 v214, v137, v147
	v_mul_f32_e32 v147, v130, v160
	v_fma_f32 v147, v130, v147, v130
	v_mul_f32_e32 v147, 0x3f4c422a, v147
	v_add_f32_e32 v147, v147, v147
	v_mul_f32_e32 v147, 0xbfb8aa3b, v147
	v_exp_f32_e32 v147, v147
	v_fmac_f32_e32 v146, v214, v214
	v_add_f32_e32 v147, 1.0, v147
	v_rcp_f32_e32 v147, v147
	s_nop 0
	v_mul_f32_e32 v213, v130, v147
	v_mul_f32_e32 v147, v131, v158
	v_fma_f32 v147, v131, v147, v131
	v_mul_f32_e32 v147, 0x3f4c422a, v147
	v_add_f32_e32 v147, v147, v147
	v_mul_f32_e32 v147, 0xbfb8aa3b, v147
	v_exp_f32_e32 v147, v147
	v_fmac_f32_e32 v146, v213, v213
	v_add_f32_e32 v147, 1.0, v147
	v_rcp_f32_e32 v147, v147
	s_nop 0
	v_mul_f32_e32 v211, v131, v147
	v_mul_f32_e32 v147, v132, v156
	v_fma_f32 v147, v132, v147, v132
	v_mul_f32_e32 v147, 0x3f4c422a, v147
	v_add_f32_e32 v147, v147, v147
	v_mul_f32_e32 v147, 0xbfb8aa3b, v147
	v_exp_f32_e32 v147, v147
	v_fmac_f32_e32 v146, v211, v211
	v_add_f32_e32 v147, 1.0, v147
	v_rcp_f32_e32 v147, v147
	s_nop 0
	v_mul_f32_e32 v209, v132, v147
	v_mul_f32_e32 v147, v133, v152
	v_fma_f32 v147, v133, v147, v133
	v_mul_f32_e32 v147, 0x3f4c422a, v147
	v_add_f32_e32 v147, v147, v147
	v_mul_f32_e32 v147, 0xbfb8aa3b, v147
	v_exp_f32_e32 v147, v147
	v_fmac_f32_e32 v146, v209, v209
	v_add_f32_e32 v147, 1.0, v147
	v_rcp_f32_e32 v147, v147
	s_nop 0
	v_mul_f32_e32 v208, v133, v147
	v_fmac_f32_e32 v146, v208, v208
	v_mov_b32_e32 v147, v146
	s_nop 1
	v_permlane16_swap_b32_e32 v147, v146
	s_waitcnt lgkmcnt(0)
	v_add_f32_e32 v146, v146, v147
	v_mov_b32_e32 v147, v146
	s_nop 1
	v_permlane32_swap_b32_e32 v147, v146
	s_waitcnt lgkmcnt(0)
	v_add_f32_e32 v146, v146, v147
	v_fmamk_f32 v146, v146, 0x3c800000, v231
	v_rsq_f32_e32 v210, v146
	v_ashrrev_i32_e32 v146, 7, v154
	v_ashrrev_i32_e32 v147, 31, v146
	v_lshlrev_b64 v[146:147], 16, v[146:147]
	v_lshl_add_u64 v[146:147], s[12:13], 0, v[146:147]
	v_lshl_add_u64 v[146:147], v[146:147], 0, v[148:149]
	v_and_b32_e32 v148, 8, v154
	v_lshlrev_b32_e32 v148, 1, v148
	v_lshl_add_u64 v[146:147], v[146:147], 0, v[148:149]
	v_and_b32_e32 v148, 7, v154
	v_lshlrev_b32_e32 v148, 1, v148
	v_readlane_b32 s12, v254, 15
	v_lshl_add_u64 v[146:147], v[146:147], 0, v[148:149]
	s_lshl_b32 s12, s12, 1
	s_mov_b32 s13, s71
	v_lshl_add_u64 v[146:147], v[146:147], 0, s[12:13]
	v_lshlrev_b32_e32 v148, 1, v186
	v_lshl_add_u64 v[150:151], v[146:147], 0, v[148:149]
	global_load_dwordx4 v[146:149], v[202:203], off
	v_mul_f32_e32 v155, v155, v210
	s_movk_i32 s12, 0x2000
	s_waitcnt vmcnt(0)
	v_mul_f32_e32 v146, v146, v155
	v_cvt_pk_bf16_f32 v146, v146, s0
	global_store_short v[150:151], v146, off
	v_mul_f32_e32 v146, v170, v210
	v_mul_f32_e32 v146, v147, v146
	v_cvt_pk_bf16_f32 v146, v146, s0
	global_store_short v[150:151], v146, off offset:32
	v_mul_f32_e32 v146, v171, v210
	v_mul_f32_e32 v146, v148, v146
	v_cvt_pk_bf16_f32 v146, v146, s0
	global_store_short v[150:151], v146, off offset:64
	v_mul_f32_e32 v146, v172, v210
	v_mul_f32_e32 v146, v149, v146
	v_cvt_pk_bf16_f32 v146, v146, s0
	global_store_short v[150:151], v146, off offset:96
	global_load_dwordx4 v[146:149], v[202:203], off offset:16
	v_mul_f32_e32 v155, v173, v210
	s_waitcnt vmcnt(0)
	v_mul_f32_e32 v146, v155, v146
	v_cvt_pk_bf16_f32 v146, v146, s0
	global_store_short v[150:151], v146, off offset:128
	v_mul_f32_e32 v146, v191, v210
	v_mul_f32_e32 v146, v146, v147
	v_cvt_pk_bf16_f32 v146, v146, s0
	global_store_short v[150:151], v146, off offset:160
	v_mul_f32_e32 v146, v199, v210
	v_mul_f32_e32 v146, v146, v148
	v_cvt_pk_bf16_f32 v146, v146, s0
	global_store_short v[150:151], v146, off offset:192
	v_mul_f32_e32 v146, v204, v210
	v_mul_f32_e32 v146, v146, v149
	v_cvt_pk_bf16_f32 v146, v146, s0
	global_store_short v[150:151], v146, off offset:224
	global_load_dwordx4 v[146:149], v[202:203], off offset:128
	v_mul_f32_e32 v155, v205, v210
	v_add_co_u32_e32 v150, vcc, s12, v150
	s_mov_b64 s[12:13], 0
	s_nop 0
	v_addc_co_u32_e32 v151, vcc, 0, v151, vcc
	s_waitcnt vmcnt(0)
	v_mul_f32_e32 v146, v155, v146
	v_cvt_pk_bf16_f32 v146, v146, s0
	global_store_short v[150:151], v146, off
	v_mul_f32_e32 v146, v212, v210
	v_mul_f32_e32 v146, v146, v147
	v_cvt_pk_bf16_f32 v146, v146, s0
	global_store_short v[150:151], v146, off offset:32
	v_mul_f32_e32 v146, v187, v210
	v_mul_f32_e32 v146, v146, v148
	v_cvt_pk_bf16_f32 v146, v146, s0
	global_store_short v[150:151], v146, off offset:64
	v_mul_f32_e32 v146, v214, v210
	v_mul_f32_e32 v146, v146, v149
	v_cvt_pk_bf16_f32 v146, v146, s0
	global_store_short v[150:151], v146, off offset:96
	global_load_dwordx4 v[146:149], v[202:203], off offset:144
	v_mul_f32_e32 v155, v213, v210
	s_waitcnt vmcnt(0)
	v_mul_f32_e32 v146, v155, v146
	v_cvt_pk_bf16_f32 v146, v146, s0
	global_store_short v[150:151], v146, off offset:128
	v_mul_f32_e32 v146, v211, v210
	v_mul_f32_e32 v146, v146, v147
	v_cvt_pk_bf16_f32 v146, v146, s0
	global_store_short v[150:151], v146, off offset:160
	v_mul_f32_e32 v146, v209, v210
	v_mul_f32_e32 v146, v146, v148
	v_cvt_pk_bf16_f32 v146, v146, s0
	global_store_short v[150:151], v146, off offset:192
	v_mul_f32_e32 v146, v208, v210
	v_mul_f32_e32 v146, v146, v149
	v_cvt_pk_bf16_f32 v146, v146, s0
	global_store_short v[150:151], v146, off offset:224

.LBB0_315:
	v_readlane_b32 s54, v253, 59
	s_andn2_b64 vcc, exec, s[12:13]
	v_readlane_b32 s55, v253, 60
	s_cbranch_vccnz .LBB0_325
	v_mul_f32_e32 v146, v143, v143
	v_mul_f32_e32 v147, v145, v145
	v_fmac_f32_e32 v146, v142, v142
	v_fmac_f32_e32 v147, v144, v144
	v_add_f32_e32 v146, v146, v147
	v_mul_f32_e32 v147, v139, v139
	v_mul_f32_e32 v148, v141, v141
	v_fmac_f32_e32 v147, v138, v138
	v_fmac_f32_e32 v148, v140, v140
	v_add_f32_e32 v147, v147, v148
	v_add_f32_e32 v146, v146, v147
	v_mul_f32_e32 v147, v135, v135
	v_mul_f32_e32 v148, v137, v137
	v_fmac_f32_e32 v147, v134, v134
	v_fmac_f32_e32 v148, v136, v136
	v_add_f32_e32 v147, v147, v148
	v_add_f32_e32 v146, v147, v146
	v_mul_f32_e32 v147, v131, v131
	v_mul_f32_e32 v148, v133, v133
	v_fmac_f32_e32 v147, v130, v130
	v_fmac_f32_e32 v148, v132, v132
	v_add_f32_e32 v147, v147, v148
	v_add_f32_e32 v146, v147, v146
	v_mov_b32_e32 v147, v146
	s_nop 1
	v_permlane16_swap_b32_e32 v147, v146
	v_readlane_b32 s12, v255, 4
	v_readlane_b32 s13, v255, 5
	s_andn2_b64 vcc, exec, s[12:13]
	s_mov_b64 s[12:13], -1
	s_waitcnt lgkmcnt(0)
	v_add_f32_e32 v146, v146, v147
	v_mov_b32_e32 v147, v146
	s_nop 1
	v_permlane32_swap_b32_e32 v147, v146
	s_cbranch_vccnz .LBB0_318
	v_ashrrev_i32_e32 v155, 31, v154
	v_lshlrev_b64 v[148:149], 7, v[154:155]
	v_lshl_add_u64 v[156:157], v[176:177], 0, v[148:149]
	s_mov_b64 s[12:13], 0

.LBB0_350:
	v_readlane_b32 s64, v254, 33
	v_readlane_b32 s65, v254, 34
	v_readlane_b32 s66, v254, 36
	v_readlane_b32 s67, v254, 37
	s_and_b64 s[64:65], s[64:65], s[66:67]
	s_and_b64 vcc, exec, s[64:65]
	s_cbranch_vccz .Lepr_general
	s_load_dwordx4 s[64:67], s[0:1], 0xb8
	s_lshl_b32 s17, s34, 8
	s_mov_b64 s[52:53], 0x8000
	s_mov_b64 s[14:15], 0x28000
	v_add_u32_e32 v130, s17, v241
	v_ashrrev_i32_e32 v131, 31, v130
	v_lshlrev_b64 v[130:131], 11, v[130:131]
	v_lshl_add_u64 v[130:131], v[220:221], 1, v[130:131]
	s_waitcnt lgkmcnt(0)
	s_add_u32 s54, s66, 0xe800000
	s_addc_u32 s55, s67, 0
	v_lshl_add_u64 v[220:221], v[130:131], 0, s[54:55]
	s_add_u32 s54, s66, 0x6000000
	s_addc_u32 s55, s67, 0
	v_lshl_add_u64 v[218:219], v[130:131], 0, s[54:55]
	v_mov_b32_e32 v216, v220
	v_mov_b32_e32 v217, v221
	global_load_dwordx4 v[154:157], v[220:221], off
	global_load_dwordx4 v[158:161], v[220:221], off offset:256
	v_lshl_add_u64 v[220:221], v[220:221], 0, s[52:53]
	global_load_dwordx4 v[162:165], v[220:221], off
	global_load_dwordx4 v[166:169], v[220:221], off offset:256
	v_lshl_add_u64 v[220:221], v[220:221], 0, s[52:53]
	global_load_dwordx4 v[170:173], v[220:221], off
	global_load_dwordx4 v[174:177], v[220:221], off offset:256
	v_lshl_add_u64 v[220:221], v[220:221], 0, s[52:53]
	global_load_dwordx4 v[130:133], v[220:221], off
	global_load_dwordx4 v[134:137], v[220:221], off offset:256
	v_lshl_add_u64 v[220:221], v[220:221], 0, s[14:15]
	v_pk_mul_f32 v[146:147], v[146:147], v[192:193]
	v_pk_mul_f32 v[148:149], v[148:149], v[192:193]
	v_pk_mul_f32 v[150:151], v[150:151], v[192:193]
	v_pk_mul_f32 v[152:153], v[152:153], v[192:193]
	v_pk_mul_f32 v[138:139], v[138:139], v[192:193]
	v_pk_mul_f32 v[140:141], v[140:141], v[192:193]
	v_pk_mul_f32 v[142:143], v[142:143], v[192:193]
	v_pk_mul_f32 v[144:145], v[144:145], v[192:193]
	s_waitcnt vmcnt(7)
	v_lshlrev_b32_e32 v222, 16, v154
	v_and_b32_e32 v223, 0xffff0000, v154
	v_lshlrev_b32_e32 v224, 16, v156
	v_and_b32_e32 v225, 0xffff0000, v156
	v_lshlrev_b32_e32 v154, 16, v155
	v_and_b32_e32 v155, 0xffff0000, v155
	v_lshlrev_b32_e32 v156, 16, v157
	v_and_b32_e32 v157, 0xffff0000, v157
	v_pk_fma_f32 v[30:31], v[30:31], v[146:147], v[222:223]
	v_pk_fma_f32 v[32:33], v[32:33], v[148:149], v[154:155]
	v_pk_fma_f32 v[26:27], v[26:27], v[150:151], v[224:225]
	v_pk_fma_f32 v[28:29], v[28:29], v[152:153], v[156:157]
	v_cvt_pk_bf16_f32 v222, v30, v31
	v_cvt_pk_bf16_f32 v223, v32, v33
	v_cvt_pk_bf16_f32 v224, v26, v27
	v_cvt_pk_bf16_f32 v225, v28, v29
	global_store_dwordx4 v[216:217], v[222:225], off
	v_pk_mul_f32 v[226:227], v[30:31], v[30:31]
	v_pk_fma_f32 v[226:227], v[32:33], v[32:33], v[226:227]
	v_pk_fma_f32 v[226:227], v[26:27], v[26:27], v[226:227]
	v_pk_fma_f32 v[226:227], v[28:29], v[28:29], v[226:227]
	v_pk_mul_f32 v[30:31], v[30:31], v[208:209]
	v_pk_mul_f32 v[32:33], v[32:33], v[210:211]
	v_pk_mul_f32 v[26:27], v[26:27], v[212:213]
	v_pk_mul_f32 v[28:29], v[28:29], v[214:215]
	v_cvt_pk_bf16_f32 v154, v30, v31
	v_cvt_pk_bf16_f32 v155, v32, v33
	v_cvt_pk_bf16_f32 v156, v26, v27
	v_cvt_pk_bf16_f32 v157, v28, v29
	global_store_dwordx4 v[218:219], v[154:157], off
	s_waitcnt vmcnt(8)
	v_lshlrev_b32_e32 v222, 16, v158
	v_and_b32_e32 v223, 0xffff0000, v158
	v_lshlrev_b32_e32 v224, 16, v160
	v_and_b32_e32 v225, 0xffff0000, v160
	v_lshlrev_b32_e32 v158, 16, v159
	v_and_b32_e32 v159, 0xffff0000, v159
	v_lshlrev_b32_e32 v160, 16, v161
	v_and_b32_e32 v161, 0xffff0000, v161
	v_pk_fma_f32 v[22:23], v[22:23], v[138:139], v[222:223]
	v_pk_fma_f32 v[24:25], v[24:25], v[140:141], v[158:159]
	v_pk_fma_f32 v[14:15], v[14:15], v[142:143], v[224:225]
	v_pk_fma_f32 v[16:17], v[16:17], v[144:145], v[160:161]
	v_cvt_pk_bf16_f32 v222, v22, v23
	v_cvt_pk_bf16_f32 v223, v24, v25
	v_cvt_pk_bf16_f32 v224, v14, v15
	v_cvt_pk_bf16_f32 v225, v16, v17
	global_store_dwordx4 v[216:217], v[222:225], off offset:256
	v_pk_fma_f32 v[226:227], v[22:23], v[22:23], v[226:227]
	v_pk_fma_f32 v[226:227], v[24:25], v[24:25], v[226:227]
	v_pk_fma_f32 v[226:227], v[14:15], v[14:15], v[226:227]
	v_pk_fma_f32 v[226:227], v[16:17], v[16:17], v[226:227]
	v_pk_mul_f32 v[22:23], v[22:23], v[200:201]
	v_pk_mul_f32 v[24:25], v[24:25], v[202:203]
	v_pk_mul_f32 v[14:15], v[14:15], v[204:205]
	v_pk_mul_f32 v[16:17], v[16:17], v[206:207]
	v_cvt_pk_bf16_f32 v158, v22, v23
	v_cvt_pk_bf16_f32 v159, v24, v25
	v_cvt_pk_bf16_f32 v160, v14, v15
	v_cvt_pk_bf16_f32 v161, v16, v17
	global_store_dwordx4 v[218:219], v[158:161], off offset:256
	v_add_f32_e32 v228, v226, v227
	v_lshl_add_u64 v[216:217], v[216:217], 0, s[52:53]
	v_lshl_add_u64 v[218:219], v[218:219], 0, s[52:53]
	global_load_dwordx4 v[154:157], v[220:221], off
	global_load_dwordx4 v[158:161], v[220:221], off offset:256
	v_lshl_add_u64 v[220:221], v[220:221], 0, s[52:53]
	s_waitcnt vmcnt(11)
	v_lshlrev_b32_e32 v222, 16, v162
	v_and_b32_e32 v223, 0xffff0000, v162
	v_lshlrev_b32_e32 v224, 16, v164
	v_and_b32_e32 v225, 0xffff0000, v164
	v_lshlrev_b32_e32 v162, 16, v163
	v_and_b32_e32 v163, 0xffff0000, v163
	v_lshlrev_b32_e32 v164, 16, v165
	v_and_b32_e32 v165, 0xffff0000, v165
	v_pk_fma_f32 v[18:19], v[18:19], v[146:147], v[222:223]
	v_pk_fma_f32 v[20:21], v[20:21], v[148:149], v[162:163]
	v_pk_fma_f32 v[10:11], v[10:11], v[150:151], v[224:225]
	v_pk_fma_f32 v[12:13], v[12:13], v[152:153], v[164:165]
	v_cvt_pk_bf16_f32 v222, v18, v19
	v_cvt_pk_bf16_f32 v223, v20, v21
	v_cvt_pk_bf16_f32 v224, v10, v11
	v_cvt_pk_bf16_f32 v225, v12, v13
	global_store_dwordx4 v[216:217], v[222:225], off
	v_pk_mul_f32 v[226:227], v[18:19], v[18:19]
	v_pk_fma_f32 v[226:227], v[20:21], v[20:21], v[226:227]
	v_pk_fma_f32 v[226:227], v[10:11], v[10:11], v[226:227]
	v_pk_fma_f32 v[226:227], v[12:13], v[12:13], v[226:227]
	v_pk_mul_f32 v[18:19], v[18:19], v[208:209]
	v_pk_mul_f32 v[20:21], v[20:21], v[210:211]
	v_pk_mul_f32 v[10:11], v[10:11], v[212:213]
	v_pk_mul_f32 v[12:13], v[12:13], v[214:215]
	v_cvt_pk_bf16_f32 v162, v18, v19
	v_cvt_pk_bf16_f32 v163, v20, v21
	v_cvt_pk_bf16_f32 v164, v10, v11
	v_cvt_pk_bf16_f32 v165, v12, v13
	global_store_dwordx4 v[218:219], v[162:165], off
	s_waitcnt vmcnt(12)
	v_lshlrev_b32_e32 v222, 16, v166
	v_and_b32_e32 v223, 0xffff0000, v166
	v_lshlrev_b32_e32 v224, 16, v168
	v_and_b32_e32 v225, 0xffff0000, v168
	v_lshlrev_b32_e32 v166, 16, v167
	v_and_b32_e32 v167, 0xffff0000, v167
	v_lshlrev_b32_e32 v168, 16, v169
	v_and_b32_e32 v169, 0xffff0000, v169
	v_pk_fma_f32 v[6:7], v[6:7], v[138:139], v[222:223]
	v_pk_fma_f32 v[8:9], v[8:9], v[140:141], v[166:167]
	v_pk_fma_f32 v[2:3], v[2:3], v[142:143], v[224:225]
	v_pk_fma_f32 v[4:5], v[4:5], v[144:145], v[168:169]
	v_cvt_pk_bf16_f32 v222, v6, v7
	v_cvt_pk_bf16_f32 v223, v8, v9
	v_cvt_pk_bf16_f32 v224, v2, v3
	v_cvt_pk_bf16_f32 v225, v4, v5
	global_store_dwordx4 v[216:217], v[222:225], off offset:256
	v_pk_fma_f32 v[226:227], v[6:7], v[6:7], v[226:227]
	v_pk_fma_f32 v[226:227], v[8:9], v[8:9], v[226:227]
	v_pk_fma_f32 v[226:227], v[2:3], v[2:3], v[226:227]
	v_pk_fma_f32 v[226:227], v[4:5], v[4:5], v[226:227]
	v_pk_mul_f32 v[6:7], v[6:7], v[200:201]
	v_pk_mul_f32 v[8:9], v[8:9], v[202:203]
	v_pk_mul_f32 v[2:3], v[2:3], v[204:205]
	v_pk_mul_f32 v[4:5], v[4:5], v[206:207]
	v_cvt_pk_bf16_f32 v166, v6, v7
	v_cvt_pk_bf16_f32 v167, v8, v9
	v_cvt_pk_bf16_f32 v168, v2, v3
	v_cvt_pk_bf16_f32 v169, v4, v5
	global_store_dwordx4 v[218:219], v[166:169], off offset:256
	v_add_f32_e32 v229, v226, v227
	v_lshl_add_u64 v[216:217], v[216:217], 0, s[52:53]
	v_lshl_add_u64 v[218:219], v[218:219], 0, s[52:53]
	global_load_dwordx4 v[162:165], v[220:221], off
	global_load_dwordx4 v[166:169], v[220:221], off offset:256
	v_lshl_add_u64 v[220:221], v[220:221], 0, s[52:53]
	s_waitcnt vmcnt(15)
	v_lshlrev_b32_e32 v222, 16, v170
	v_and_b32_e32 v223, 0xffff0000, v170
	v_lshlrev_b32_e32 v224, 16, v172
	v_and_b32_e32 v225, 0xffff0000, v172
	v_lshlrev_b32_e32 v170, 16, v171
	v_and_b32_e32 v171, 0xffff0000, v171
	v_lshlrev_b32_e32 v172, 16, v173
	v_and_b32_e32 v173, 0xffff0000, v173
	v_pk_fma_f32 v[126:127], v[126:127], v[146:147], v[222:223]
	v_pk_fma_f32 v[128:129], v[128:129], v[148:149], v[170:171]
	v_pk_fma_f32 v[122:123], v[122:123], v[150:151], v[224:225]
	v_pk_fma_f32 v[124:125], v[124:125], v[152:153], v[172:173]
	v_cvt_pk_bf16_f32 v222, v126, v127
	v_cvt_pk_bf16_f32 v223, v128, v129
	v_cvt_pk_bf16_f32 v224, v122, v123
	v_cvt_pk_bf16_f32 v225, v124, v125
	global_store_dwordx4 v[216:217], v[222:225], off
	v_pk_mul_f32 v[226:227], v[126:127], v[126:127]
	v_pk_fma_f32 v[226:227], v[128:129], v[128:129], v[226:227]
	v_pk_fma_f32 v[226:227], v[122:123], v[122:123], v[226:227]
	v_pk_fma_f32 v[226:227], v[124:125], v[124:125], v[226:227]
	v_pk_mul_f32 v[126:127], v[126:127], v[208:209]
	v_pk_mul_f32 v[128:129], v[128:129], v[210:211]
	v_pk_mul_f32 v[122:123], v[122:123], v[212:213]
	v_pk_mul_f32 v[124:125], v[124:125], v[214:215]
	v_cvt_pk_bf16_f32 v170, v126, v127
	v_cvt_pk_bf16_f32 v171, v128, v129
	v_cvt_pk_bf16_f32 v172, v122, v123
	v_cvt_pk_bf16_f32 v173, v124, v125
	global_store_dwordx4 v[218:219], v[170:173], off
	s_waitcnt vmcnt(16)
	v_lshlrev_b32_e32 v222, 16, v174
	v_and_b32_e32 v223, 0xffff0000, v174
	v_lshlrev_b32_e32 v224, 16, v176
	v_and_b32_e32 v225, 0xffff0000, v176
	v_lshlrev_b32_e32 v174, 16, v175
	v_and_b32_e32 v175, 0xffff0000, v175
	v_lshlrev_b32_e32 v176, 16, v177
	v_and_b32_e32 v177, 0xffff0000, v177
	v_pk_fma_f32 v[118:119], v[118:119], v[138:139], v[222:223]
	v_pk_fma_f32 v[120:121], v[120:121], v[140:141], v[174:175]
	v_pk_fma_f32 v[114:115], v[114:115], v[142:143], v[224:225]
	v_pk_fma_f32 v[116:117], v[116:117], v[144:145], v[176:177]
	v_cvt_pk_bf16_f32 v222, v118, v119
	v_cvt_pk_bf16_f32 v223, v120, v121
	v_cvt_pk_bf16_f32 v224, v114, v115
	v_cvt_pk_bf16_f32 v225, v116, v117
	global_store_dwordx4 v[216:217], v[222:225], off offset:256
	v_pk_fma_f32 v[226:227], v[118:119], v[118:119], v[226:227]
	v_pk_fma_f32 v[226:227], v[120:121], v[120:121], v[226:227]
	v_pk_fma_f32 v[226:227], v[114:115], v[114:115], v[226:227]
	v_pk_fma_f32 v[226:227], v[116:117], v[116:117], v[226:227]
	v_pk_mul_f32 v[118:119], v[118:119], v[200:201]
	v_pk_mul_f32 v[120:121], v[120:121], v[202:203]
	v_pk_mul_f32 v[114:115], v[114:115], v[204:205]
	v_pk_mul_f32 v[116:117], v[116:117], v[206:207]
	v_cvt_pk_bf16_f32 v174, v118, v119
	v_cvt_pk_bf16_f32 v175, v120, v121
	v_cvt_pk_bf16_f32 v176, v114, v115
	v_cvt_pk_bf16_f32 v177, v116, v117
	global_store_dwordx4 v[218:219], v[174:177], off offset:256
	v_add_f32_e32 v22, v226, v227
	v_lshl_add_u64 v[216:217], v[216:217], 0, s[52:53]
	v_lshl_add_u64 v[218:219], v[218:219], 0, s[52:53]
	global_load_dwordx4 v[170:173], v[220:221], off
	global_load_dwordx4 v[174:177], v[220:221], off offset:256
	v_lshl_add_u64 v[220:221], v[220:221], 0, s[52:53]
	s_waitcnt vmcnt(19)
	v_lshlrev_b32_e32 v222, 16, v130
	v_and_b32_e32 v223, 0xffff0000, v130
	v_lshlrev_b32_e32 v224, 16, v132
	v_and_b32_e32 v225, 0xffff0000, v132
	v_lshlrev_b32_e32 v130, 16, v131
	v_and_b32_e32 v131, 0xffff0000, v131
	v_lshlrev_b32_e32 v132, 16, v133
	v_and_b32_e32 v133, 0xffff0000, v133
	v_pk_fma_f32 v[110:111], v[110:111], v[146:147], v[222:223]
	v_pk_fma_f32 v[112:113], v[112:113], v[148:149], v[130:131]
	v_pk_fma_f32 v[106:107], v[106:107], v[150:151], v[224:225]
	v_pk_fma_f32 v[108:109], v[108:109], v[152:153], v[132:133]
	v_cvt_pk_bf16_f32 v222, v110, v111
	v_cvt_pk_bf16_f32 v223, v112, v113
	v_cvt_pk_bf16_f32 v224, v106, v107
	v_cvt_pk_bf16_f32 v225, v108, v109
	global_store_dwordx4 v[216:217], v[222:225], off
	v_pk_mul_f32 v[226:227], v[110:111], v[110:111]
	v_pk_fma_f32 v[226:227], v[112:113], v[112:113], v[226:227]
	v_pk_fma_f32 v[226:227], v[106:107], v[106:107], v[226:227]
	v_pk_fma_f32 v[226:227], v[108:109], v[108:109], v[226:227]
	v_pk_mul_f32 v[110:111], v[110:111], v[208:209]
	v_pk_mul_f32 v[112:113], v[112:113], v[210:211]
	v_pk_mul_f32 v[106:107], v[106:107], v[212:213]
	v_pk_mul_f32 v[108:109], v[108:109], v[214:215]
	v_cvt_pk_bf16_f32 v130, v110, v111
	v_cvt_pk_bf16_f32 v131, v112, v113
	v_cvt_pk_bf16_f32 v132, v106, v107
	v_cvt_pk_bf16_f32 v133, v108, v109
	global_store_dwordx4 v[218:219], v[130:133], off
	s_waitcnt vmcnt(20)
	v_lshlrev_b32_e32 v222, 16, v134
	v_and_b32_e32 v223, 0xffff0000, v134
	v_lshlrev_b32_e32 v224, 16, v136
	v_and_b32_e32 v225, 0xffff0000, v136
	v_lshlrev_b32_e32 v134, 16, v135
	v_and_b32_e32 v135, 0xffff0000, v135
	v_lshlrev_b32_e32 v136, 16, v137
	v_and_b32_e32 v137, 0xffff0000, v137
	v_pk_fma_f32 v[102:103], v[102:103], v[138:139], v[222:223]
	v_pk_fma_f32 v[104:105], v[104:105], v[140:141], v[134:135]
	v_pk_fma_f32 v[98:99], v[98:99], v[142:143], v[224:225]
	v_pk_fma_f32 v[100:101], v[100:101], v[144:145], v[136:137]
	v_cvt_pk_bf16_f32 v222, v102, v103
	v_cvt_pk_bf16_f32 v223, v104, v105
	v_cvt_pk_bf16_f32 v224, v98, v99
	v_cvt_pk_bf16_f32 v225, v100, v101
	global_store_dwordx4 v[216:217], v[222:225], off offset:256
	v_pk_fma_f32 v[226:227], v[102:103], v[102:103], v[226:227]
	v_pk_fma_f32 v[226:227], v[104:105], v[104:105], v[226:227]
	v_pk_fma_f32 v[226:227], v[98:99], v[98:99], v[226:227]
	v_pk_fma_f32 v[226:227], v[100:101], v[100:101], v[226:227]
	v_pk_mul_f32 v[102:103], v[102:103], v[200:201]
	v_pk_mul_f32 v[104:105], v[104:105], v[202:203]
	v_pk_mul_f32 v[98:99], v[98:99], v[204:205]
	v_pk_mul_f32 v[100:101], v[100:101], v[206:207]
	v_cvt_pk_bf16_f32 v134, v102, v103
	v_cvt_pk_bf16_f32 v135, v104, v105
	v_cvt_pk_bf16_f32 v136, v98, v99
	v_cvt_pk_bf16_f32 v137, v100, v101
	global_store_dwordx4 v[218:219], v[134:137], off offset:256
	v_add_f32_e32 v23, v226, v227
	v_lshl_add_u64 v[216:217], v[216:217], 0, s[14:15]
	v_lshl_add_u64 v[218:219], v[218:219], 0, s[14:15]
	global_load_dwordx4 v[130:133], v[220:221], off
	global_load_dwordx4 v[134:137], v[220:221], off offset:256
	s_waitcnt vmcnt(19)
	v_lshlrev_b32_e32 v222, 16, v154
	v_and_b32_e32 v223, 0xffff0000, v154
	v_lshlrev_b32_e32 v224, 16, v156
	v_and_b32_e32 v225, 0xffff0000, v156
	v_lshlrev_b32_e32 v154, 16, v155
	v_and_b32_e32 v155, 0xffff0000, v155
	v_lshlrev_b32_e32 v156, 16, v157
	v_and_b32_e32 v157, 0xffff0000, v157
	v_pk_fma_f32 v[94:95], v[94:95], v[146:147], v[222:223]
	v_pk_fma_f32 v[96:97], v[96:97], v[148:149], v[154:155]
	v_pk_fma_f32 v[90:91], v[90:91], v[150:151], v[224:225]
	v_pk_fma_f32 v[92:93], v[92:93], v[152:153], v[156:157]
	v_cvt_pk_bf16_f32 v222, v94, v95
	v_cvt_pk_bf16_f32 v223, v96, v97
	v_cvt_pk_bf16_f32 v224, v90, v91
	v_cvt_pk_bf16_f32 v225, v92, v93
	global_store_dwordx4 v[216:217], v[222:225], off
	v_pk_mul_f32 v[226:227], v[94:95], v[94:95]
	v_pk_fma_f32 v[226:227], v[96:97], v[96:97], v[226:227]
	v_pk_fma_f32 v[226:227], v[90:91], v[90:91], v[226:227]
	v_pk_fma_f32 v[226:227], v[92:93], v[92:93], v[226:227]
	v_pk_mul_f32 v[94:95], v[94:95], v[208:209]
	v_pk_mul_f32 v[96:97], v[96:97], v[210:211]
	v_pk_mul_f32 v[90:91], v[90:91], v[212:213]
	v_pk_mul_f32 v[92:93], v[92:93], v[214:215]
	v_cvt_pk_bf16_f32 v154, v94, v95
	v_cvt_pk_bf16_f32 v155, v96, v97
	v_cvt_pk_bf16_f32 v156, v90, v91
	v_cvt_pk_bf16_f32 v157, v92, v93
	global_store_dwordx4 v[218:219], v[154:157], off
	s_waitcnt vmcnt(20)
	v_lshlrev_b32_e32 v222, 16, v158
	v_and_b32_e32 v223, 0xffff0000, v158
	v_lshlrev_b32_e32 v224, 16, v160
	v_and_b32_e32 v225, 0xffff0000, v160
	v_lshlrev_b32_e32 v158, 16, v159
	v_and_b32_e32 v159, 0xffff0000, v159
	v_lshlrev_b32_e32 v160, 16, v161
	v_and_b32_e32 v161, 0xffff0000, v161
	v_pk_fma_f32 v[86:87], v[86:87], v[138:139], v[222:223]
	v_pk_fma_f32 v[88:89], v[88:89], v[140:141], v[158:159]
	v_pk_fma_f32 v[82:83], v[82:83], v[142:143], v[224:225]
	v_pk_fma_f32 v[84:85], v[84:85], v[144:145], v[160:161]
	v_cvt_pk_bf16_f32 v222, v86, v87
	v_cvt_pk_bf16_f32 v223, v88, v89
	v_cvt_pk_bf16_f32 v224, v82, v83
	v_cvt_pk_bf16_f32 v225, v84, v85
	global_store_dwordx4 v[216:217], v[222:225], off offset:256
	v_pk_fma_f32 v[226:227], v[86:87], v[86:87], v[226:227]
	v_pk_fma_f32 v[226:227], v[88:89], v[88:89], v[226:227]
	v_pk_fma_f32 v[226:227], v[82:83], v[82:83], v[226:227]
	v_pk_fma_f32 v[226:227], v[84:85], v[84:85], v[226:227]
	v_pk_mul_f32 v[86:87], v[86:87], v[200:201]
	v_pk_mul_f32 v[88:89], v[88:89], v[202:203]
	v_pk_mul_f32 v[82:83], v[82:83], v[204:205]
	v_pk_mul_f32 v[84:85], v[84:85], v[206:207]
	v_cvt_pk_bf16_f32 v158, v86, v87
	v_cvt_pk_bf16_f32 v159, v88, v89
	v_cvt_pk_bf16_f32 v160, v82, v83
	v_cvt_pk_bf16_f32 v161, v84, v85
	global_store_dwordx4 v[218:219], v[158:161], off offset:256
	v_add_f32_e32 v24, v226, v227
	v_lshl_add_u64 v[216:217], v[216:217], 0, s[52:53]
	v_lshl_add_u64 v[218:219], v[218:219], 0, s[52:53]
	s_waitcnt vmcnt(17)
	v_lshlrev_b32_e32 v222, 16, v162
	v_and_b32_e32 v223, 0xffff0000, v162
	v_lshlrev_b32_e32 v224, 16, v164
	v_and_b32_e32 v225, 0xffff0000, v164
	v_lshlrev_b32_e32 v162, 16, v163
	v_and_b32_e32 v163, 0xffff0000, v163
	v_lshlrev_b32_e32 v164, 16, v165
	v_and_b32_e32 v165, 0xffff0000, v165
	v_pk_fma_f32 v[78:79], v[78:79], v[146:147], v[222:223]
	v_pk_fma_f32 v[80:81], v[80:81], v[148:149], v[162:163]
	v_pk_fma_f32 v[74:75], v[74:75], v[150:151], v[224:225]
	v_pk_fma_f32 v[76:77], v[76:77], v[152:153], v[164:165]
	v_cvt_pk_bf16_f32 v222, v78, v79
	v_cvt_pk_bf16_f32 v223, v80, v81
	v_cvt_pk_bf16_f32 v224, v74, v75
	v_cvt_pk_bf16_f32 v225, v76, v77
	global_store_dwordx4 v[216:217], v[222:225], off
	v_pk_mul_f32 v[226:227], v[78:79], v[78:79]
	v_pk_fma_f32 v[226:227], v[80:81], v[80:81], v[226:227]
	v_pk_fma_f32 v[226:227], v[74:75], v[74:75], v[226:227]
	v_pk_fma_f32 v[226:227], v[76:77], v[76:77], v[226:227]
	v_pk_mul_f32 v[78:79], v[78:79], v[208:209]
	v_pk_mul_f32 v[80:81], v[80:81], v[210:211]
	v_pk_mul_f32 v[74:75], v[74:75], v[212:213]
	v_pk_mul_f32 v[76:77], v[76:77], v[214:215]
	v_cvt_pk_bf16_f32 v162, v78, v79
	v_cvt_pk_bf16_f32 v163, v80, v81
	v_cvt_pk_bf16_f32 v164, v74, v75
	v_cvt_pk_bf16_f32 v165, v76, v77
	global_store_dwordx4 v[218:219], v[162:165], off
	s_waitcnt vmcnt(18)
	v_lshlrev_b32_e32 v222, 16, v166
	v_and_b32_e32 v223, 0xffff0000, v166
	v_lshlrev_b32_e32 v224, 16, v168
	v_and_b32_e32 v225, 0xffff0000, v168
	v_lshlrev_b32_e32 v166, 16, v167
	v_and_b32_e32 v167, 0xffff0000, v167
	v_lshlrev_b32_e32 v168, 16, v169
	v_and_b32_e32 v169, 0xffff0000, v169
	v_pk_fma_f32 v[70:71], v[70:71], v[138:139], v[222:223]
	v_pk_fma_f32 v[72:73], v[72:73], v[140:141], v[166:167]
	v_pk_fma_f32 v[66:67], v[66:67], v[142:143], v[224:225]
	v_pk_fma_f32 v[68:69], v[68:69], v[144:145], v[168:169]
	v_cvt_pk_bf16_f32 v222, v70, v71
	v_cvt_pk_bf16_f32 v223, v72, v73
	v_cvt_pk_bf16_f32 v224, v66, v67
	v_cvt_pk_bf16_f32 v225, v68, v69
	global_store_dwordx4 v[216:217], v[222:225], off offset:256
	v_pk_fma_f32 v[226:227], v[70:71], v[70:71], v[226:227]
	v_pk_fma_f32 v[226:227], v[72:73], v[72:73], v[226:227]
	v_pk_fma_f32 v[226:227], v[66:67], v[66:67], v[226:227]
	v_pk_fma_f32 v[226:227], v[68:69], v[68:69], v[226:227]
	v_pk_mul_f32 v[70:71], v[70:71], v[200:201]
	v_pk_mul_f32 v[72:73], v[72:73], v[202:203]
	v_pk_mul_f32 v[66:67], v[66:67], v[204:205]
	v_pk_mul_f32 v[68:69], v[68:69], v[206:207]
	v_cvt_pk_bf16_f32 v166, v70, v71
	v_cvt_pk_bf16_f32 v167, v72, v73
	v_cvt_pk_bf16_f32 v168, v66, v67
	v_cvt_pk_bf16_f32 v169, v68, v69
	global_store_dwordx4 v[218:219], v[166:169], off offset:256
	v_add_f32_e32 v25, v226, v227
	v_lshl_add_u64 v[216:217], v[216:217], 0, s[52:53]
	v_lshl_add_u64 v[218:219], v[218:219], 0, s[52:53]
	s_waitcnt vmcnt(15)
	v_lshlrev_b32_e32 v222, 16, v170
	v_and_b32_e32 v223, 0xffff0000, v170
	v_lshlrev_b32_e32 v224, 16, v172
	v_and_b32_e32 v225, 0xffff0000, v172
	v_lshlrev_b32_e32 v170, 16, v171
	v_and_b32_e32 v171, 0xffff0000, v171
	v_lshlrev_b32_e32 v172, 16, v173
	v_and_b32_e32 v173, 0xffff0000, v173
	v_pk_fma_f32 v[62:63], v[62:63], v[146:147], v[222:223]
	v_pk_fma_f32 v[64:65], v[64:65], v[148:149], v[170:171]
	v_pk_fma_f32 v[58:59], v[58:59], v[150:151], v[224:225]
	v_pk_fma_f32 v[60:61], v[60:61], v[152:153], v[172:173]
	v_cvt_pk_bf16_f32 v222, v62, v63
	v_cvt_pk_bf16_f32 v223, v64, v65
	v_cvt_pk_bf16_f32 v224, v58, v59
	v_cvt_pk_bf16_f32 v225, v60, v61
	global_store_dwordx4 v[216:217], v[222:225], off
	v_pk_mul_f32 v[226:227], v[62:63], v[62:63]
	v_pk_fma_f32 v[226:227], v[64:65], v[64:65], v[226:227]
	v_pk_fma_f32 v[226:227], v[58:59], v[58:59], v[226:227]
	v_pk_fma_f32 v[226:227], v[60:61], v[60:61], v[226:227]
	v_pk_mul_f32 v[62:63], v[62:63], v[208:209]
	v_pk_mul_f32 v[64:65], v[64:65], v[210:211]
	v_pk_mul_f32 v[58:59], v[58:59], v[212:213]
	v_pk_mul_f32 v[60:61], v[60:61], v[214:215]
	v_cvt_pk_bf16_f32 v170, v62, v63
	v_cvt_pk_bf16_f32 v171, v64, v65
	v_cvt_pk_bf16_f32 v172, v58, v59
	v_cvt_pk_bf16_f32 v173, v60, v61
	global_store_dwordx4 v[218:219], v[170:173], off
	s_waitcnt vmcnt(16)
	v_lshlrev_b32_e32 v222, 16, v174
	v_and_b32_e32 v223, 0xffff0000, v174
	v_lshlrev_b32_e32 v224, 16, v176
	v_and_b32_e32 v225, 0xffff0000, v176
	v_lshlrev_b32_e32 v174, 16, v175
	v_and_b32_e32 v175, 0xffff0000, v175
	v_lshlrev_b32_e32 v176, 16, v177
	v_and_b32_e32 v177, 0xffff0000, v177
	v_pk_fma_f32 v[54:55], v[54:55], v[138:139], v[222:223]
	v_pk_fma_f32 v[56:57], v[56:57], v[140:141], v[174:175]
	v_pk_fma_f32 v[50:51], v[50:51], v[142:143], v[224:225]
	v_pk_fma_f32 v[52:53], v[52:53], v[144:145], v[176:177]
	v_cvt_pk_bf16_f32 v222, v54, v55
	v_cvt_pk_bf16_f32 v223, v56, v57
	v_cvt_pk_bf16_f32 v224, v50, v51
	v_cvt_pk_bf16_f32 v225, v52, v53
	global_store_dwordx4 v[216:217], v[222:225], off offset:256
	v_pk_fma_f32 v[226:227], v[54:55], v[54:55], v[226:227]
	v_pk_fma_f32 v[226:227], v[56:57], v[56:57], v[226:227]
	v_pk_fma_f32 v[226:227], v[50:51], v[50:51], v[226:227]
	v_pk_fma_f32 v[226:227], v[52:53], v[52:53], v[226:227]
	v_pk_mul_f32 v[54:55], v[54:55], v[200:201]
	v_pk_mul_f32 v[56:57], v[56:57], v[202:203]
	v_pk_mul_f32 v[50:51], v[50:51], v[204:205]
	v_pk_mul_f32 v[52:53], v[52:53], v[206:207]
	v_cvt_pk_bf16_f32 v174, v54, v55
	v_cvt_pk_bf16_f32 v175, v56, v57
	v_cvt_pk_bf16_f32 v176, v50, v51
	v_cvt_pk_bf16_f32 v177, v52, v53
	global_store_dwordx4 v[218:219], v[174:177], off offset:256
	v_add_f32_e32 v26, v226, v227
	v_lshl_add_u64 v[216:217], v[216:217], 0, s[52:53]
	v_lshl_add_u64 v[218:219], v[218:219], 0, s[52:53]
	s_waitcnt vmcnt(13)
	v_lshlrev_b32_e32 v222, 16, v130
	v_and_b32_e32 v223, 0xffff0000, v130
	v_lshlrev_b32_e32 v224, 16, v132
	v_and_b32_e32 v225, 0xffff0000, v132
	v_lshlrev_b32_e32 v130, 16, v131
	v_and_b32_e32 v131, 0xffff0000, v131
	v_lshlrev_b32_e32 v132, 16, v133
	v_and_b32_e32 v133, 0xffff0000, v133
	v_pk_fma_f32 v[46:47], v[46:47], v[146:147], v[222:223]
	v_pk_fma_f32 v[48:49], v[48:49], v[148:149], v[130:131]
	v_pk_fma_f32 v[42:43], v[42:43], v[150:151], v[224:225]
	v_pk_fma_f32 v[44:45], v[44:45], v[152:153], v[132:133]
	v_cvt_pk_bf16_f32 v222, v46, v47
	v_cvt_pk_bf16_f32 v223, v48, v49
	v_cvt_pk_bf16_f32 v224, v42, v43
	v_cvt_pk_bf16_f32 v225, v44, v45
	global_store_dwordx4 v[216:217], v[222:225], off
	v_pk_mul_f32 v[226:227], v[46:47], v[46:47]
	v_pk_fma_f32 v[226:227], v[48:49], v[48:49], v[226:227]
	v_pk_fma_f32 v[226:227], v[42:43], v[42:43], v[226:227]
	v_pk_fma_f32 v[226:227], v[44:45], v[44:45], v[226:227]
	v_pk_mul_f32 v[46:47], v[46:47], v[208:209]
	v_pk_mul_f32 v[48:49], v[48:49], v[210:211]
	v_pk_mul_f32 v[42:43], v[42:43], v[212:213]
	v_pk_mul_f32 v[44:45], v[44:45], v[214:215]
	v_cvt_pk_bf16_f32 v130, v46, v47
	v_cvt_pk_bf16_f32 v131, v48, v49
	v_cvt_pk_bf16_f32 v132, v42, v43
	v_cvt_pk_bf16_f32 v133, v44, v45
	global_store_dwordx4 v[218:219], v[130:133], off
	s_waitcnt vmcnt(14)
	v_lshlrev_b32_e32 v222, 16, v134
	v_and_b32_e32 v223, 0xffff0000, v134
	v_lshlrev_b32_e32 v224, 16, v136
	v_and_b32_e32 v225, 0xffff0000, v136
	v_lshlrev_b32_e32 v134, 16, v135
	v_and_b32_e32 v135, 0xffff0000, v135
	v_lshlrev_b32_e32 v136, 16, v137
	v_and_b32_e32 v137, 0xffff0000, v137
	v_pk_fma_f32 v[38:39], v[38:39], v[138:139], v[222:223]
	v_pk_fma_f32 v[40:41], v[40:41], v[140:141], v[134:135]
	v_pk_fma_f32 v[34:35], v[34:35], v[142:143], v[224:225]
	v_pk_fma_f32 v[36:37], v[36:37], v[144:145], v[136:137]
	v_cvt_pk_bf16_f32 v222, v38, v39
	v_cvt_pk_bf16_f32 v223, v40, v41
	v_cvt_pk_bf16_f32 v224, v34, v35
	v_cvt_pk_bf16_f32 v225, v36, v37
	global_store_dwordx4 v[216:217], v[222:225], off offset:256
	v_pk_fma_f32 v[226:227], v[38:39], v[38:39], v[226:227]
	v_pk_fma_f32 v[226:227], v[40:41], v[40:41], v[226:227]
	v_pk_fma_f32 v[226:227], v[34:35], v[34:35], v[226:227]
	v_pk_fma_f32 v[226:227], v[36:37], v[36:37], v[226:227]
	v_pk_mul_f32 v[38:39], v[38:39], v[200:201]
	v_pk_mul_f32 v[40:41], v[40:41], v[202:203]
	v_pk_mul_f32 v[34:35], v[34:35], v[204:205]
	v_pk_mul_f32 v[36:37], v[36:37], v[206:207]
	v_cvt_pk_bf16_f32 v134, v38, v39
	v_cvt_pk_bf16_f32 v135, v40, v41
	v_cvt_pk_bf16_f32 v136, v34, v35
	v_cvt_pk_bf16_f32 v137, v36, v37
	global_store_dwordx4 v[218:219], v[134:137], off offset:256
	v_add_f32_e32 v27, v226, v227
	v_mov_b32_e32 v28, v228
	s_nop 1
	v_permlane16_swap_b32_e32 v28, v228
	v_mov_b32_e32 v29, v229
	s_nop 1
	v_permlane16_swap_b32_e32 v29, v229
	v_mov_b32_e32 v30, v22
	s_nop 1
	v_permlane16_swap_b32_e32 v30, v22
	v_mov_b32_e32 v31, v23
	s_nop 1
	v_permlane16_swap_b32_e32 v31, v23
	v_mov_b32_e32 v32, v24
	s_nop 1
	v_permlane16_swap_b32_e32 v32, v24
	v_mov_b32_e32 v33, v25
	s_nop 1
	v_permlane16_swap_b32_e32 v33, v25
	v_mov_b32_e32 v14, v26
	s_nop 1
	v_permlane16_swap_b32_e32 v14, v26
	v_mov_b32_e32 v15, v27
	s_nop 1
	v_permlane16_swap_b32_e32 v15, v27
	v_readlane_b32 s12, v254, 44
	s_waitcnt lgkmcnt(0)
	v_add_f32_e32 v228, v228, v28
	v_add_f32_e32 v229, v229, v29
	v_add_f32_e32 v22, v22, v30
	v_add_f32_e32 v23, v23, v31
	v_add_f32_e32 v24, v24, v32
	v_add_f32_e32 v25, v25, v33
	v_add_f32_e32 v26, v26, v14
	v_add_f32_e32 v27, v27, v15
	v_mov_b32_e32 v28, v228
	s_nop 1
	v_permlane32_swap_b32_e32 v28, v228
	v_mov_b32_e32 v29, v229
	s_nop 1
	v_permlane32_swap_b32_e32 v29, v229
	v_mov_b32_e32 v30, v22
	s_nop 1
	v_permlane32_swap_b32_e32 v30, v22
	v_mov_b32_e32 v31, v23
	s_nop 1
	v_permlane32_swap_b32_e32 v31, v23
	v_mov_b32_e32 v32, v24
	s_nop 1
	v_permlane32_swap_b32_e32 v32, v24
	v_mov_b32_e32 v33, v25
	s_nop 1
	v_permlane32_swap_b32_e32 v33, v25
	v_mov_b32_e32 v14, v26
	s_nop 1
	v_permlane32_swap_b32_e32 v14, v26
	v_mov_b32_e32 v15, v27
	s_nop 1
	v_permlane32_swap_b32_e32 v15, v27
	v_lshl_add_u32 v0, v241, 4, s12
	s_waitcnt lgkmcnt(0)
	v_add_f32_e32 v228, v228, v28
	v_add_f32_e32 v229, v229, v29
	v_add_f32_e32 v22, v22, v30
	v_add_f32_e32 v23, v23, v31
	v_add_f32_e32 v24, v24, v32
	v_add_f32_e32 v25, v25, v33
	v_add_f32_e32 v26, v26, v14
	v_add_f32_e32 v27, v27, v15
	s_and_saveexec_b64 s[10:11], s[88:89]
	ds_write_b32 v0, v228
	ds_write_b32 v0, v229 offset:256
	ds_write_b32 v0, v22 offset:512
	ds_write_b32 v0, v23 offset:768
	ds_write_b32 v0, v24 offset:2048
	ds_write_b32 v0, v25 offset:2304
	ds_write_b32 v0, v26 offset:2560
	ds_write_b32 v0, v27 offset:2816
	v_readlane_b32 s72, v253, 57
	v_readlane_b32 s73, v253, 58
	v_readlane_b32 s80, v254, 51
	v_readlane_b32 s81, v254, 52
	v_readlane_b32 s66, v254, 58
	v_readlane_b32 s67, v254, 59
	v_readlane_b32 s54, v253, 59
	v_readlane_b32 s55, v253, 60
	s_branch .LBB0_503

.LBB0_368:
	v_mul_f32_e32 v146, v139, v139
	v_mul_f32_e32 v147, v141, v141
	v_fmac_f32_e32 v146, v138, v138
	v_fmac_f32_e32 v147, v140, v140
	v_add_f32_e32 v146, v146, v147
	v_mul_f32_e32 v147, v143, v143
	v_mul_f32_e32 v148, v145, v145
	v_fmac_f32_e32 v147, v142, v142
	v_fmac_f32_e32 v148, v144, v144
	v_add_f32_e32 v147, v147, v148
	v_add_f32_e32 v146, v147, v146
	v_add_f32_e32 v148, v146, v187
	v_pk_mul_f32 v[146:147], v[202:203], v[140:141]
	v_mov_b32_e32 v141, v148
	s_nop 1
	v_permlane16_swap_b32_e32 v141, v148
	v_pk_mul_f32 v[138:139], v[200:201], v[138:139]
	v_pk_mul_f32 v[144:145], v[206:207], v[144:145]
	v_cvt_pk_bf16_f32 v140, v138, v139
	v_pk_mul_f32 v[142:143], v[204:205], v[142:143]
	s_waitcnt lgkmcnt(0)
	v_add_f32_e32 v138, v148, v141
	v_mov_b32_e32 v139, v138
	s_nop 1
	v_permlane32_swap_b32_e32 v139, v138
	v_cvt_pk_bf16_f32 v141, v146, v147
	v_cvt_pk_bf16_f32 v142, v142, v143
	v_cvt_pk_bf16_f32 v143, v144, v145
	global_store_dwordx4 v[226:227], v[140:143], off offset:256
	s_and_saveexec_b64 s[52:53], s[88:89]
	s_cbranch_execz .LBB0_370
	v_readlane_b32 s55, v254, 44
	s_waitcnt lgkmcnt(0)
	v_add_f32_e32 v138, v138, v139
	v_lshl_add_u32 v0, v0, 4, s55
	ds_write_b32 v0, v138

.LBB0_387:
	v_mul_f32_e32 v146, v131, v131
	v_mul_f32_e32 v147, v133, v133
	v_fmac_f32_e32 v146, v130, v130
	v_fmac_f32_e32 v147, v132, v132
	v_add_f32_e32 v146, v146, v147
	v_mul_f32_e32 v147, v135, v135
	v_mul_f32_e32 v148, v137, v137
	v_fmac_f32_e32 v147, v134, v134
	v_fmac_f32_e32 v148, v136, v136
	v_add_f32_e32 v147, v147, v148
	v_add_f32_e32 v146, v147, v146
	v_add_f32_e32 v148, v146, v158
	v_pk_mul_f32 v[146:147], v[202:203], v[132:133]
	v_mov_b32_e32 v133, v148
	s_nop 1
	v_permlane16_swap_b32_e32 v133, v148
	v_pk_mul_f32 v[130:131], v[200:201], v[130:131]
	v_pk_mul_f32 v[136:137], v[206:207], v[136:137]
	v_cvt_pk_bf16_f32 v132, v130, v131
	v_pk_mul_f32 v[134:135], v[204:205], v[134:135]
	s_waitcnt lgkmcnt(0)
	v_add_f32_e32 v130, v148, v133
	v_mov_b32_e32 v131, v130
	s_nop 1
	v_permlane32_swap_b32_e32 v131, v130
	v_cvt_pk_bf16_f32 v133, v146, v147
	v_cvt_pk_bf16_f32 v134, v134, v135
	v_cvt_pk_bf16_f32 v135, v136, v137
	global_store_dwordx4 v[154:155], v[132:135], off offset:256
	s_and_saveexec_b64 s[52:53], s[88:89]
	s_cbranch_execz .LBB0_389
	v_readlane_b32 s55, v254, 44
	s_waitcnt lgkmcnt(0)
	v_add_f32_e32 v130, v130, v131
	v_lshl_add_u32 v0, v0, 4, s55
	ds_write_b32 v0, v130

.LBB0_406:
	v_mul_f32_e32 v142, v139, v139
	v_mul_f32_e32 v143, v141, v141
	v_fmac_f32_e32 v142, v138, v138
	v_fmac_f32_e32 v143, v140, v140
	v_add_f32_e32 v142, v142, v143
	v_mul_f32_e32 v143, v135, v135
	v_mul_f32_e32 v144, v137, v137
	v_fmac_f32_e32 v143, v134, v134
	v_fmac_f32_e32 v144, v136, v136
	v_add_f32_e32 v143, v143, v144
	v_add_f32_e32 v142, v143, v142
	v_add_f32_e32 v150, v142, v158
	v_mov_b32_e32 v151, v150
	s_nop 1
	v_permlane16_swap_b32_e32 v151, v150
	v_pk_mul_f32 v[144:145], v[204:205], v[134:135]
	v_pk_mul_f32 v[140:141], v[202:203], v[140:141]
	v_pk_mul_f32 v[138:139], v[200:201], v[138:139]
	v_pk_mul_f32 v[142:143], v[206:207], v[136:137]
	s_waitcnt lgkmcnt(0)
	v_add_f32_e32 v134, v150, v151
	v_mov_b32_e32 v135, v134
	s_nop 1
	v_permlane32_swap_b32_e32 v135, v134
	v_cvt_pk_bf16_f32 v136, v138, v139
	v_cvt_pk_bf16_f32 v137, v140, v141
	v_cvt_pk_bf16_f32 v138, v144, v145
	v_cvt_pk_bf16_f32 v139, v142, v143
	global_store_dwordx4 v[154:155], v[136:139], off offset:256
	s_and_saveexec_b64 s[52:53], s[88:89]
	s_cbranch_execz .LBB0_408
	v_readlane_b32 s55, v254, 44
	s_waitcnt lgkmcnt(0)
	v_add_f32_e32 v134, v134, v135
	v_lshl_add_u32 v0, v0, 4, s55
	ds_write_b32 v0, v134

.LBB0_425:
	v_mul_f32_e32 v146, v131, v131
	v_mul_f32_e32 v147, v133, v133
	v_fmac_f32_e32 v146, v130, v130
	v_fmac_f32_e32 v147, v132, v132
	v_add_f32_e32 v146, v146, v147
	v_mul_f32_e32 v147, v143, v143
	v_mul_f32_e32 v148, v145, v145
	v_fmac_f32_e32 v147, v142, v142
	v_fmac_f32_e32 v148, v144, v144
	v_add_f32_e32 v147, v147, v148
	v_add_f32_e32 v146, v147, v146
	v_add_f32_e32 v148, v146, v158
	v_mov_b32_e32 v149, v148
	s_nop 1
	v_permlane16_swap_b32_e32 v149, v148
	v_pk_mul_f32 v[130:131], v[200:201], v[130:131]
	v_pk_mul_f32 v[146:147], v[206:207], v[144:145]
	v_pk_mul_f32 v[144:145], v[204:205], v[142:143]
	v_cvt_pk_bf16_f32 v142, v130, v131
	s_waitcnt lgkmcnt(0)
	v_add_f32_e32 v130, v148, v149
	v_mov_b32_e32 v131, v130
	s_nop 1
	v_permlane32_swap_b32_e32 v131, v130
	v_pk_mul_f32 v[132:133], v[202:203], v[132:133]
	v_cvt_pk_bf16_f32 v144, v144, v145
	v_cvt_pk_bf16_f32 v143, v132, v133
	v_cvt_pk_bf16_f32 v145, v146, v147
	global_store_dwordx4 v[154:155], v[142:145], off offset:256
	s_and_saveexec_b64 s[52:53], s[88:89]
	s_cbranch_execz .LBB0_427
	v_readlane_b32 s55, v254, 44
	s_waitcnt lgkmcnt(0)
	v_add_f32_e32 v130, v130, v131
	v_lshl_add_u32 v0, v0, 4, s55
	ds_write_b32 v0, v130

.LBB0_444:
	v_mul_f32_e32 v146, v135, v135
	v_mul_f32_e32 v147, v137, v137
	v_fmac_f32_e32 v146, v134, v134
	v_fmac_f32_e32 v147, v136, v136
	v_add_f32_e32 v146, v146, v147
	v_mul_f32_e32 v147, v139, v139
	v_mul_f32_e32 v148, v141, v141
	v_fmac_f32_e32 v147, v138, v138
	v_fmac_f32_e32 v148, v140, v140
	v_add_f32_e32 v147, v147, v148
	v_add_f32_e32 v146, v147, v146
	v_add_f32_e32 v148, v146, v158
	v_pk_mul_f32 v[146:147], v[202:203], v[136:137]
	v_mov_b32_e32 v137, v148
	s_nop 1
	v_permlane16_swap_b32_e32 v137, v148
	v_pk_mul_f32 v[134:135], v[200:201], v[134:135]
	v_pk_mul_f32 v[140:141], v[206:207], v[140:141]
	v_cvt_pk_bf16_f32 v136, v134, v135
	v_pk_mul_f32 v[138:139], v[204:205], v[138:139]
	s_waitcnt lgkmcnt(0)
	v_add_f32_e32 v134, v148, v137
	v_mov_b32_e32 v135, v134
	s_nop 1
	v_permlane32_swap_b32_e32 v135, v134
	v_cvt_pk_bf16_f32 v137, v146, v147
	v_cvt_pk_bf16_f32 v138, v138, v139
	v_cvt_pk_bf16_f32 v139, v140, v141
	global_store_dwordx4 v[154:155], v[136:139], off offset:256
	s_and_saveexec_b64 s[52:53], s[88:89]
	s_cbranch_execz .LBB0_446
	v_readlane_b32 s55, v254, 44
	s_waitcnt lgkmcnt(0)
	v_add_f32_e32 v134, v134, v135
	v_lshl_add_u32 v0, v0, 4, s55
	ds_write_b32 v0, v134

.LBB0_501:
	v_mul_f32_e32 v138, v131, v131
	v_mul_f32_e32 v139, v133, v133
	v_fmac_f32_e32 v138, v130, v130
	v_fmac_f32_e32 v139, v132, v132
	v_add_f32_e32 v138, v138, v139
	v_mul_f32_e32 v139, v135, v135
	v_mul_f32_e32 v140, v137, v137
	v_fmac_f32_e32 v139, v134, v134
	v_fmac_f32_e32 v140, v136, v136
	v_add_f32_e32 v139, v139, v140
	v_add_f32_e32 v138, v139, v138
	v_add_f32_e32 v140, v138, v150
	v_pk_mul_f32 v[138:139], v[202:203], v[132:133]
	v_mov_b32_e32 v133, v140
	s_nop 1
	v_permlane16_swap_b32_e32 v133, v140
	v_pk_mul_f32 v[130:131], v[200:201], v[130:131]
	v_pk_mul_f32 v[136:137], v[206:207], v[136:137]
	v_cvt_pk_bf16_f32 v132, v130, v131
	v_pk_mul_f32 v[134:135], v[204:205], v[134:135]
	s_waitcnt lgkmcnt(0)
	v_add_f32_e32 v130, v140, v133
	v_mov_b32_e32 v131, v130
	s_nop 1
	v_permlane32_swap_b32_e32 v131, v130
	v_cvt_pk_bf16_f32 v133, v138, v139
	v_cvt_pk_bf16_f32 v134, v134, v135
	v_cvt_pk_bf16_f32 v135, v136, v137
	global_store_dwordx4 v[146:147], v[132:135], off offset:256
	s_and_saveexec_b64 s[10:11], s[88:89]
	s_cbranch_execz .LBB0_503
	v_readlane_b32 s12, v254, 44
	s_waitcnt lgkmcnt(0)
	v_add_f32_e32 v130, v130, v131
	v_lshl_add_u32 v0, v0, 4, s12
	ds_write_b32 v0, v130
